# GEMM super-phases: MFMAs reordered k-inner so the two updates of each accumulator issue back-to-back (SrcC forwarding), on top of v004
# speedup vs baseline: 1.0079x; 1.0079x over previous
; #define PG8_STAGE(bufoff, gbase, voff) do { _Pragma("unroll") for (int _i = 0; _i < 2; ++_i) \
;         __builtin_amdgcn_global_load_lds((const unsigned*)((const char*)(gbase) + (voff)[_i]), (PG8_LAS unsigned*)(lds + (bufoff) + ldsw + _i * 8192), 16, 0, 0); } while (0)
; #define PG8_LDA(dst, b, h) do { _Pragma("unroll") for (int m = 0; m < 4; ++m) _Pragma("unroll") for (int k = 0; k < 2; ++k) dst[m][k] = *(const PG8_LAS bf16x8*)(lds + PG8_SA(b, h) + aoff + m * 2048 + k * 1024); } while (0)
; #define PG8_LDB(dst, b, h) do { _Pragma("unroll") for (int n = 0; n < 2; ++n) _Pragma("unroll") for (int k = 0; k < 2; ++k) dst[n][k] = *(const PG8_LAS bf16x8*)(lds + PG8_SB(b, h) + boff + n * 2048 + k * 1024); } while (0)
; #define PG8_MMA(ai, bj, At, Bt) do { __builtin_amdgcn_s_setprio(1); _Pragma("unroll") for (int m = 0; m < 4; ++m) _Pragma("unroll") for (int n = 0; n < 2; ++n) _Pragma("unroll") for (int k = 0; k < 2; ++k) \
;         acc[ai][bj][m][n] = __builtin_amdgcn_mfma_f32_16x16x32_bf16(Bt[n][k], At[m][k], acc[ai][bj][m][n], 0, 0, 0); __builtin_amdgcn_s_setprio(0); } while (0)
; #define PG8_WAIT_V(n) asm volatile("s_waitcnt vmcnt(" #n ")" ::: "memory")
; #define PG8_WAIT_L(n) asm volatile("s_waitcnt lgkmcnt(" #n ")" ::: "memory")
; template <class Epi, class Sched, bool ALIGN_EPI = false, bool SP2 = false>
; __device__ __forceinline__ void gemm_phase(PG8_LAS unsigned char* lds, const Gemm g, const Sched& S, const Epi& E, const int tid) {
;     ...
;             const bool last = (t == nt - 2);
;             const char* a1 = cA + (size_t)(t + 1) * kstep;
;             const char* a2 = last ? nA : cA + (size_t)(t + 2) * kstep; const char* b2 = last ? nB : cB + (size_t)(t + 2) * kstep;
;             const char* a3 = a2 + kstep; const char* b3 = b2 + kstep;
;             if (last && has_next) S.a_ready(nxt);
;             if constexpr (SP2) {
;             PG8_LDB(B0, 0, 0); PG8_LDB(B1, 0, 1); PG8_SCHED; PG8_LDA(At, 0, 0); PG8_STAGE(PG8_SA(1, 1), a1 + hstep, voffA);
;             PG8_WAIT_V(8); PG8_WAIT_L(0); PG8_BAR; PG8_MMA(0, 0, At, B0); PG8_MMA(0, 1, At, B1); PG8_BAR; PG8_SCHED;
;             PG8_LDA(At, 0, 1); PG8_STAGE(PG8_SB(0, 0), b2, voffB); PG8_STAGE(PG8_SB(0, 1), b2 + hstep, voffB); PG8_STAGE(PG8_SA(0, 0), a2, voffA);
;             PG8_WAIT_V(8); PG8_WAIT_L(0); PG8_BAR; PG8_MMA(1, 0, At, B0); PG8_MMA(1, 1, At, B1); PG8_BAR; PG8_SCHED;
.LBB0_120:
	ds_read_b128 v[122:125], v191
	ds_read_b128 v[126:129], v192
	ds_read_b128 v[138:141], v193
	ds_read_b128 v[142:145], v194
	ds_read_b128 v[146:149], v195
	ds_read_b128 v[150:153], v196
	ds_read_b128 v[164:167], v197
	ds_read_b128 v[168:171], v198
	s_add_u32 s43, s30, 0xfffc0080
	s_addc_u32 s45, s31, -1
	s_cmp_eq_u32 s27, 12
	s_cselect_b32 s87, s5, s45
	s_cselect_b32 s86, s15, s43
	s_cselect_b32 s85, s20, s26
	s_cselect_b32 s84, s21, s24
	s_mov_b32 m0, s38
	v_lshl_add_u64 v[188:189], s[30:31], 0, v[160:161]
	ds_read_b128 v[172:175], v190
	ds_read_b128 v[176:179], v190 offset:1024
	ds_read_b128 v[180:183], v190 offset:2048
	ds_read_b128 v[184:187], v190 offset:3072
	ds_read_b128 v[214:217], v190 offset:4096
	ds_read_b128 v[218:221], v190 offset:5120
	ds_read_b128 v[222:225], v190 offset:6144
	ds_read_b128 v[226:229], v190 offset:7168
	global_load_lds_dwordx4 v[188:189], off
	v_lshl_add_u64 v[188:189], s[30:31], 0, v[162:163]
	s_mov_b32 m0, s0
	s_nop 0
	global_load_lds_dwordx4 v[188:189], off
	s_waitcnt vmcnt(8)
	s_waitcnt lgkmcnt(0)
	s_barrier
	s_setprio 1
	s_waitcnt lgkmcnt(0)
	v_mfma_f32_16x16x32_bf16 v[134:137], v[122:125], v[172:175], v[134:137]
	v_mfma_f32_16x16x32_bf16 v[134:137], v[126:129], v[176:179], v[134:137]
	v_mfma_f32_16x16x32_bf16 v[130:133], v[138:141], v[172:175], v[130:133]
	v_mfma_f32_16x16x32_bf16 v[130:133], v[142:145], v[176:179], v[130:133]
	v_mfma_f32_16x16x32_bf16 v[118:121], v[122:125], v[180:183], v[118:121]
	v_mfma_f32_16x16x32_bf16 v[118:121], v[126:129], v[184:187], v[118:121]
	v_mfma_f32_16x16x32_bf16 v[114:117], v[138:141], v[180:183], v[114:117]
	v_mfma_f32_16x16x32_bf16 v[114:117], v[142:145], v[184:187], v[114:117]
	v_mfma_f32_16x16x32_bf16 v[110:113], v[122:125], v[214:217], v[110:113]
	v_mfma_f32_16x16x32_bf16 v[110:113], v[126:129], v[218:221], v[110:113]
	v_mfma_f32_16x16x32_bf16 v[106:109], v[138:141], v[214:217], v[106:109]
	v_mfma_f32_16x16x32_bf16 v[106:109], v[142:145], v[218:221], v[106:109]
	v_mfma_f32_16x16x32_bf16 v[102:105], v[122:125], v[222:225], v[102:105]
	v_mfma_f32_16x16x32_bf16 v[102:105], v[126:129], v[226:229], v[102:105]
	v_mfma_f32_16x16x32_bf16 v[98:101], v[138:141], v[222:225], v[98:101]
	v_mfma_f32_16x16x32_bf16 v[98:101], v[142:145], v[226:229], v[98:101]
	s_setprio 0
	s_setprio 1
	v_mfma_f32_16x16x32_bf16 v[62:65], v[146:149], v[172:175], v[62:65]
	v_mfma_f32_16x16x32_bf16 v[62:65], v[150:153], v[176:179], v[62:65]
	v_mfma_f32_16x16x32_bf16 v[58:61], v[164:167], v[172:175], v[58:61]
	v_mfma_f32_16x16x32_bf16 v[58:61], v[168:171], v[176:179], v[58:61]
	v_mfma_f32_16x16x32_bf16 v[54:57], v[146:149], v[180:183], v[54:57]
	v_mfma_f32_16x16x32_bf16 v[54:57], v[150:153], v[184:187], v[54:57]
	v_mfma_f32_16x16x32_bf16 v[50:53], v[164:167], v[180:183], v[50:53]
	v_mfma_f32_16x16x32_bf16 v[50:53], v[168:171], v[184:187], v[50:53]
	v_mfma_f32_16x16x32_bf16 v[46:49], v[146:149], v[214:217], v[46:49]
	v_mfma_f32_16x16x32_bf16 v[46:49], v[150:153], v[218:221], v[46:49]
	v_mfma_f32_16x16x32_bf16 v[42:45], v[164:167], v[214:217], v[42:45]
	v_mfma_f32_16x16x32_bf16 v[42:45], v[168:171], v[218:221], v[42:45]
	v_mfma_f32_16x16x32_bf16 v[38:41], v[146:149], v[222:225], v[38:41]
	v_mfma_f32_16x16x32_bf16 v[38:41], v[150:153], v[226:229], v[38:41]
	v_mfma_f32_16x16x32_bf16 v[34:37], v[164:167], v[222:225], v[34:37]
	v_mfma_f32_16x16x32_bf16 v[34:37], v[168:171], v[226:229], v[34:37]
	s_setprio 0
	s_barrier
	s_mov_b32 m0, s6
	v_lshl_add_u64 v[188:189], s[84:85], 0, v[0:1]
	s_add_u32 s50, s84, 0x40000
	ds_read_b128 v[172:175], v190 offset:16384
	ds_read_b128 v[176:179], v190 offset:17408
	ds_read_b128 v[180:183], v190 offset:18432
	ds_read_b128 v[184:187], v190 offset:19456
	ds_read_b128 v[214:217], v190 offset:20480
	ds_read_b128 v[218:221], v190 offset:21504
	ds_read_b128 v[222:225], v190 offset:22528
	ds_read_b128 v[226:229], v190 offset:23552
	global_load_lds_dwordx4 v[188:189], off
	v_lshl_add_u64 v[208:209], s[84:85], 0, v[154:155]
	s_mov_b32 m0, s8
	s_addc_u32 s51, s85, 0
	global_load_lds_dwordx4 v[208:209], off
	v_lshl_add_u64 v[210:211], s[50:51], 0, v[0:1]
	s_mov_b32 m0, s9
	v_lshl_add_u64 v[212:213], s[86:87], 0, v[156:157]
	global_load_lds_dwordx4 v[210:211], off
	v_lshl_add_u64 v[210:211], s[50:51], 0, v[154:155]
	s_mov_b32 m0, s14
	s_nop 0
	global_load_lds_dwordx4 v[210:211], off
	v_lshl_add_u64 v[210:211], s[86:87], 0, v[158:159]
	s_mov_b32 m0, s17
	s_nop 0
	global_load_lds_dwordx4 v[210:211], off
	s_mov_b32 m0, s34
	s_nop 0
	global_load_lds_dwordx4 v[212:213], off
	s_waitcnt vmcnt(8)
	s_waitcnt lgkmcnt(0)
	s_barrier
; #define PG8_STAGE(bufoff, gbase, voff) do { _Pragma("unroll") for (int _i = 0; _i < 2; ++_i) \
;         __builtin_amdgcn_global_load_lds((const unsigned*)((const char*)(gbase) + (voff)[_i]), (PG8_LAS unsigned*)(lds + (bufoff) + ldsw + _i * 8192), 16, 0, 0); } while (0)
; #define PG8_LDA(dst, b, h) do { _Pragma("unroll") for (int m = 0; m < 4; ++m) _Pragma("unroll") for (int k = 0; k < 2; ++k) dst[m][k] = *(const PG8_LAS bf16x8*)(lds + PG8_SA(b, h) + aoff + m * 2048 + k * 1024); } while (0)
; #define PG8_LDB(dst, b, h) do { _Pragma("unroll") for (int n = 0; n < 2; ++n) _Pragma("unroll") for (int k = 0; k < 2; ++k) dst[n][k] = *(const PG8_LAS bf16x8*)(lds + PG8_SB(b, h) + boff + n * 2048 + k * 1024); } while (0)
; #define PG8_MMA(ai, bj, At, Bt) do { __builtin_amdgcn_s_setprio(1); _Pragma("unroll") for (int m = 0; m < 4; ++m) _Pragma("unroll") for (int n = 0; n < 2; ++n) _Pragma("unroll") for (int k = 0; k < 2; ++k) \
;         acc[ai][bj][m][n] = __builtin_amdgcn_mfma_f32_16x16x32_bf16(Bt[n][k], At[m][k], acc[ai][bj][m][n], 0, 0, 0); __builtin_amdgcn_s_setprio(0); } while (0)
; #define PG8_WAIT_V(n) asm volatile("s_waitcnt vmcnt(" #n ")" ::: "memory")
; #define PG8_WAIT_L(n) asm volatile("s_waitcnt lgkmcnt(" #n ")" ::: "memory")
; #define PG8_BAR __builtin_amdgcn_s_barrier()
; #define PG8_SCHED __builtin_amdgcn_sched_barrier(0)
; template <class Epi, class Sched, bool ALIGN_EPI = false, bool SP2 = false>
; __device__ __forceinline__ void gemm_phase(PG8_LAS unsigned char* lds, const Gemm g, const Sched& S, const Epi& E, const int tid) {
;     ...
;             PG8_WAIT_V(8); PG8_WAIT_L(0); PG8_BAR; PG8_MMA(1, 0, At, B0); PG8_MMA(1, 1, At, B1); PG8_BAR; PG8_SCHED;
;             PG8_LDB(B0, 1, 0); PG8_LDB(B1, 1, 1); PG8_SCHED; PG8_LDA(At, 1, 0); PG8_STAGE(PG8_SA(0, 1), a2 + hstep, voffA);
;             PG8_WAIT_V(8); PG8_WAIT_L(0); PG8_BAR; PG8_MMA(0, 0, At, B0); PG8_MMA(0, 1, At, B1); PG8_BAR; PG8_SCHED;
	s_setprio 1
	s_waitcnt lgkmcnt(0)
	v_mfma_f32_16x16x32_bf16 v[94:97], v[122:125], v[172:175], v[94:97]
	v_mfma_f32_16x16x32_bf16 v[94:97], v[126:129], v[176:179], v[94:97]
	v_mfma_f32_16x16x32_bf16 v[90:93], v[138:141], v[172:175], v[90:93]
	v_mfma_f32_16x16x32_bf16 v[90:93], v[142:145], v[176:179], v[90:93]
	v_mfma_f32_16x16x32_bf16 v[86:89], v[122:125], v[180:183], v[86:89]
	v_mfma_f32_16x16x32_bf16 v[86:89], v[126:129], v[184:187], v[86:89]
	v_mfma_f32_16x16x32_bf16 v[82:85], v[138:141], v[180:183], v[82:85]
	v_mfma_f32_16x16x32_bf16 v[82:85], v[142:145], v[184:187], v[82:85]
	v_mfma_f32_16x16x32_bf16 v[78:81], v[122:125], v[214:217], v[78:81]
	v_mfma_f32_16x16x32_bf16 v[78:81], v[126:129], v[218:221], v[78:81]
	v_mfma_f32_16x16x32_bf16 v[74:77], v[138:141], v[214:217], v[74:77]
	v_mfma_f32_16x16x32_bf16 v[74:77], v[142:145], v[218:221], v[74:77]
	v_mfma_f32_16x16x32_bf16 v[70:73], v[122:125], v[222:225], v[70:73]
	v_mfma_f32_16x16x32_bf16 v[70:73], v[126:129], v[226:229], v[70:73]
	v_mfma_f32_16x16x32_bf16 v[66:69], v[138:141], v[222:225], v[66:69]
	v_mfma_f32_16x16x32_bf16 v[66:69], v[142:145], v[226:229], v[66:69]
	s_setprio 0
	s_setprio 1
	v_mfma_f32_16x16x32_bf16 v[30:33], v[146:149], v[172:175], v[30:33]
	v_mfma_f32_16x16x32_bf16 v[30:33], v[150:153], v[176:179], v[30:33]
	v_mfma_f32_16x16x32_bf16 v[26:29], v[164:167], v[172:175], v[26:29]
	v_mfma_f32_16x16x32_bf16 v[26:29], v[168:171], v[176:179], v[26:29]
	v_mfma_f32_16x16x32_bf16 v[22:25], v[146:149], v[180:183], v[22:25]
	v_mfma_f32_16x16x32_bf16 v[22:25], v[150:153], v[184:187], v[22:25]
	v_mfma_f32_16x16x32_bf16 v[18:21], v[164:167], v[180:183], v[18:21]
	v_mfma_f32_16x16x32_bf16 v[18:21], v[168:171], v[184:187], v[18:21]
	v_mfma_f32_16x16x32_bf16 v[14:17], v[146:149], v[214:217], v[14:17]
	v_mfma_f32_16x16x32_bf16 v[14:17], v[150:153], v[218:221], v[14:17]
	v_mfma_f32_16x16x32_bf16 v[10:13], v[164:167], v[214:217], v[10:13]
	v_mfma_f32_16x16x32_bf16 v[10:13], v[168:171], v[218:221], v[10:13]
	v_mfma_f32_16x16x32_bf16 v[6:9], v[146:149], v[222:225], v[6:9]
	v_mfma_f32_16x16x32_bf16 v[6:9], v[150:153], v[226:229], v[6:9]
	v_mfma_f32_16x16x32_bf16 v[2:5], v[164:167], v[222:225], v[2:5]
	v_mfma_f32_16x16x32_bf16 v[2:5], v[168:171], v[226:229], v[2:5]
	s_setprio 0
	s_barrier
	ds_read_b128 v[122:125], v199
	ds_read_b128 v[126:129], v200
	ds_read_b128 v[138:141], v201
	ds_read_b128 v[142:145], v202
	ds_read_b128 v[146:149], v203
	ds_read_b128 v[150:153], v204
	ds_read_b128 v[164:167], v205
	ds_read_b128 v[168:171], v206
	s_add_u32 s50, s86, 0x40000
	s_addc_u32 s51, s87, 0
	s_mov_b32 m0, s35
	v_lshl_add_u64 v[230:231], s[50:51], 0, v[158:159]
	ds_read_b128 v[172:175], v190 offset:32768
	ds_read_b128 v[176:179], v190 offset:33792
	ds_read_b128 v[180:183], v190 offset:34816
	ds_read_b128 v[184:187], v190 offset:35840
	ds_read_b128 v[214:217], v190 offset:36864
	ds_read_b128 v[218:221], v190 offset:37888
	ds_read_b128 v[222:225], v190 offset:38912
	ds_read_b128 v[226:229], v190 offset:39936
	global_load_lds_dwordx4 v[230:231], off
	v_lshl_add_u64 v[230:231], s[50:51], 0, v[156:157]
	s_mov_b32 m0, s88
	s_nop 0
	global_load_lds_dwordx4 v[230:231], off
	s_waitcnt vmcnt(8)
	s_waitcnt lgkmcnt(0)
	s_barrier
	s_setprio 1
	s_waitcnt lgkmcnt(0)
	v_mfma_f32_16x16x32_bf16 v[134:137], v[122:125], v[172:175], v[134:137]
	v_mfma_f32_16x16x32_bf16 v[134:137], v[126:129], v[176:179], v[134:137]
	v_mfma_f32_16x16x32_bf16 v[130:133], v[138:141], v[172:175], v[130:133]
	v_mfma_f32_16x16x32_bf16 v[130:133], v[142:145], v[176:179], v[130:133]
	v_mfma_f32_16x16x32_bf16 v[118:121], v[122:125], v[180:183], v[118:121]
	v_mfma_f32_16x16x32_bf16 v[118:121], v[126:129], v[184:187], v[118:121]
	v_mfma_f32_16x16x32_bf16 v[114:117], v[138:141], v[180:183], v[114:117]
	v_mfma_f32_16x16x32_bf16 v[114:117], v[142:145], v[184:187], v[114:117]
	v_mfma_f32_16x16x32_bf16 v[110:113], v[122:125], v[214:217], v[110:113]
	v_mfma_f32_16x16x32_bf16 v[110:113], v[126:129], v[218:221], v[110:113]
	v_mfma_f32_16x16x32_bf16 v[106:109], v[138:141], v[214:217], v[106:109]
	v_mfma_f32_16x16x32_bf16 v[106:109], v[142:145], v[218:221], v[106:109]
	v_mfma_f32_16x16x32_bf16 v[102:105], v[122:125], v[222:225], v[102:105]
	v_mfma_f32_16x16x32_bf16 v[102:105], v[126:129], v[226:229], v[102:105]
	v_mfma_f32_16x16x32_bf16 v[98:101], v[138:141], v[222:225], v[98:101]
	v_mfma_f32_16x16x32_bf16 v[98:101], v[142:145], v[226:229], v[98:101]
	s_setprio 0
	s_setprio 1
	v_mfma_f32_16x16x32_bf16 v[62:65], v[146:149], v[172:175], v[62:65]
	v_mfma_f32_16x16x32_bf16 v[62:65], v[150:153], v[176:179], v[62:65]
	v_mfma_f32_16x16x32_bf16 v[58:61], v[164:167], v[172:175], v[58:61]
	v_mfma_f32_16x16x32_bf16 v[58:61], v[168:171], v[176:179], v[58:61]
	v_mfma_f32_16x16x32_bf16 v[54:57], v[146:149], v[180:183], v[54:57]
	v_mfma_f32_16x16x32_bf16 v[54:57], v[150:153], v[184:187], v[54:57]
	v_mfma_f32_16x16x32_bf16 v[50:53], v[164:167], v[180:183], v[50:53]
	v_mfma_f32_16x16x32_bf16 v[50:53], v[168:171], v[184:187], v[50:53]
	v_mfma_f32_16x16x32_bf16 v[46:49], v[146:149], v[214:217], v[46:49]
	v_mfma_f32_16x16x32_bf16 v[46:49], v[150:153], v[218:221], v[46:49]
	v_mfma_f32_16x16x32_bf16 v[42:45], v[164:167], v[214:217], v[42:45]
	v_mfma_f32_16x16x32_bf16 v[42:45], v[168:171], v[218:221], v[42:45]
	v_mfma_f32_16x16x32_bf16 v[38:41], v[146:149], v[222:225], v[38:41]
	v_mfma_f32_16x16x32_bf16 v[38:41], v[150:153], v[226:229], v[38:41]
	v_mfma_f32_16x16x32_bf16 v[34:37], v[164:167], v[222:225], v[34:37]
	v_mfma_f32_16x16x32_bf16 v[34:37], v[168:171], v[226:229], v[34:37]
	s_setprio 0
	s_barrier
; #define PG8_STAGE(bufoff, gbase, voff) do { _Pragma("unroll") for (int _i = 0; _i < 2; ++_i) \
;         __builtin_amdgcn_global_load_lds((const unsigned*)((const char*)(gbase) + (voff)[_i]), (PG8_LAS unsigned*)(lds + (bufoff) + ldsw + _i * 8192), 16, 0, 0); } while (0)
; #define PG8_LDA(dst, b, h) do { _Pragma("unroll") for (int m = 0; m < 4; ++m) _Pragma("unroll") for (int k = 0; k < 2; ++k) dst[m][k] = *(const PG8_LAS bf16x8*)(lds + PG8_SA(b, h) + aoff + m * 2048 + k * 1024); } while (0)
; #define PG8_MMA(ai, bj, At, Bt) do { __builtin_amdgcn_s_setprio(1); _Pragma("unroll") for (int m = 0; m < 4; ++m) _Pragma("unroll") for (int n = 0; n < 2; ++n) _Pragma("unroll") for (int k = 0; k < 2; ++k) \
;         acc[ai][bj][m][n] = __builtin_amdgcn_mfma_f32_16x16x32_bf16(Bt[n][k], At[m][k], acc[ai][bj][m][n], 0, 0, 0); __builtin_amdgcn_s_setprio(0); } while (0)
; #define PG8_WAIT_V(n) asm volatile("s_waitcnt vmcnt(" #n ")" ::: "memory")
; #define PG8_WAIT_L(n) asm volatile("s_waitcnt lgkmcnt(" #n ")" ::: "memory")
; #define PG8_BAR __builtin_amdgcn_s_barrier()
; #define PG8_SCHED __builtin_amdgcn_sched_barrier(0)
; template <class Epi, class Sched, bool ALIGN_EPI = false, bool SP2 = false>
; __device__ __forceinline__ void gemm_phase(PG8_LAS unsigned char* lds, const Gemm g, const Sched& S, const Epi& E, const int tid) {
;     ...
;             PG8_WAIT_V(8); PG8_WAIT_L(0); PG8_BAR; PG8_MMA(0, 0, At, B0); PG8_MMA(0, 1, At, B1); PG8_BAR; PG8_SCHED;
;             PG8_LDA(At, 1, 1); PG8_STAGE(PG8_SB(1, 0), b3, voffB); PG8_STAGE(PG8_SB(1, 1), b3 + hstep, voffB); PG8_STAGE(PG8_SA(1, 0), a3, voffA);
;             PG8_WAIT_V(8); PG8_WAIT_L(0); PG8_BAR; PG8_MMA(1, 0, At, B0); PG8_MMA(1, 1, At, B1); PG8_BAR; PG8_SCHED;
;     ...
;         if constexpr (ALIGN_EPI) { if (wr == 0) PG8_BAR; }
	s_mov_b32 m0, s89
	v_lshl_add_u64 v[188:189], v[188:189], 0, s[12:13]
	s_add_u32 s50, s84, 0x40080
	ds_read_b128 v[172:175], v190 offset:49152
	ds_read_b128 v[176:179], v190 offset:50176
	ds_read_b128 v[180:183], v190 offset:51200
	ds_read_b128 v[184:187], v190 offset:52224
	ds_read_b128 v[214:217], v190 offset:53248
	ds_read_b128 v[218:221], v190 offset:54272
	ds_read_b128 v[222:225], v190 offset:55296
	ds_read_b128 v[226:229], v190 offset:56320
	global_load_lds_dwordx4 v[188:189], off
	v_lshl_add_u64 v[188:189], v[208:209], 0, s[12:13]
	s_mov_b32 m0, s90
	s_addc_u32 s51, s85, 0
	global_load_lds_dwordx4 v[188:189], off
	v_lshl_add_u64 v[188:189], s[50:51], 0, v[0:1]
	s_mov_b32 m0, s41
	s_nop 0
	global_load_lds_dwordx4 v[188:189], off
	v_lshl_add_u64 v[188:189], s[50:51], 0, v[154:155]
	s_mov_b32 m0, s40
	s_nop 0
	global_load_lds_dwordx4 v[188:189], off
	v_lshl_add_u64 v[188:189], v[210:211], 0, s[12:13]
	s_mov_b32 m0, s91
	s_nop 0
	global_load_lds_dwordx4 v[188:189], off
	v_lshl_add_u64 v[188:189], v[212:213], 0, s[12:13]
	s_mov_b32 m0, s1
	s_nop 0
	global_load_lds_dwordx4 v[188:189], off
	s_waitcnt vmcnt(8)
	s_waitcnt lgkmcnt(0)
	s_barrier
	s_setprio 1
	s_waitcnt lgkmcnt(0)
	v_mfma_f32_16x16x32_bf16 v[94:97], v[122:125], v[172:175], v[94:97]
	v_mfma_f32_16x16x32_bf16 v[94:97], v[126:129], v[176:179], v[94:97]
	v_mfma_f32_16x16x32_bf16 v[90:93], v[138:141], v[172:175], v[90:93]
	v_mfma_f32_16x16x32_bf16 v[90:93], v[142:145], v[176:179], v[90:93]
	v_mfma_f32_16x16x32_bf16 v[86:89], v[122:125], v[180:183], v[86:89]
	v_mfma_f32_16x16x32_bf16 v[86:89], v[126:129], v[184:187], v[86:89]
	v_mfma_f32_16x16x32_bf16 v[82:85], v[138:141], v[180:183], v[82:85]
	v_mfma_f32_16x16x32_bf16 v[82:85], v[142:145], v[184:187], v[82:85]
	v_mfma_f32_16x16x32_bf16 v[78:81], v[122:125], v[214:217], v[78:81]
	v_mfma_f32_16x16x32_bf16 v[78:81], v[126:129], v[218:221], v[78:81]
	v_mfma_f32_16x16x32_bf16 v[74:77], v[138:141], v[214:217], v[74:77]
	v_mfma_f32_16x16x32_bf16 v[74:77], v[142:145], v[218:221], v[74:77]
	v_mfma_f32_16x16x32_bf16 v[70:73], v[122:125], v[222:225], v[70:73]
	v_mfma_f32_16x16x32_bf16 v[70:73], v[126:129], v[226:229], v[70:73]
	v_mfma_f32_16x16x32_bf16 v[66:69], v[138:141], v[222:225], v[66:69]
	v_mfma_f32_16x16x32_bf16 v[66:69], v[142:145], v[226:229], v[66:69]
	s_setprio 0
	s_setprio 1
	v_mfma_f32_16x16x32_bf16 v[30:33], v[146:149], v[172:175], v[30:33]
	v_mfma_f32_16x16x32_bf16 v[30:33], v[150:153], v[176:179], v[30:33]
	v_mfma_f32_16x16x32_bf16 v[26:29], v[164:167], v[172:175], v[26:29]
	v_mfma_f32_16x16x32_bf16 v[26:29], v[168:171], v[176:179], v[26:29]
	v_mfma_f32_16x16x32_bf16 v[22:25], v[146:149], v[180:183], v[22:25]
	v_mfma_f32_16x16x32_bf16 v[22:25], v[150:153], v[184:187], v[22:25]
	v_mfma_f32_16x16x32_bf16 v[18:21], v[164:167], v[180:183], v[18:21]
	v_mfma_f32_16x16x32_bf16 v[18:21], v[168:171], v[184:187], v[18:21]
	v_mfma_f32_16x16x32_bf16 v[14:17], v[146:149], v[214:217], v[14:17]
	v_mfma_f32_16x16x32_bf16 v[14:17], v[150:153], v[218:221], v[14:17]
	v_mfma_f32_16x16x32_bf16 v[10:13], v[164:167], v[214:217], v[10:13]
	v_mfma_f32_16x16x32_bf16 v[10:13], v[168:171], v[218:221], v[10:13]
	v_mfma_f32_16x16x32_bf16 v[6:9], v[146:149], v[222:225], v[6:9]
	v_mfma_f32_16x16x32_bf16 v[6:9], v[150:153], v[226:229], v[6:9]
	v_mfma_f32_16x16x32_bf16 v[2:5], v[164:167], v[222:225], v[2:5]
	v_mfma_f32_16x16x32_bf16 v[2:5], v[168:171], v[226:229], v[2:5]
	s_setprio 0
	s_barrier
	s_add_i32 s27, s27, 2
	s_add_u32 s30, s30, 0x100
	s_addc_u32 s31, s31, 0
	s_add_u32 s24, s24, 0x100
	s_addc_u32 s26, s26, 0
	s_cmp_gt_u32 s27, 13
	s_cbranch_scc0 .LBB0_120
	v_readlane_b32 s20, v255, 54
	v_readlane_b32 s21, v255, 55
	s_and_b64 vcc, exec, s[20:21]
	s_cbranch_vccz .LBB0_123
	s_barrier

; #define PG8_STAGE(bufoff, gbase, voff) do { _Pragma("unroll") for (int _i = 0; _i < 2; ++_i) \
;         __builtin_amdgcn_global_load_lds((const unsigned*)((const char*)(gbase) + (voff)[_i]), (PG8_LAS unsigned*)(lds + (bufoff) + ldsw + _i * 8192), 16, 0, 0); } while (0)
; #define PG8_LDA(dst, b, h) do { _Pragma("unroll") for (int m = 0; m < 4; ++m) _Pragma("unroll") for (int k = 0; k < 2; ++k) dst[m][k] = *(const PG8_LAS bf16x8*)(lds + PG8_SA(b, h) + aoff + m * 2048 + k * 1024); } while (0)
; #define PG8_LDB(dst, b, h) do { _Pragma("unroll") for (int n = 0; n < 2; ++n) _Pragma("unroll") for (int k = 0; k < 2; ++k) dst[n][k] = *(const PG8_LAS bf16x8*)(lds + PG8_SB(b, h) + boff + n * 2048 + k * 1024); } while (0)
; #define PG8_MMA(ai, bj, At, Bt) do { __builtin_amdgcn_s_setprio(1); _Pragma("unroll") for (int m = 0; m < 4; ++m) _Pragma("unroll") for (int n = 0; n < 2; ++n) _Pragma("unroll") for (int k = 0; k < 2; ++k) \
;         acc[ai][bj][m][n] = __builtin_amdgcn_mfma_f32_16x16x32_bf16(Bt[n][k], At[m][k], acc[ai][bj][m][n], 0, 0, 0); __builtin_amdgcn_s_setprio(0); } while (0)
; #define PG8_WAIT_V(n) asm volatile("s_waitcnt vmcnt(" #n ")" ::: "memory")
; #define PG8_WAIT_L(n) asm volatile("s_waitcnt lgkmcnt(" #n ")" ::: "memory")
; template <class Epi, class Sched, bool ALIGN_EPI = false, bool SP2 = false>
; __device__ __forceinline__ void gemm_phase(PG8_LAS unsigned char* lds, const Gemm g, const Sched& S, const Epi& E, const int tid) {
;     ...
;             const bool last = (t == nt - 2);
;             const char* a1 = cA + (size_t)(t + 1) * kstep;
;             const char* a2 = last ? nA : cA + (size_t)(t + 2) * kstep; const char* b2 = last ? nB : cB + (size_t)(t + 2) * kstep;
;             const char* a3 = a2 + kstep; const char* b3 = b2 + kstep;
;             if (last && has_next) S.a_ready(nxt);
;             if constexpr (SP2) {
;             PG8_LDB(B0, 0, 0); PG8_LDB(B1, 0, 1); PG8_SCHED; PG8_LDA(At, 0, 0); PG8_STAGE(PG8_SA(1, 1), a1 + hstep, voffA);
;             PG8_WAIT_V(8); PG8_WAIT_L(0); PG8_BAR; PG8_MMA(0, 0, At, B0); PG8_MMA(0, 1, At, B1); PG8_BAR; PG8_SCHED;
;             PG8_LDA(At, 0, 1); PG8_STAGE(PG8_SB(0, 0), b2, voffB); PG8_STAGE(PG8_SB(0, 1), b2 + hstep, voffB); PG8_STAGE(PG8_SA(0, 0), a2, voffA);
;             PG8_WAIT_V(8); PG8_WAIT_L(0); PG8_BAR; PG8_MMA(1, 0, At, B0); PG8_MMA(1, 1, At, B1); PG8_BAR; PG8_SCHED;
.LBB0_355:
	v_or_b32_e32 v98, 0x10000, v187
	v_add_u32_e32 v102, 0x10400, v187
	v_add_u32_e32 v130, 0x10800, v187
	v_add_u32_e32 v142, 0x10c00, v187
	v_or_b32_e32 v146, 0x14000, v187
	v_add_u32_e32 v160, 0x14400, v187
	v_add_u32_e32 v164, 0x14800, v187
	v_add_u32_e32 v168, 0x14c00, v187
	ds_read_b128 v[98:101], v98
	ds_read_b128 v[102:105], v102
	ds_read_b128 v[130:133], v130
	ds_read_b128 v[142:145], v142
	ds_read_b128 v[146:149], v146
	ds_read_b128 v[160:163], v160
	ds_read_b128 v[164:167], v164
	ds_read_b128 v[168:171], v168
	s_add_u32 s26, s30, 0xfffc0080
	s_addc_u32 s27, s31, -1
	s_cmp_eq_u32 s24, 12
	s_cselect_b32 s87, s4, s27
	s_cselect_b32 s86, s5, s26
	s_cselect_b32 s85, s15, s21
	s_cselect_b32 s84, s17, s20
	v_lshl_add_u64 v[180:181], s[30:31], 0, v[156:157]
	s_add_i32 m0, s6, 0xc000
	ds_read_b128 v[172:175], v186
	ds_read_b128 v[176:179], v186 offset:1024
	ds_read_b128 v[188:191], v186 offset:2048
	ds_read_b128 v[192:195], v186 offset:3072
	ds_read_b128 v[196:199], v186 offset:4096
	ds_read_b128 v[200:203], v186 offset:5120
	ds_read_b128 v[204:207], v186 offset:6144
	ds_read_b128 v[214:217], v186 offset:7168
	global_load_lds_dwordx4 v[180:181], off
	v_lshl_add_u64 v[180:181], s[30:31], 0, v[158:159]
	s_add_i32 m0, s6, 0xe000
	s_nop 0
	global_load_lds_dwordx4 v[180:181], off
	s_waitcnt vmcnt(8)
	s_waitcnt lgkmcnt(0)
	s_barrier
	s_setprio 1
	s_waitcnt lgkmcnt(0)
	v_mfma_f32_16x16x32_bf16 v[138:141], v[98:101], v[172:175], v[138:141]
	v_mfma_f32_16x16x32_bf16 v[138:141], v[102:105], v[176:179], v[138:141]
	v_mfma_f32_16x16x32_bf16 v[134:137], v[130:133], v[172:175], v[134:137]
	v_mfma_f32_16x16x32_bf16 v[134:137], v[142:145], v[176:179], v[134:137]
	v_mfma_f32_16x16x32_bf16 v[126:129], v[98:101], v[188:191], v[126:129]
	v_mfma_f32_16x16x32_bf16 v[126:129], v[102:105], v[192:195], v[126:129]
	v_mfma_f32_16x16x32_bf16 v[122:125], v[130:133], v[188:191], v[122:125]
	v_mfma_f32_16x16x32_bf16 v[122:125], v[142:145], v[192:195], v[122:125]
	v_mfma_f32_16x16x32_bf16 v[118:121], v[98:101], v[196:199], v[118:121]
	v_mfma_f32_16x16x32_bf16 v[118:121], v[102:105], v[200:203], v[118:121]
	v_mfma_f32_16x16x32_bf16 v[114:117], v[130:133], v[196:199], v[114:117]
	v_mfma_f32_16x16x32_bf16 v[114:117], v[142:145], v[200:203], v[114:117]
	v_mfma_f32_16x16x32_bf16 v[110:113], v[98:101], v[204:207], v[110:113]
	v_mfma_f32_16x16x32_bf16 v[110:113], v[102:105], v[214:217], v[110:113]
	v_mfma_f32_16x16x32_bf16 v[106:109], v[130:133], v[204:207], v[106:109]
	v_mfma_f32_16x16x32_bf16 v[106:109], v[142:145], v[214:217], v[106:109]
	s_setprio 0
	s_setprio 1
	v_mfma_f32_16x16x32_bf16 v[62:65], v[146:149], v[172:175], v[62:65]
	v_mfma_f32_16x16x32_bf16 v[62:65], v[160:163], v[176:179], v[62:65]
	v_mfma_f32_16x16x32_bf16 v[58:61], v[164:167], v[172:175], v[58:61]
	v_mfma_f32_16x16x32_bf16 v[58:61], v[168:171], v[176:179], v[58:61]
	v_mfma_f32_16x16x32_bf16 v[54:57], v[146:149], v[188:191], v[54:57]
	v_mfma_f32_16x16x32_bf16 v[54:57], v[160:163], v[192:195], v[54:57]
	v_mfma_f32_16x16x32_bf16 v[50:53], v[164:167], v[188:191], v[50:53]
	v_mfma_f32_16x16x32_bf16 v[50:53], v[168:171], v[192:195], v[50:53]
	v_mfma_f32_16x16x32_bf16 v[46:49], v[146:149], v[196:199], v[46:49]
	v_mfma_f32_16x16x32_bf16 v[46:49], v[160:163], v[200:203], v[46:49]
	v_mfma_f32_16x16x32_bf16 v[42:45], v[164:167], v[196:199], v[42:45]
	v_mfma_f32_16x16x32_bf16 v[42:45], v[168:171], v[200:203], v[42:45]
	v_mfma_f32_16x16x32_bf16 v[38:41], v[146:149], v[204:207], v[38:41]
	v_mfma_f32_16x16x32_bf16 v[38:41], v[160:163], v[214:217], v[38:41]
	v_mfma_f32_16x16x32_bf16 v[34:37], v[164:167], v[204:207], v[34:37]
	v_mfma_f32_16x16x32_bf16 v[34:37], v[168:171], v[214:217], v[34:37]
	s_setprio 0
	s_barrier
	s_mov_b32 m0, s35
	v_lshl_add_u64 v[180:181], s[84:85], 0, v[0:1]
	s_add_u32 s26, s84, 0x40000
	ds_read_b128 v[172:175], v186 offset:16384
	ds_read_b128 v[176:179], v186 offset:17408
	ds_read_b128 v[188:191], v186 offset:18432
	ds_read_b128 v[192:195], v186 offset:19456
	ds_read_b128 v[196:199], v186 offset:20480
	ds_read_b128 v[200:203], v186 offset:21504
	ds_read_b128 v[204:207], v186 offset:22528
	ds_read_b128 v[214:217], v186 offset:23552
	global_load_lds_dwordx4 v[180:181], off
	v_lshl_add_u64 v[182:183], s[84:85], 0, v[150:151]
	s_mov_b32 m0, s88
	s_addc_u32 s27, s85, 0
	global_load_lds_dwordx4 v[182:183], off
	v_lshl_add_u64 v[184:185], s[26:27], 0, v[0:1]
	s_mov_b32 m0, s89
	v_lshl_add_u64 v[218:219], s[86:87], 0, v[152:153]
	global_load_lds_dwordx4 v[184:185], off
	v_lshl_add_u64 v[184:185], s[26:27], 0, v[150:151]
	s_mov_b32 m0, s90
	s_nop 0
	global_load_lds_dwordx4 v[184:185], off
	v_lshl_add_u64 v[184:185], s[86:87], 0, v[154:155]
	s_mov_b32 m0, s6
	s_nop 0
	global_load_lds_dwordx4 v[184:185], off
	s_mov_b32 m0, s91
	s_nop 0
	global_load_lds_dwordx4 v[218:219], off
	s_waitcnt vmcnt(8)
	s_waitcnt lgkmcnt(0)
	s_barrier
; #define PG8_STAGE(bufoff, gbase, voff) do { _Pragma("unroll") for (int _i = 0; _i < 2; ++_i) \
;         __builtin_amdgcn_global_load_lds((const unsigned*)((const char*)(gbase) + (voff)[_i]), (PG8_LAS unsigned*)(lds + (bufoff) + ldsw + _i * 8192), 16, 0, 0); } while (0)
; #define PG8_LDA(dst, b, h) do { _Pragma("unroll") for (int m = 0; m < 4; ++m) _Pragma("unroll") for (int k = 0; k < 2; ++k) dst[m][k] = *(const PG8_LAS bf16x8*)(lds + PG8_SA(b, h) + aoff + m * 2048 + k * 1024); } while (0)
; #define PG8_LDB(dst, b, h) do { _Pragma("unroll") for (int n = 0; n < 2; ++n) _Pragma("unroll") for (int k = 0; k < 2; ++k) dst[n][k] = *(const PG8_LAS bf16x8*)(lds + PG8_SB(b, h) + boff + n * 2048 + k * 1024); } while (0)
; #define PG8_MMA(ai, bj, At, Bt) do { __builtin_amdgcn_s_setprio(1); _Pragma("unroll") for (int m = 0; m < 4; ++m) _Pragma("unroll") for (int n = 0; n < 2; ++n) _Pragma("unroll") for (int k = 0; k < 2; ++k) \
;         acc[ai][bj][m][n] = __builtin_amdgcn_mfma_f32_16x16x32_bf16(Bt[n][k], At[m][k], acc[ai][bj][m][n], 0, 0, 0); __builtin_amdgcn_s_setprio(0); } while (0)
; #define PG8_WAIT_V(n) asm volatile("s_waitcnt vmcnt(" #n ")" ::: "memory")
; #define PG8_WAIT_L(n) asm volatile("s_waitcnt lgkmcnt(" #n ")" ::: "memory")
; #define PG8_BAR __builtin_amdgcn_s_barrier()
; #define PG8_SCHED __builtin_amdgcn_sched_barrier(0)
; template <class Epi, class Sched, bool ALIGN_EPI = false, bool SP2 = false>
; __device__ __forceinline__ void gemm_phase(PG8_LAS unsigned char* lds, const Gemm g, const Sched& S, const Epi& E, const int tid) {
;     ...
;             PG8_WAIT_V(8); PG8_WAIT_L(0); PG8_BAR; PG8_MMA(1, 0, At, B0); PG8_MMA(1, 1, At, B1); PG8_BAR; PG8_SCHED;
;             PG8_LDB(B0, 1, 0); PG8_LDB(B1, 1, 1); PG8_SCHED; PG8_LDA(At, 1, 0); PG8_STAGE(PG8_SA(0, 1), a2 + hstep, voffA);
;             PG8_WAIT_V(8); PG8_WAIT_L(0); PG8_BAR; PG8_MMA(0, 0, At, B0); PG8_MMA(0, 1, At, B1); PG8_BAR; PG8_SCHED;
	s_setprio 1
	s_waitcnt lgkmcnt(0)
	v_mfma_f32_16x16x32_bf16 v[94:97], v[98:101], v[172:175], v[94:97]
	v_mfma_f32_16x16x32_bf16 v[94:97], v[102:105], v[176:179], v[94:97]
	v_mfma_f32_16x16x32_bf16 v[90:93], v[130:133], v[172:175], v[90:93]
	v_mfma_f32_16x16x32_bf16 v[90:93], v[142:145], v[176:179], v[90:93]
	v_mfma_f32_16x16x32_bf16 v[86:89], v[98:101], v[188:191], v[86:89]
	v_mfma_f32_16x16x32_bf16 v[86:89], v[102:105], v[192:195], v[86:89]
	v_mfma_f32_16x16x32_bf16 v[82:85], v[130:133], v[188:191], v[82:85]
	v_mfma_f32_16x16x32_bf16 v[82:85], v[142:145], v[192:195], v[82:85]
	v_mfma_f32_16x16x32_bf16 v[78:81], v[98:101], v[196:199], v[78:81]
	v_mfma_f32_16x16x32_bf16 v[78:81], v[102:105], v[200:203], v[78:81]
	v_mfma_f32_16x16x32_bf16 v[74:77], v[130:133], v[196:199], v[74:77]
	v_mfma_f32_16x16x32_bf16 v[74:77], v[142:145], v[200:203], v[74:77]
	v_mfma_f32_16x16x32_bf16 v[70:73], v[98:101], v[204:207], v[70:73]
	v_mfma_f32_16x16x32_bf16 v[70:73], v[102:105], v[214:217], v[70:73]
	v_mfma_f32_16x16x32_bf16 v[66:69], v[130:133], v[204:207], v[66:69]
	v_mfma_f32_16x16x32_bf16 v[66:69], v[142:145], v[214:217], v[66:69]
	s_setprio 0
	s_setprio 1
	v_mfma_f32_16x16x32_bf16 v[30:33], v[146:149], v[172:175], v[30:33]
	v_mfma_f32_16x16x32_bf16 v[30:33], v[160:163], v[176:179], v[30:33]
	v_mfma_f32_16x16x32_bf16 v[26:29], v[164:167], v[172:175], v[26:29]
	v_mfma_f32_16x16x32_bf16 v[26:29], v[168:171], v[176:179], v[26:29]
	v_mfma_f32_16x16x32_bf16 v[22:25], v[146:149], v[188:191], v[22:25]
	v_mfma_f32_16x16x32_bf16 v[22:25], v[160:163], v[192:195], v[22:25]
	v_mfma_f32_16x16x32_bf16 v[18:21], v[164:167], v[188:191], v[18:21]
	v_mfma_f32_16x16x32_bf16 v[18:21], v[168:171], v[192:195], v[18:21]
	v_mfma_f32_16x16x32_bf16 v[14:17], v[146:149], v[196:199], v[14:17]
	v_mfma_f32_16x16x32_bf16 v[14:17], v[160:163], v[200:203], v[14:17]
	v_mfma_f32_16x16x32_bf16 v[10:13], v[164:167], v[196:199], v[10:13]
	v_mfma_f32_16x16x32_bf16 v[10:13], v[168:171], v[200:203], v[10:13]
	v_mfma_f32_16x16x32_bf16 v[6:9], v[146:149], v[204:207], v[6:9]
	v_mfma_f32_16x16x32_bf16 v[6:9], v[160:163], v[214:217], v[6:9]
	v_mfma_f32_16x16x32_bf16 v[2:5], v[164:167], v[204:207], v[2:5]
	v_mfma_f32_16x16x32_bf16 v[2:5], v[168:171], v[214:217], v[2:5]
	s_setprio 0
	s_barrier
	v_or_b32_e32 v98, 0x18000, v187
	v_add_u32_e32 v102, 0x18400, v187
	v_add_u32_e32 v130, 0x18800, v187
	v_add_u32_e32 v142, 0x18c00, v187
	v_or_b32_e32 v146, 0x1c000, v187
	v_add_u32_e32 v160, 0x1c400, v187
	v_add_u32_e32 v164, 0x1c800, v187
	v_add_u32_e32 v168, 0x1cc00, v187
	ds_read_b128 v[98:101], v98
	ds_read_b128 v[102:105], v102
	ds_read_b128 v[130:133], v130
	ds_read_b128 v[142:145], v142
	ds_read_b128 v[146:149], v146
	ds_read_b128 v[160:163], v160
	ds_read_b128 v[164:167], v164
	ds_read_b128 v[168:171], v168
	s_add_u32 s26, s86, 0x40000
	s_addc_u32 s27, s87, 0
	s_mov_b32 m0, s42
	v_lshl_add_u64 v[220:221], s[26:27], 0, v[154:155]
	ds_read_b128 v[172:175], v186 offset:32768
	ds_read_b128 v[176:179], v186 offset:33792
	ds_read_b128 v[188:191], v186 offset:34816
	ds_read_b128 v[192:195], v186 offset:35840
	ds_read_b128 v[196:199], v186 offset:36864
	ds_read_b128 v[200:203], v186 offset:37888
	ds_read_b128 v[204:207], v186 offset:38912
	ds_read_b128 v[214:217], v186 offset:39936
	global_load_lds_dwordx4 v[220:221], off
	v_lshl_add_u64 v[220:221], s[26:27], 0, v[152:153]
	s_mov_b32 m0, s43
	s_nop 0
	global_load_lds_dwordx4 v[220:221], off
	s_waitcnt vmcnt(8)
	s_waitcnt lgkmcnt(0)
	s_barrier
	s_setprio 1
	s_waitcnt lgkmcnt(0)
	v_mfma_f32_16x16x32_bf16 v[138:141], v[98:101], v[172:175], v[138:141]
	v_mfma_f32_16x16x32_bf16 v[138:141], v[102:105], v[176:179], v[138:141]
	v_mfma_f32_16x16x32_bf16 v[134:137], v[130:133], v[172:175], v[134:137]
	v_mfma_f32_16x16x32_bf16 v[134:137], v[142:145], v[176:179], v[134:137]
	v_mfma_f32_16x16x32_bf16 v[126:129], v[98:101], v[188:191], v[126:129]
	v_mfma_f32_16x16x32_bf16 v[126:129], v[102:105], v[192:195], v[126:129]
	v_mfma_f32_16x16x32_bf16 v[122:125], v[130:133], v[188:191], v[122:125]
	v_mfma_f32_16x16x32_bf16 v[122:125], v[142:145], v[192:195], v[122:125]
	v_mfma_f32_16x16x32_bf16 v[118:121], v[98:101], v[196:199], v[118:121]
	v_mfma_f32_16x16x32_bf16 v[118:121], v[102:105], v[200:203], v[118:121]
	v_mfma_f32_16x16x32_bf16 v[114:117], v[130:133], v[196:199], v[114:117]
	v_mfma_f32_16x16x32_bf16 v[114:117], v[142:145], v[200:203], v[114:117]
	v_mfma_f32_16x16x32_bf16 v[110:113], v[98:101], v[204:207], v[110:113]
	v_mfma_f32_16x16x32_bf16 v[110:113], v[102:105], v[214:217], v[110:113]
	v_mfma_f32_16x16x32_bf16 v[106:109], v[130:133], v[204:207], v[106:109]
	v_mfma_f32_16x16x32_bf16 v[106:109], v[142:145], v[214:217], v[106:109]
	s_setprio 0
	s_setprio 1
	v_mfma_f32_16x16x32_bf16 v[62:65], v[146:149], v[172:175], v[62:65]
	v_mfma_f32_16x16x32_bf16 v[62:65], v[160:163], v[176:179], v[62:65]
	v_mfma_f32_16x16x32_bf16 v[58:61], v[164:167], v[172:175], v[58:61]
	v_mfma_f32_16x16x32_bf16 v[58:61], v[168:171], v[176:179], v[58:61]
	v_mfma_f32_16x16x32_bf16 v[54:57], v[146:149], v[188:191], v[54:57]
	v_mfma_f32_16x16x32_bf16 v[54:57], v[160:163], v[192:195], v[54:57]
	v_mfma_f32_16x16x32_bf16 v[50:53], v[164:167], v[188:191], v[50:53]
	v_mfma_f32_16x16x32_bf16 v[50:53], v[168:171], v[192:195], v[50:53]
	v_mfma_f32_16x16x32_bf16 v[46:49], v[146:149], v[196:199], v[46:49]
	v_mfma_f32_16x16x32_bf16 v[46:49], v[160:163], v[200:203], v[46:49]
	v_mfma_f32_16x16x32_bf16 v[42:45], v[164:167], v[196:199], v[42:45]
	v_mfma_f32_16x16x32_bf16 v[42:45], v[168:171], v[200:203], v[42:45]
	v_mfma_f32_16x16x32_bf16 v[38:41], v[146:149], v[204:207], v[38:41]
	v_mfma_f32_16x16x32_bf16 v[38:41], v[160:163], v[214:217], v[38:41]
	v_mfma_f32_16x16x32_bf16 v[34:37], v[164:167], v[204:207], v[34:37]
	v_mfma_f32_16x16x32_bf16 v[34:37], v[168:171], v[214:217], v[34:37]
	s_setprio 0
	s_barrier
; #define PG8_STAGE(bufoff, gbase, voff) do { _Pragma("unroll") for (int _i = 0; _i < 2; ++_i) \
;         __builtin_amdgcn_global_load_lds((const unsigned*)((const char*)(gbase) + (voff)[_i]), (PG8_LAS unsigned*)(lds + (bufoff) + ldsw + _i * 8192), 16, 0, 0); } while (0)
; #define PG8_LDA(dst, b, h) do { _Pragma("unroll") for (int m = 0; m < 4; ++m) _Pragma("unroll") for (int k = 0; k < 2; ++k) dst[m][k] = *(const PG8_LAS bf16x8*)(lds + PG8_SA(b, h) + aoff + m * 2048 + k * 1024); } while (0)
; #define PG8_MMA(ai, bj, At, Bt) do { __builtin_amdgcn_s_setprio(1); _Pragma("unroll") for (int m = 0; m < 4; ++m) _Pragma("unroll") for (int n = 0; n < 2; ++n) _Pragma("unroll") for (int k = 0; k < 2; ++k) \
;         acc[ai][bj][m][n] = __builtin_amdgcn_mfma_f32_16x16x32_bf16(Bt[n][k], At[m][k], acc[ai][bj][m][n], 0, 0, 0); __builtin_amdgcn_s_setprio(0); } while (0)
; #define PG8_WAIT_V(n) asm volatile("s_waitcnt vmcnt(" #n ")" ::: "memory")
; #define PG8_WAIT_L(n) asm volatile("s_waitcnt lgkmcnt(" #n ")" ::: "memory")
; #define PG8_BAR __builtin_amdgcn_s_barrier()
; #define PG8_SCHED __builtin_amdgcn_sched_barrier(0)
; template <class Epi, class Sched, bool ALIGN_EPI = false, bool SP2 = false>
; __device__ __forceinline__ void gemm_phase(PG8_LAS unsigned char* lds, const Gemm g, const Sched& S, const Epi& E, const int tid) {
;     ...
;             PG8_WAIT_V(8); PG8_WAIT_L(0); PG8_BAR; PG8_MMA(0, 0, At, B0); PG8_MMA(0, 1, At, B1); PG8_BAR; PG8_SCHED;
;             PG8_LDA(At, 1, 1); PG8_STAGE(PG8_SB(1, 0), b3, voffB); PG8_STAGE(PG8_SB(1, 1), b3 + hstep, voffB); PG8_STAGE(PG8_SA(1, 0), a3, voffA);
;             PG8_WAIT_V(8); PG8_WAIT_L(0); PG8_BAR; PG8_MMA(1, 0, At, B0); PG8_MMA(1, 1, At, B1); PG8_BAR; PG8_SCHED;
;     ...
;         if constexpr (ALIGN_EPI) { if (wr == 0) PG8_BAR; }
	s_mov_b32 m0, s40
	v_lshl_add_u64 v[180:181], v[180:181], 0, s[12:13]
	s_add_u32 s26, s84, 0x40080
	ds_read_b128 v[172:175], v186 offset:49152
	ds_read_b128 v[176:179], v186 offset:50176
	ds_read_b128 v[188:191], v186 offset:51200
	ds_read_b128 v[192:195], v186 offset:52224
	ds_read_b128 v[196:199], v186 offset:53248
	ds_read_b128 v[200:203], v186 offset:54272
	ds_read_b128 v[204:207], v186 offset:55296
	ds_read_b128 v[214:217], v186 offset:56320
	global_load_lds_dwordx4 v[180:181], off
	v_lshl_add_u64 v[180:181], v[182:183], 0, s[12:13]
	s_mov_b32 m0, s41
	s_addc_u32 s27, s85, 0
	global_load_lds_dwordx4 v[180:181], off
	v_lshl_add_u64 v[180:181], s[26:27], 0, v[0:1]
	s_mov_b32 m0, s34
	s_nop 0
	global_load_lds_dwordx4 v[180:181], off
	v_lshl_add_u64 v[180:181], s[26:27], 0, v[150:151]
	s_mov_b32 m0, s8
	s_nop 0
	global_load_lds_dwordx4 v[180:181], off
	v_lshl_add_u64 v[180:181], v[184:185], 0, s[12:13]
	s_mov_b32 m0, s1
	s_nop 0
	global_load_lds_dwordx4 v[180:181], off
	v_lshl_add_u64 v[180:181], v[218:219], 0, s[12:13]
	s_mov_b32 m0, s14
	s_nop 0
	global_load_lds_dwordx4 v[180:181], off
	s_waitcnt vmcnt(8)
	s_waitcnt lgkmcnt(0)
	s_barrier
	s_setprio 1
	s_waitcnt lgkmcnt(0)
	v_mfma_f32_16x16x32_bf16 v[94:97], v[98:101], v[172:175], v[94:97]
	v_mfma_f32_16x16x32_bf16 v[94:97], v[102:105], v[176:179], v[94:97]
	v_mfma_f32_16x16x32_bf16 v[90:93], v[130:133], v[172:175], v[90:93]
	v_mfma_f32_16x16x32_bf16 v[90:93], v[142:145], v[176:179], v[90:93]
	v_mfma_f32_16x16x32_bf16 v[86:89], v[98:101], v[188:191], v[86:89]
	v_mfma_f32_16x16x32_bf16 v[86:89], v[102:105], v[192:195], v[86:89]
	v_mfma_f32_16x16x32_bf16 v[82:85], v[130:133], v[188:191], v[82:85]
	v_mfma_f32_16x16x32_bf16 v[82:85], v[142:145], v[192:195], v[82:85]
	v_mfma_f32_16x16x32_bf16 v[78:81], v[98:101], v[196:199], v[78:81]
	v_mfma_f32_16x16x32_bf16 v[78:81], v[102:105], v[200:203], v[78:81]
	v_mfma_f32_16x16x32_bf16 v[74:77], v[130:133], v[196:199], v[74:77]
	v_mfma_f32_16x16x32_bf16 v[74:77], v[142:145], v[200:203], v[74:77]
	v_mfma_f32_16x16x32_bf16 v[70:73], v[98:101], v[204:207], v[70:73]
	v_mfma_f32_16x16x32_bf16 v[70:73], v[102:105], v[214:217], v[70:73]
	v_mfma_f32_16x16x32_bf16 v[66:69], v[130:133], v[204:207], v[66:69]
	v_mfma_f32_16x16x32_bf16 v[66:69], v[142:145], v[214:217], v[66:69]
	s_setprio 0
	s_setprio 1
	v_mfma_f32_16x16x32_bf16 v[30:33], v[146:149], v[172:175], v[30:33]
	v_mfma_f32_16x16x32_bf16 v[30:33], v[160:163], v[176:179], v[30:33]
	v_mfma_f32_16x16x32_bf16 v[26:29], v[164:167], v[172:175], v[26:29]
	v_mfma_f32_16x16x32_bf16 v[26:29], v[168:171], v[176:179], v[26:29]
	v_mfma_f32_16x16x32_bf16 v[22:25], v[146:149], v[188:191], v[22:25]
	v_mfma_f32_16x16x32_bf16 v[22:25], v[160:163], v[192:195], v[22:25]
	v_mfma_f32_16x16x32_bf16 v[18:21], v[164:167], v[188:191], v[18:21]
	v_mfma_f32_16x16x32_bf16 v[18:21], v[168:171], v[192:195], v[18:21]
	v_mfma_f32_16x16x32_bf16 v[14:17], v[146:149], v[196:199], v[14:17]
	v_mfma_f32_16x16x32_bf16 v[14:17], v[160:163], v[200:203], v[14:17]
	v_mfma_f32_16x16x32_bf16 v[10:13], v[164:167], v[196:199], v[10:13]
	v_mfma_f32_16x16x32_bf16 v[10:13], v[168:171], v[200:203], v[10:13]
	v_mfma_f32_16x16x32_bf16 v[6:9], v[146:149], v[204:207], v[6:9]
	v_mfma_f32_16x16x32_bf16 v[6:9], v[160:163], v[214:217], v[6:9]
	v_mfma_f32_16x16x32_bf16 v[2:5], v[164:167], v[204:207], v[2:5]
	v_mfma_f32_16x16x32_bf16 v[2:5], v[168:171], v[214:217], v[2:5]
	s_setprio 0
	s_barrier
	s_add_i32 s24, s24, 2
	s_add_u32 s30, s30, 0x100
	s_addc_u32 s31, s31, 0
	s_add_u32 s20, s20, 0x100
	s_addc_u32 s21, s21, 0
	s_cmp_gt_u32 s24, 13
	s_cbranch_scc0 .LBB0_355
	v_readlane_b32 s4, v255, 54
	v_readlane_b32 s5, v255, 55
	s_and_b64 vcc, exec, s[4:5]
	s_cbranch_vccz .LBB0_358
	s_barrier

; #define PG8_STAGE(bufoff, gbase, voff) do { _Pragma("unroll") for (int _i = 0; _i < 2; ++_i) \
;         __builtin_amdgcn_global_load_lds((const unsigned*)((const char*)(gbase) + (voff)[_i]), (PG8_LAS unsigned*)(lds + (bufoff) + ldsw + _i * 8192), 16, 0, 0); } while (0)
; #define PG8_LDA(dst, b, h) do { _Pragma("unroll") for (int m = 0; m < 4; ++m) _Pragma("unroll") for (int k = 0; k < 2; ++k) dst[m][k] = *(const PG8_LAS bf16x8*)(lds + PG8_SA(b, h) + aoff + m * 2048 + k * 1024); } while (0)
; #define PG8_LDB(dst, b, h) do { _Pragma("unroll") for (int n = 0; n < 2; ++n) _Pragma("unroll") for (int k = 0; k < 2; ++k) dst[n][k] = *(const PG8_LAS bf16x8*)(lds + PG8_SB(b, h) + boff + n * 2048 + k * 1024); } while (0)
; #define PG8_WAIT_V(n) asm volatile("s_waitcnt vmcnt(" #n ")" ::: "memory")
; #define PG8_WAIT_L(n) asm volatile("s_waitcnt lgkmcnt(" #n ")" ::: "memory")
; #define PG8_BAR __builtin_amdgcn_s_barrier()
; #define PG8_SCHED __builtin_amdgcn_sched_barrier(0)
; template <class Epi, class Sched, bool ALIGN_EPI = false, bool SP2 = false>
; __device__ __forceinline__ void gemm_phase(PG8_LAS unsigned char* lds, const Gemm g, const Sched& S, const Epi& E, const int tid) {
;     ...
;         const bool has_next = S.next(ui + 1, nxt);
;         const char* nA = has_next ? (const char*)g.A + (size_t)nxt.pm * tstep : cA; const char* nB = has_next ? (const char*)g.Bt + (size_t)nxt.pn * tstep : cB;
;         for (int t = 0; t < nt; t += 2) {
;             const bool last = (t == nt - 2);
;             const char* a1 = cA + (size_t)(t + 1) * kstep;
;             const char* a2 = last ? nA : cA + (size_t)(t + 2) * kstep; const char* b2 = last ? nB : cB + (size_t)(t + 2) * kstep;
;             const char* a3 = a2 + kstep; const char* b3 = b2 + kstep;
;             if (last && has_next) S.a_ready(nxt);
;             if constexpr (SP2) {
;             PG8_LDB(B0, 0, 0); PG8_LDB(B1, 0, 1); PG8_SCHED; PG8_LDA(At, 0, 0); PG8_STAGE(PG8_SA(1, 1), a1 + hstep, voffA);
;             PG8_WAIT_V(8); PG8_WAIT_L(0); PG8_BAR; PG8_MMA(0, 0, At, B0); PG8_MMA(0, 1, At, B1); PG8_BAR; PG8_SCHED;
;             PG8_LDA(At, 0, 1); PG8_STAGE(PG8_SB(0, 0), b2, voffB); PG8_STAGE(PG8_SB(0, 1), b2 + hstep, voffB); PG8_STAGE(PG8_SA(0, 0), a2, voffA);
;             PG8_WAIT_V(8); PG8_WAIT_L(0); PG8_BAR; PG8_MMA(1, 0, At, B0); PG8_MMA(1, 1, At, B1); PG8_BAR; PG8_SCHED;
.LBB0_370:
	s_ashr_i32 s43, s42, 31
	s_lshl_b64 s[44:45], s[42:43], 17
	v_readlane_b32 s41, v253, 63
	s_add_u32 s44, s41, s44
	v_readlane_b32 s41, v254, 0
	s_addc_u32 s45, s41, s45
	s_and_b64 s[46:47], s[36:37], exec
	v_or_b32_e32 v208, 0x10000, v139
	v_add_u32_e32 v210, 0x10800, v139
	v_or_b32_e32 v212, 0x14000, v139
	v_add_u32_e32 v218, 0x14800, v139
	s_cselect_b32 s87, s45, s89
	s_cselect_b32 s86, s44, s88
	s_ashr_i32 s41, s40, 31
	v_add_u32_e32 v209, 0x10400, v139
	ds_read_b128 v[2:5], v208
	ds_read_b128 v[6:9], v209
	v_add_u32_e32 v211, 0x10c00, v139
	ds_read_b128 v[10:13], v210
	ds_read_b128 v[14:17], v211
	v_add_u32_e32 v213, 0x14400, v139
	ds_read_b128 v[18:21], v212
	ds_read_b128 v[22:25], v213
	v_add_u32_e32 v219, 0x14c00, v139
	ds_read_b128 v[26:29], v218
	ds_read_b128 v[30:33], v219
	s_lshl_b64 s[46:47], s[40:41], 17
	v_readlane_b32 s50, v253, 59
	v_readlane_b32 s51, v253, 60
	s_add_u32 s46, s50, s46
	s_addc_u32 s47, s51, s47
	s_and_b64 s[50:51], s[36:37], exec
	s_cselect_b32 s85, s47, s91
	s_cselect_b32 s84, s46, s90
	s_add_u32 s50, s88, 0x10080
	s_addc_u32 s51, s89, 0
	s_add_i32 s43, s0, 0xc000
	v_lshl_add_u64 v[66:67], s[50:51], 0, v[134:135]
	s_mov_b32 m0, s43
	s_add_i32 s41, s0, 0xe000
	ds_read_b128 v[34:37], v138
	ds_read_b128 v[38:41], v138 offset:1024
	ds_read_b128 v[42:45], v138 offset:2048
	ds_read_b128 v[46:49], v138 offset:3072
	ds_read_b128 v[50:53], v138 offset:4096
	ds_read_b128 v[54:57], v138 offset:5120
	ds_read_b128 v[58:61], v138 offset:6144
	ds_read_b128 v[62:65], v138 offset:7168
	global_load_lds_dwordx4 v[66:67], off
	v_lshl_add_u64 v[66:67], s[50:51], 0, v[132:133]
	s_mov_b32 m0, s41
	s_nop 0
	global_load_lds_dwordx4 v[66:67], off
	s_waitcnt vmcnt(8)
	s_waitcnt lgkmcnt(0)
	s_barrier
	s_setprio 1
	s_waitcnt lgkmcnt(0)
	v_mfma_f32_16x16x32_bf16 v[66:69], v[2:5], v[34:37], 0
	v_mfma_f32_16x16x32_bf16 v[70:73], v[10:13], v[34:37], 0
	v_mfma_f32_16x16x32_bf16 v[74:77], v[2:5], v[42:45], 0
	v_mfma_f32_16x16x32_bf16 v[78:81], v[10:13], v[42:45], 0
	v_mfma_f32_16x16x32_bf16 v[82:85], v[2:5], v[50:53], 0
	v_mfma_f32_16x16x32_bf16 v[86:89], v[10:13], v[50:53], 0
	v_mfma_f32_16x16x32_bf16 v[90:93], v[2:5], v[58:61], 0
	v_mfma_f32_16x16x32_bf16 v[94:97], v[10:13], v[58:61], 0
	v_mfma_f32_16x16x32_bf16 v[66:69], v[6:9], v[38:41], v[66:69]
	v_mfma_f32_16x16x32_bf16 v[70:73], v[14:17], v[38:41], v[70:73]
	v_mfma_f32_16x16x32_bf16 v[74:77], v[6:9], v[46:49], v[74:77]
	v_mfma_f32_16x16x32_bf16 v[78:81], v[14:17], v[46:49], v[78:81]
	v_mfma_f32_16x16x32_bf16 v[82:85], v[6:9], v[54:57], v[82:85]
	v_mfma_f32_16x16x32_bf16 v[86:89], v[14:17], v[54:57], v[86:89]
	v_mfma_f32_16x16x32_bf16 v[90:93], v[6:9], v[62:65], v[90:93]
	v_mfma_f32_16x16x32_bf16 v[94:97], v[14:17], v[62:65], v[94:97]
	s_setprio 0
	s_setprio 1
	v_mfma_f32_16x16x32_bf16 v[98:101], v[18:21], v[34:37], 0
	v_mfma_f32_16x16x32_bf16 v[34:37], v[26:29], v[34:37], 0
	v_mfma_f32_16x16x32_bf16 v[98:101], v[22:25], v[38:41], v[98:101]
	v_mfma_f32_16x16x32_bf16 v[34:37], v[30:33], v[38:41], v[34:37]
	v_mfma_f32_16x16x32_bf16 v[38:41], v[18:21], v[42:45], 0
	v_mfma_f32_16x16x32_bf16 v[42:45], v[26:29], v[42:45], 0
	v_mfma_f32_16x16x32_bf16 v[38:41], v[22:25], v[46:49], v[38:41]
	v_mfma_f32_16x16x32_bf16 v[42:45], v[30:33], v[46:49], v[42:45]
	v_mfma_f32_16x16x32_bf16 v[46:49], v[18:21], v[50:53], 0
	v_mfma_f32_16x16x32_bf16 v[50:53], v[26:29], v[50:53], 0
	v_mfma_f32_16x16x32_bf16 v[46:49], v[22:25], v[54:57], v[46:49]
	v_mfma_f32_16x16x32_bf16 v[50:53], v[30:33], v[54:57], v[50:53]
	v_mfma_f32_16x16x32_bf16 v[54:57], v[18:21], v[58:61], 0
	v_mfma_f32_16x16x32_bf16 v[58:61], v[26:29], v[58:61], 0
	v_mfma_f32_16x16x32_bf16 v[54:57], v[22:25], v[62:65], v[54:57]
	v_mfma_f32_16x16x32_bf16 v[58:61], v[30:33], v[62:65], v[58:61]
	s_setprio 0
	s_barrier
	v_lshl_add_u64 v[136:137], s[90:91], 0, v[0:1]
	s_mov_b64 s[92:93], 0x100
	s_mov_b32 m0, s1
	v_lshl_add_u64 v[140:141], v[136:137], 0, s[92:93]
	v_lshl_add_u64 v[180:181], s[90:91], 0, v[130:131]
	s_add_u32 s50, s90, 0x10100
	ds_read_b128 v[62:65], v138 offset:16384
	ds_read_b128 v[102:105], v138 offset:17408
	ds_read_b128 v[106:109], v138 offset:18432
	ds_read_b128 v[110:113], v138 offset:19456
	ds_read_b128 v[114:117], v138 offset:20480
	ds_read_b128 v[118:121], v138 offset:21504
	ds_read_b128 v[122:125], v138 offset:22528
	ds_read_b128 v[126:129], v138 offset:23552
	global_load_lds_dwordx4 v[140:141], off
	v_lshl_add_u64 v[140:141], v[180:181], 0, s[92:93]
	s_mov_b32 m0, s2
	s_addc_u32 s51, s91, 0
	global_load_lds_dwordx4 v[140:141], off
	v_lshl_add_u64 v[140:141], s[50:51], 0, v[0:1]
	s_mov_b32 m0, s4
	v_lshl_add_u64 v[182:183], s[88:89], 0, v[134:135]
	global_load_lds_dwordx4 v[140:141], off
	v_lshl_add_u64 v[140:141], s[50:51], 0, v[130:131]
	s_mov_b32 m0, s5
	v_lshl_add_u64 v[214:215], s[88:89], 0, v[132:133]
	global_load_lds_dwordx4 v[140:141], off
	v_lshl_add_u64 v[140:141], v[182:183], 0, s[92:93]
	s_mov_b32 m0, s0
	s_nop 0
	global_load_lds_dwordx4 v[140:141], off
	v_lshl_add_u64 v[140:141], v[214:215], 0, s[92:93]
	s_mov_b32 m0, s6
	s_nop 0
	global_load_lds_dwordx4 v[140:141], off
	s_waitcnt vmcnt(8)
	s_waitcnt lgkmcnt(0)
	s_barrier
; #define PG8_STAGE(bufoff, gbase, voff) do { _Pragma("unroll") for (int _i = 0; _i < 2; ++_i) \
;         __builtin_amdgcn_global_load_lds((const unsigned*)((const char*)(gbase) + (voff)[_i]), (PG8_LAS unsigned*)(lds + (bufoff) + ldsw + _i * 8192), 16, 0, 0); } while (0)
; #define PG8_LDA(dst, b, h) do { _Pragma("unroll") for (int m = 0; m < 4; ++m) _Pragma("unroll") for (int k = 0; k < 2; ++k) dst[m][k] = *(const PG8_LAS bf16x8*)(lds + PG8_SA(b, h) + aoff + m * 2048 + k * 1024); } while (0)
; #define PG8_LDB(dst, b, h) do { _Pragma("unroll") for (int n = 0; n < 2; ++n) _Pragma("unroll") for (int k = 0; k < 2; ++k) dst[n][k] = *(const PG8_LAS bf16x8*)(lds + PG8_SB(b, h) + boff + n * 2048 + k * 1024); } while (0)
; #define PG8_MMA(ai, bj, At, Bt) do { __builtin_amdgcn_s_setprio(1); _Pragma("unroll") for (int m = 0; m < 4; ++m) _Pragma("unroll") for (int n = 0; n < 2; ++n) _Pragma("unroll") for (int k = 0; k < 2; ++k) \
;         acc[ai][bj][m][n] = __builtin_amdgcn_mfma_f32_16x16x32_bf16(Bt[n][k], At[m][k], acc[ai][bj][m][n], 0, 0, 0); __builtin_amdgcn_s_setprio(0); } while (0)
; #define PG8_WAIT_V(n) asm volatile("s_waitcnt vmcnt(" #n ")" ::: "memory")
; #define PG8_WAIT_L(n) asm volatile("s_waitcnt lgkmcnt(" #n ")" ::: "memory")
; #define PG8_BAR __builtin_amdgcn_s_barrier()
; #define PG8_SCHED __builtin_amdgcn_sched_barrier(0)
; template <class Epi, class Sched, bool ALIGN_EPI = false, bool SP2 = false>
; __device__ __forceinline__ void gemm_phase(PG8_LAS unsigned char* lds, const Gemm g, const Sched& S, const Epi& E, const int tid) {
;     ...
;             PG8_WAIT_V(8); PG8_WAIT_L(0); PG8_BAR; PG8_MMA(1, 0, At, B0); PG8_MMA(1, 1, At, B1); PG8_BAR; PG8_SCHED;
;             PG8_LDB(B0, 1, 0); PG8_LDB(B1, 1, 1); PG8_SCHED; PG8_LDA(At, 1, 0); PG8_STAGE(PG8_SA(0, 1), a2 + hstep, voffA);
;             PG8_WAIT_V(8); PG8_WAIT_L(0); PG8_BAR; PG8_MMA(0, 0, At, B0); PG8_MMA(0, 1, At, B1); PG8_BAR; PG8_SCHED;
	s_setprio 1
	s_waitcnt lgkmcnt(0)
	v_mfma_f32_16x16x32_bf16 v[140:143], v[2:5], v[62:65], 0
	v_mfma_f32_16x16x32_bf16 v[148:151], v[2:5], v[106:109], 0
	v_mfma_f32_16x16x32_bf16 v[156:159], v[2:5], v[114:117], 0
	v_mfma_f32_16x16x32_bf16 v[2:5], v[2:5], v[122:125], 0
	v_mfma_f32_16x16x32_bf16 v[140:143], v[6:9], v[102:105], v[140:143]
	v_mfma_f32_16x16x32_bf16 v[148:151], v[6:9], v[110:113], v[148:151]
	v_mfma_f32_16x16x32_bf16 v[156:159], v[6:9], v[118:121], v[156:159]
	v_mfma_f32_16x16x32_bf16 v[2:5], v[6:9], v[126:129], v[2:5]
	v_mfma_f32_16x16x32_bf16 v[6:9], v[10:13], v[122:125], 0
	v_mfma_f32_16x16x32_bf16 v[144:147], v[10:13], v[62:65], 0
	v_mfma_f32_16x16x32_bf16 v[152:155], v[10:13], v[106:109], 0
	v_mfma_f32_16x16x32_bf16 v[160:163], v[10:13], v[114:117], 0
	v_mfma_f32_16x16x32_bf16 v[6:9], v[14:17], v[126:129], v[6:9]
	v_mfma_f32_16x16x32_bf16 v[144:147], v[14:17], v[102:105], v[144:147]
	v_mfma_f32_16x16x32_bf16 v[152:155], v[14:17], v[110:113], v[152:155]
	v_mfma_f32_16x16x32_bf16 v[160:163], v[14:17], v[118:121], v[160:163]
	s_setprio 0
	s_setprio 1
	v_mfma_f32_16x16x32_bf16 v[10:13], v[18:21], v[62:65], 0
	v_mfma_f32_16x16x32_bf16 v[14:17], v[26:29], v[62:65], 0
	v_mfma_f32_16x16x32_bf16 v[10:13], v[22:25], v[102:105], v[10:13]
	v_mfma_f32_16x16x32_bf16 v[14:17], v[30:33], v[102:105], v[14:17]
	v_mfma_f32_16x16x32_bf16 v[62:65], v[18:21], v[106:109], 0
	v_mfma_f32_16x16x32_bf16 v[102:105], v[26:29], v[106:109], 0
	v_mfma_f32_16x16x32_bf16 v[106:109], v[18:21], v[114:117], 0
	v_mfma_f32_16x16x32_bf16 v[18:21], v[18:21], v[122:125], 0
	v_mfma_f32_16x16x32_bf16 v[62:65], v[22:25], v[110:113], v[62:65]
	v_mfma_f32_16x16x32_bf16 v[102:105], v[30:33], v[110:113], v[102:105]
	v_mfma_f32_16x16x32_bf16 v[106:109], v[22:25], v[118:121], v[106:109]
	v_mfma_f32_16x16x32_bf16 v[110:113], v[26:29], v[114:117], 0
	v_mfma_f32_16x16x32_bf16 v[18:21], v[22:25], v[126:129], v[18:21]
	v_mfma_f32_16x16x32_bf16 v[22:25], v[26:29], v[122:125], 0
	v_mfma_f32_16x16x32_bf16 v[110:113], v[30:33], v[118:121], v[110:113]
	v_mfma_f32_16x16x32_bf16 v[22:25], v[30:33], v[126:129], v[22:25]
	s_setprio 0
	s_barrier
	v_or_b32_e32 v222, 0x18000, v139
	v_add_u32_e32 v224, 0x18800, v139
	v_or_b32_e32 v226, 0x1c000, v139
	v_add_u32_e32 v228, 0x1c800, v139
	v_add_u32_e32 v223, 0x18400, v139
	ds_read_b128 v[26:29], v222
	ds_read_b128 v[30:33], v223
	v_add_u32_e32 v225, 0x18c00, v139
	ds_read_b128 v[114:117], v224
	ds_read_b128 v[118:121], v225
	v_add_u32_e32 v227, 0x1c400, v139
	ds_read_b128 v[122:125], v226
	ds_read_b128 v[126:129], v227
	v_add_u32_e32 v230, 0x1cc00, v139
	ds_read_b128 v[164:167], v228
	ds_read_b128 v[168:171], v230
	s_add_u32 s50, s88, 0x10100
	s_addc_u32 s51, s89, 0
	s_mov_b32 m0, s8
	v_lshl_add_u64 v[216:217], s[50:51], 0, v[134:135]
	ds_read_b128 v[172:175], v138 offset:32768
	ds_read_b128 v[176:179], v138 offset:33792
	ds_read_b128 v[184:187], v138 offset:34816
	ds_read_b128 v[188:191], v138 offset:35840
	ds_read_b128 v[192:195], v138 offset:36864
	ds_read_b128 v[196:199], v138 offset:37888
	ds_read_b128 v[200:203], v138 offset:38912
	ds_read_b128 v[204:207], v138 offset:39936
	global_load_lds_dwordx4 v[216:217], off
	v_lshl_add_u64 v[216:217], s[50:51], 0, v[132:133]
	s_mov_b32 m0, s9
	s_nop 0
	global_load_lds_dwordx4 v[216:217], off
	s_waitcnt vmcnt(8)
	s_waitcnt lgkmcnt(0)
	s_barrier
	s_setprio 1
	s_waitcnt lgkmcnt(0)
	v_mfma_f32_16x16x32_bf16 v[66:69], v[26:29], v[172:175], v[66:69]
	v_mfma_f32_16x16x32_bf16 v[66:69], v[30:33], v[176:179], v[66:69]
	v_mfma_f32_16x16x32_bf16 v[70:73], v[114:117], v[172:175], v[70:73]
	v_mfma_f32_16x16x32_bf16 v[70:73], v[118:121], v[176:179], v[70:73]
	v_mfma_f32_16x16x32_bf16 v[74:77], v[26:29], v[184:187], v[74:77]
	v_mfma_f32_16x16x32_bf16 v[74:77], v[30:33], v[188:191], v[74:77]
	v_mfma_f32_16x16x32_bf16 v[78:81], v[114:117], v[184:187], v[78:81]
	v_mfma_f32_16x16x32_bf16 v[78:81], v[118:121], v[188:191], v[78:81]
	v_mfma_f32_16x16x32_bf16 v[82:85], v[26:29], v[192:195], v[82:85]
	v_mfma_f32_16x16x32_bf16 v[82:85], v[30:33], v[196:199], v[82:85]
	v_mfma_f32_16x16x32_bf16 v[86:89], v[114:117], v[192:195], v[86:89]
	v_mfma_f32_16x16x32_bf16 v[86:89], v[118:121], v[196:199], v[86:89]
	v_mfma_f32_16x16x32_bf16 v[90:93], v[26:29], v[200:203], v[90:93]
	v_mfma_f32_16x16x32_bf16 v[90:93], v[30:33], v[204:207], v[90:93]
	v_mfma_f32_16x16x32_bf16 v[94:97], v[114:117], v[200:203], v[94:97]
	v_mfma_f32_16x16x32_bf16 v[94:97], v[118:121], v[204:207], v[94:97]
	s_setprio 0
	s_setprio 1
	v_mfma_f32_16x16x32_bf16 v[98:101], v[122:125], v[172:175], v[98:101]
	v_mfma_f32_16x16x32_bf16 v[98:101], v[126:129], v[176:179], v[98:101]
	v_mfma_f32_16x16x32_bf16 v[34:37], v[164:167], v[172:175], v[34:37]
	v_mfma_f32_16x16x32_bf16 v[34:37], v[168:171], v[176:179], v[34:37]
	v_mfma_f32_16x16x32_bf16 v[38:41], v[122:125], v[184:187], v[38:41]
	v_mfma_f32_16x16x32_bf16 v[38:41], v[126:129], v[188:191], v[38:41]
	v_mfma_f32_16x16x32_bf16 v[42:45], v[164:167], v[184:187], v[42:45]
	v_mfma_f32_16x16x32_bf16 v[42:45], v[168:171], v[188:191], v[42:45]
	v_mfma_f32_16x16x32_bf16 v[46:49], v[122:125], v[192:195], v[46:49]
	v_mfma_f32_16x16x32_bf16 v[46:49], v[126:129], v[196:199], v[46:49]
	v_mfma_f32_16x16x32_bf16 v[50:53], v[164:167], v[192:195], v[50:53]
	v_mfma_f32_16x16x32_bf16 v[50:53], v[168:171], v[196:199], v[50:53]
	v_mfma_f32_16x16x32_bf16 v[54:57], v[122:125], v[200:203], v[54:57]
	v_mfma_f32_16x16x32_bf16 v[54:57], v[126:129], v[204:207], v[54:57]
	v_mfma_f32_16x16x32_bf16 v[58:61], v[164:167], v[200:203], v[58:61]
	v_mfma_f32_16x16x32_bf16 v[58:61], v[168:171], v[204:207], v[58:61]
	s_setprio 0
	s_barrier
; #define PG8_STAGE(bufoff, gbase, voff) do { _Pragma("unroll") for (int _i = 0; _i < 2; ++_i) \
;         __builtin_amdgcn_global_load_lds((const unsigned*)((const char*)(gbase) + (voff)[_i]), (PG8_LAS unsigned*)(lds + (bufoff) + ldsw + _i * 8192), 16, 0, 0); } while (0)
; #define PG8_LDA(dst, b, h) do { _Pragma("unroll") for (int m = 0; m < 4; ++m) _Pragma("unroll") for (int k = 0; k < 2; ++k) dst[m][k] = *(const PG8_LAS bf16x8*)(lds + PG8_SA(b, h) + aoff + m * 2048 + k * 1024); } while (0)
; #define PG8_LDB(dst, b, h) do { _Pragma("unroll") for (int n = 0; n < 2; ++n) _Pragma("unroll") for (int k = 0; k < 2; ++k) dst[n][k] = *(const PG8_LAS bf16x8*)(lds + PG8_SB(b, h) + boff + n * 2048 + k * 1024); } while (0)
; #define PG8_MMA(ai, bj, At, Bt) do { __builtin_amdgcn_s_setprio(1); _Pragma("unroll") for (int m = 0; m < 4; ++m) _Pragma("unroll") for (int n = 0; n < 2; ++n) _Pragma("unroll") for (int k = 0; k < 2; ++k) \
;         acc[ai][bj][m][n] = __builtin_amdgcn_mfma_f32_16x16x32_bf16(Bt[n][k], At[m][k], acc[ai][bj][m][n], 0, 0, 0); __builtin_amdgcn_s_setprio(0); } while (0)
; #define PG8_BAR __builtin_amdgcn_s_barrier()
; template <class Epi, class Sched, bool ALIGN_EPI = false, bool SP2 = false>
; __device__ __forceinline__ void gemm_phase(PG8_LAS unsigned char* lds, const Gemm g, const Sched& S, const Epi& E, const int tid) {
;     ...
;             PG8_LDB(B0, 0, 0); PG8_LDB(B1, 0, 1); PG8_SCHED; PG8_LDA(At, 0, 0); PG8_STAGE(PG8_SA(1, 1), a1 + hstep, voffA);
;             PG8_WAIT_V(8); PG8_WAIT_L(0); PG8_BAR; PG8_MMA(0, 0, At, B0); PG8_MMA(0, 1, At, B1); PG8_BAR; PG8_SCHED;
;             PG8_LDA(At, 0, 1); PG8_STAGE(PG8_SB(0, 0), b2, voffB); PG8_STAGE(PG8_SB(0, 1), b2 + hstep, voffB); PG8_STAGE(PG8_SA(0, 0), a2, voffA);
;             PG8_WAIT_V(8); PG8_WAIT_L(0); PG8_BAR; PG8_MMA(1, 0, At, B0); PG8_MMA(1, 1, At, B1); PG8_BAR; PG8_SCHED;
;             PG8_LDB(B0, 1, 0); PG8_LDB(B1, 1, 1); PG8_SCHED; PG8_LDA(At, 1, 0); PG8_STAGE(PG8_SA(0, 1), a2 + hstep, voffA);
;             PG8_WAIT_V(8); PG8_WAIT_L(0); PG8_BAR; PG8_MMA(0, 0, At, B0); PG8_MMA(0, 1, At, B1); PG8_BAR; PG8_SCHED;
;             PG8_LDA(At, 1, 1); PG8_STAGE(PG8_SB(1, 0), b3, voffB); PG8_STAGE(PG8_SB(1, 1), b3 + hstep, voffB); PG8_STAGE(PG8_SA(1, 0), a3, voffA);
;             PG8_WAIT_V(8); PG8_WAIT_L(0); PG8_BAR; PG8_MMA(1, 0, At, B0); PG8_MMA(1, 1, At, B1); PG8_BAR; PG8_SCHED;
	s_mov_b64 s[92:93], 0x180
	s_mov_b32 m0, s17
	v_lshl_add_u64 v[136:137], v[136:137], 0, s[92:93]
	s_add_u32 s50, s90, 0x10180
	ds_read_b128 v[172:175], v138 offset:49152
	ds_read_b128 v[176:179], v138 offset:50176
	ds_read_b128 v[184:187], v138 offset:51200
	ds_read_b128 v[188:191], v138 offset:52224
	ds_read_b128 v[192:195], v138 offset:53248
	ds_read_b128 v[196:199], v138 offset:54272
	ds_read_b128 v[200:203], v138 offset:55296
	ds_read_b128 v[204:207], v138 offset:56320
	global_load_lds_dwordx4 v[136:137], off
	v_lshl_add_u64 v[136:137], v[180:181], 0, s[92:93]
	s_mov_b32 m0, s20
	s_addc_u32 s51, s91, 0
	global_load_lds_dwordx4 v[136:137], off
	v_lshl_add_u64 v[136:137], s[50:51], 0, v[0:1]
	s_mov_b32 m0, s26
	s_nop 0
	global_load_lds_dwordx4 v[136:137], off
	v_lshl_add_u64 v[136:137], s[50:51], 0, v[130:131]
	s_mov_b32 m0, s27
	s_nop 0
	global_load_lds_dwordx4 v[136:137], off
	v_lshl_add_u64 v[136:137], v[182:183], 0, s[92:93]
	s_mov_b32 m0, s21
	s_nop 0
	global_load_lds_dwordx4 v[136:137], off
	v_lshl_add_u64 v[136:137], v[214:215], 0, s[92:93]
	s_mov_b32 m0, s24
	s_nop 0
	global_load_lds_dwordx4 v[136:137], off
	s_waitcnt vmcnt(8)
	s_waitcnt lgkmcnt(0)
	s_barrier
	s_setprio 1
	s_waitcnt lgkmcnt(0)
	v_mfma_f32_16x16x32_bf16 v[2:5], v[26:29], v[200:203], v[2:5]
	v_mfma_f32_16x16x32_bf16 v[2:5], v[30:33], v[204:207], v[2:5]
	v_mfma_f32_16x16x32_bf16 v[6:9], v[114:117], v[200:203], v[6:9]
	v_mfma_f32_16x16x32_bf16 v[6:9], v[118:121], v[204:207], v[6:9]
	v_mfma_f32_16x16x32_bf16 v[140:143], v[26:29], v[172:175], v[140:143]
	v_mfma_f32_16x16x32_bf16 v[140:143], v[30:33], v[176:179], v[140:143]
	v_mfma_f32_16x16x32_bf16 v[144:147], v[114:117], v[172:175], v[144:147]
	v_mfma_f32_16x16x32_bf16 v[144:147], v[118:121], v[176:179], v[144:147]
	v_mfma_f32_16x16x32_bf16 v[148:151], v[26:29], v[184:187], v[148:151]
	v_mfma_f32_16x16x32_bf16 v[148:151], v[30:33], v[188:191], v[148:151]
	v_mfma_f32_16x16x32_bf16 v[152:155], v[114:117], v[184:187], v[152:155]
	v_mfma_f32_16x16x32_bf16 v[152:155], v[118:121], v[188:191], v[152:155]
	v_mfma_f32_16x16x32_bf16 v[156:159], v[26:29], v[192:195], v[156:159]
	v_mfma_f32_16x16x32_bf16 v[156:159], v[30:33], v[196:199], v[156:159]
	v_mfma_f32_16x16x32_bf16 v[160:163], v[114:117], v[192:195], v[160:163]
	v_mfma_f32_16x16x32_bf16 v[160:163], v[118:121], v[196:199], v[160:163]
	s_setprio 0
	s_setprio 1
	v_mfma_f32_16x16x32_bf16 v[10:13], v[122:125], v[172:175], v[10:13]
	v_mfma_f32_16x16x32_bf16 v[14:17], v[164:167], v[172:175], v[14:17]
	v_mfma_f32_16x16x32_bf16 v[26:29], v[122:125], v[184:187], v[62:65]
	v_mfma_f32_16x16x32_bf16 v[30:33], v[164:167], v[184:187], v[102:105]
	v_mfma_f32_16x16x32_bf16 v[62:65], v[122:125], v[192:195], v[106:109]
	v_mfma_f32_16x16x32_bf16 v[102:105], v[164:167], v[192:195], v[110:113]
	v_mfma_f32_16x16x32_bf16 v[18:21], v[122:125], v[200:203], v[18:21]
	v_mfma_f32_16x16x32_bf16 v[22:25], v[164:167], v[200:203], v[22:25]
	v_mfma_f32_16x16x32_bf16 v[10:13], v[126:129], v[176:179], v[10:13]
	v_mfma_f32_16x16x32_bf16 v[14:17], v[168:171], v[176:179], v[14:17]
	v_mfma_f32_16x16x32_bf16 v[26:29], v[126:129], v[188:191], v[26:29]
	v_mfma_f32_16x16x32_bf16 v[30:33], v[168:171], v[188:191], v[30:33]
	v_mfma_f32_16x16x32_bf16 v[62:65], v[126:129], v[196:199], v[62:65]
	v_mfma_f32_16x16x32_bf16 v[102:105], v[168:171], v[196:199], v[102:105]
	v_mfma_f32_16x16x32_bf16 v[18:21], v[126:129], v[204:207], v[18:21]
	v_mfma_f32_16x16x32_bf16 v[22:25], v[168:171], v[204:207], v[22:25]
	s_setprio 0
	s_barrier
	ds_read_b128 v[106:109], v208
	ds_read_b128 v[110:113], v209
	ds_read_b128 v[114:117], v210
	ds_read_b128 v[118:121], v211
	ds_read_b128 v[122:125], v212
	ds_read_b128 v[126:129], v213
	ds_read_b128 v[164:167], v218
	ds_read_b128 v[168:171], v219
	s_add_u32 s50, s88, 0x10180
	s_addc_u32 s51, s89, 0
	s_mov_b32 m0, s43
	v_lshl_add_u64 v[136:137], s[50:51], 0, v[134:135]
	ds_read_b128 v[172:175], v138
	ds_read_b128 v[176:179], v138 offset:1024
	ds_read_b128 v[184:187], v138 offset:2048
	ds_read_b128 v[188:191], v138 offset:3072
	ds_read_b128 v[192:195], v138 offset:4096
	ds_read_b128 v[196:199], v138 offset:5120
	ds_read_b128 v[200:203], v138 offset:6144
	ds_read_b128 v[204:207], v138 offset:7168
	global_load_lds_dwordx4 v[136:137], off
	v_lshl_add_u64 v[136:137], s[50:51], 0, v[132:133]
	s_mov_b32 m0, s41
	s_nop 0
	global_load_lds_dwordx4 v[136:137], off
	s_waitcnt vmcnt(8)
	s_waitcnt lgkmcnt(0)
	s_barrier
	s_setprio 1
	s_waitcnt lgkmcnt(0)
	v_mfma_f32_16x16x32_bf16 v[66:69], v[106:109], v[172:175], v[66:69]
	v_mfma_f32_16x16x32_bf16 v[70:73], v[114:117], v[172:175], v[70:73]
	v_mfma_f32_16x16x32_bf16 v[74:77], v[106:109], v[184:187], v[74:77]
	v_mfma_f32_16x16x32_bf16 v[78:81], v[114:117], v[184:187], v[78:81]
	v_mfma_f32_16x16x32_bf16 v[82:85], v[106:109], v[192:195], v[82:85]
	v_mfma_f32_16x16x32_bf16 v[86:89], v[114:117], v[192:195], v[86:89]
	v_mfma_f32_16x16x32_bf16 v[90:93], v[106:109], v[200:203], v[90:93]
	v_mfma_f32_16x16x32_bf16 v[66:69], v[110:113], v[176:179], v[66:69]
	v_mfma_f32_16x16x32_bf16 v[70:73], v[118:121], v[176:179], v[70:73]
	v_mfma_f32_16x16x32_bf16 v[74:77], v[110:113], v[188:191], v[74:77]
	v_mfma_f32_16x16x32_bf16 v[78:81], v[118:121], v[188:191], v[78:81]
	v_mfma_f32_16x16x32_bf16 v[82:85], v[110:113], v[196:199], v[82:85]
	v_mfma_f32_16x16x32_bf16 v[86:89], v[118:121], v[196:199], v[86:89]
	v_mfma_f32_16x16x32_bf16 v[90:93], v[110:113], v[204:207], v[90:93]
	v_mfma_f32_16x16x32_bf16 v[94:97], v[114:117], v[200:203], v[94:97]
	v_mfma_f32_16x16x32_bf16 v[214:217], v[118:121], v[204:207], v[94:97]
	s_setprio 0
	s_setprio 1
	v_mfma_f32_16x16x32_bf16 v[94:97], v[122:125], v[172:175], v[98:101]
	v_mfma_f32_16x16x32_bf16 v[34:37], v[164:167], v[172:175], v[34:37]
	v_mfma_f32_16x16x32_bf16 v[38:41], v[122:125], v[184:187], v[38:41]
	v_mfma_f32_16x16x32_bf16 v[42:45], v[164:167], v[184:187], v[42:45]
	v_mfma_f32_16x16x32_bf16 v[46:49], v[122:125], v[192:195], v[46:49]
	v_mfma_f32_16x16x32_bf16 v[50:53], v[164:167], v[192:195], v[50:53]
	v_mfma_f32_16x16x32_bf16 v[54:57], v[122:125], v[200:203], v[54:57]
	v_mfma_f32_16x16x32_bf16 v[98:101], v[126:129], v[176:179], v[94:97]
	v_mfma_f32_16x16x32_bf16 v[34:37], v[168:171], v[176:179], v[34:37]
	v_mfma_f32_16x16x32_bf16 v[38:41], v[126:129], v[188:191], v[38:41]
	v_mfma_f32_16x16x32_bf16 v[42:45], v[168:171], v[188:191], v[42:45]
	v_mfma_f32_16x16x32_bf16 v[46:49], v[126:129], v[196:199], v[46:49]
	v_mfma_f32_16x16x32_bf16 v[50:53], v[168:171], v[196:199], v[50:53]
	v_mfma_f32_16x16x32_bf16 v[172:175], v[126:129], v[204:207], v[54:57]
	v_mfma_f32_16x16x32_bf16 v[54:57], v[164:167], v[200:203], v[58:61]
	v_mfma_f32_16x16x32_bf16 v[176:179], v[168:171], v[204:207], v[54:57]
	s_setprio 0
	s_barrier
; #define PG8_STAGE(bufoff, gbase, voff) do { _Pragma("unroll") for (int _i = 0; _i < 2; ++_i) \
;         __builtin_amdgcn_global_load_lds((const unsigned*)((const char*)(gbase) + (voff)[_i]), (PG8_LAS unsigned*)(lds + (bufoff) + ldsw + _i * 8192), 16, 0, 0); } while (0)
; #define PG8_LDA(dst, b, h) do { _Pragma("unroll") for (int m = 0; m < 4; ++m) _Pragma("unroll") for (int k = 0; k < 2; ++k) dst[m][k] = *(const PG8_LAS bf16x8*)(lds + PG8_SA(b, h) + aoff + m * 2048 + k * 1024); } while (0)
; #define PG8_LDB(dst, b, h) do { _Pragma("unroll") for (int n = 0; n < 2; ++n) _Pragma("unroll") for (int k = 0; k < 2; ++k) dst[n][k] = *(const PG8_LAS bf16x8*)(lds + PG8_SB(b, h) + boff + n * 2048 + k * 1024); } while (0)
; #define PG8_MMA(ai, bj, At, Bt) do { __builtin_amdgcn_s_setprio(1); _Pragma("unroll") for (int m = 0; m < 4; ++m) _Pragma("unroll") for (int n = 0; n < 2; ++n) _Pragma("unroll") for (int k = 0; k < 2; ++k) \
;         acc[ai][bj][m][n] = __builtin_amdgcn_mfma_f32_16x16x32_bf16(Bt[n][k], At[m][k], acc[ai][bj][m][n], 0, 0, 0); __builtin_amdgcn_s_setprio(0); } while (0)
; #define PG8_WAIT_V(n) asm volatile("s_waitcnt vmcnt(" #n ")" ::: "memory")
; #define PG8_WAIT_L(n) asm volatile("s_waitcnt lgkmcnt(" #n ")" ::: "memory")
; #define PG8_BAR __builtin_amdgcn_s_barrier()
; #define PG8_SCHED __builtin_amdgcn_sched_barrier(0)
; template <class Epi, class Sched, bool ALIGN_EPI = false, bool SP2 = false>
; __device__ __forceinline__ void gemm_phase(PG8_LAS unsigned char* lds, const Gemm g, const Sched& S, const Epi& E, const int tid) {
;     ...
;             PG8_LDA(At, 0, 1); PG8_STAGE(PG8_SB(0, 0), b2, voffB); PG8_STAGE(PG8_SB(0, 1), b2 + hstep, voffB); PG8_STAGE(PG8_SA(0, 0), a2, voffA);
;             PG8_WAIT_V(8); PG8_WAIT_L(0); PG8_BAR; PG8_MMA(1, 0, At, B0); PG8_MMA(1, 1, At, B1); PG8_BAR; PG8_SCHED;
;             PG8_LDB(B0, 1, 0); PG8_LDB(B1, 1, 1); PG8_SCHED; PG8_LDA(At, 1, 0); PG8_STAGE(PG8_SA(0, 1), a2 + hstep, voffA);
;             PG8_WAIT_V(8); PG8_WAIT_L(0); PG8_BAR; PG8_MMA(0, 0, At, B0); PG8_MMA(0, 1, At, B1); PG8_BAR; PG8_SCHED;
	s_mov_b32 m0, s1
	v_lshl_add_u64 v[136:137], s[84:85], 0, v[0:1]
	s_add_u32 s50, s84, 0x10000
	s_nop 1
	ds_read_b128 v[54:57], v138 offset:16384
	ds_read_b128 v[58:61], v138 offset:17408
	ds_read_b128 v[94:97], v138 offset:18432
	ds_read_b128 v[184:187], v138 offset:19456
	ds_read_b128 v[188:191], v138 offset:20480
	ds_read_b128 v[192:195], v138 offset:21504
	ds_read_b128 v[196:199], v138 offset:22528
	ds_read_b128 v[200:203], v138 offset:23552
	global_load_lds_dwordx4 v[136:137], off
	v_lshl_add_u64 v[208:209], s[84:85], 0, v[130:131]
	s_mov_b32 m0, s2
	s_addc_u32 s51, s85, 0
	global_load_lds_dwordx4 v[208:209], off
	v_lshl_add_u64 v[180:181], s[50:51], 0, v[0:1]
	s_mov_b32 m0, s4
	v_lshl_add_u64 v[210:211], s[86:87], 0, v[134:135]
	global_load_lds_dwordx4 v[180:181], off
	v_lshl_add_u64 v[180:181], s[50:51], 0, v[130:131]
	s_mov_b32 m0, s5
	v_lshl_add_u64 v[212:213], s[86:87], 0, v[132:133]
	global_load_lds_dwordx4 v[180:181], off
	s_mov_b32 m0, s0
	s_nop 0
	global_load_lds_dwordx4 v[210:211], off
	s_mov_b32 m0, s6
	s_nop 0
	global_load_lds_dwordx4 v[212:213], off
	s_waitcnt vmcnt(8)
	s_waitcnt lgkmcnt(0)
	s_barrier
	s_setprio 1
	s_waitcnt lgkmcnt(0)
	v_mfma_f32_16x16x32_bf16 v[2:5], v[106:109], v[196:199], v[2:5]
	v_mfma_f32_16x16x32_bf16 v[2:5], v[110:113], v[200:203], v[2:5]
	v_mfma_f32_16x16x32_bf16 v[6:9], v[114:117], v[196:199], v[6:9]
	v_mfma_f32_16x16x32_bf16 v[6:9], v[118:121], v[200:203], v[6:9]
	v_mfma_f32_16x16x32_bf16 v[140:143], v[106:109], v[54:57], v[140:143]
	v_mfma_f32_16x16x32_bf16 v[140:143], v[110:113], v[58:61], v[140:143]
	v_mfma_f32_16x16x32_bf16 v[144:147], v[114:117], v[54:57], v[144:147]
	v_mfma_f32_16x16x32_bf16 v[144:147], v[118:121], v[58:61], v[144:147]
	v_mfma_f32_16x16x32_bf16 v[148:151], v[106:109], v[94:97], v[148:151]
	v_mfma_f32_16x16x32_bf16 v[148:151], v[110:113], v[184:187], v[148:151]
	v_mfma_f32_16x16x32_bf16 v[152:155], v[114:117], v[94:97], v[152:155]
	v_mfma_f32_16x16x32_bf16 v[152:155], v[118:121], v[184:187], v[152:155]
	v_mfma_f32_16x16x32_bf16 v[156:159], v[106:109], v[188:191], v[156:159]
	v_mfma_f32_16x16x32_bf16 v[156:159], v[110:113], v[192:195], v[156:159]
	v_mfma_f32_16x16x32_bf16 v[160:163], v[114:117], v[188:191], v[160:163]
	v_mfma_f32_16x16x32_bf16 v[160:163], v[118:121], v[192:195], v[160:163]
	s_setprio 0
	s_setprio 1
	v_mfma_f32_16x16x32_bf16 v[14:17], v[164:167], v[54:57], v[14:17]
	v_mfma_f32_16x16x32_bf16 v[204:207], v[168:171], v[58:61], v[14:17]
	v_mfma_f32_16x16x32_bf16 v[14:17], v[122:125], v[94:97], v[26:29]
	v_mfma_f32_16x16x32_bf16 v[26:29], v[126:129], v[184:187], v[14:17]
	v_mfma_f32_16x16x32_bf16 v[14:17], v[164:167], v[94:97], v[30:33]
	v_mfma_f32_16x16x32_bf16 v[184:187], v[168:171], v[184:187], v[14:17]
	v_mfma_f32_16x16x32_bf16 v[14:17], v[122:125], v[188:191], v[62:65]
	v_mfma_f32_16x16x32_bf16 v[218:221], v[126:129], v[192:195], v[14:17]
	v_mfma_f32_16x16x32_bf16 v[14:17], v[164:167], v[188:191], v[102:105]
	v_mfma_f32_16x16x32_bf16 v[10:13], v[122:125], v[54:57], v[10:13]
	v_mfma_f32_16x16x32_bf16 v[188:191], v[168:171], v[192:195], v[14:17]
	v_mfma_f32_16x16x32_bf16 v[14:17], v[122:125], v[196:199], v[18:21]
	v_mfma_f32_16x16x32_bf16 v[10:13], v[126:129], v[58:61], v[10:13]
	v_mfma_f32_16x16x32_bf16 v[192:195], v[126:129], v[200:203], v[14:17]
	v_mfma_f32_16x16x32_bf16 v[14:17], v[164:167], v[196:199], v[22:25]
	v_mfma_f32_16x16x32_bf16 v[164:167], v[168:171], v[200:203], v[14:17]
	s_setprio 0
	s_barrier
	s_nop 4
	ds_read_b128 v[14:17], v222
	ds_read_b128 v[18:21], v223
	ds_read_b128 v[168:171], v224
	ds_read_b128 v[196:199], v225
	ds_read_b128 v[200:203], v226
	ds_read_b128 v[222:225], v227
	ds_read_b128 v[226:229], v228
	ds_read_b128 v[230:233], v230
	s_add_u32 s50, s86, 0x10000
	s_addc_u32 s51, s87, 0
	s_mov_b32 m0, s8
	v_lshl_add_u64 v[54:55], s[50:51], 0, v[134:135]
	ds_read_b128 v[22:25], v138 offset:32768
	ds_read_b128 v[30:33], v138 offset:33792
	ds_read_b128 v[58:61], v138 offset:34816
	ds_read_b128 v[234:237], v138 offset:35840
	ds_read_b128 v[238:241], v138 offset:36864
	ds_read_b128 v[242:245], v138 offset:37888
	ds_read_b128 v[246:249], v138 offset:38912
	ds_read_b128 v[180:183], v138 offset:39936
	global_load_lds_dwordx4 v[54:55], off
	v_lshl_add_u64 v[54:55], s[50:51], 0, v[132:133]
	s_mov_b32 m0, s9
	s_nop 0
	global_load_lds_dwordx4 v[54:55], off
	s_waitcnt vmcnt(8)
	s_waitcnt lgkmcnt(0)
	s_barrier
; #define PG8_STAGE(bufoff, gbase, voff) do { _Pragma("unroll") for (int _i = 0; _i < 2; ++_i) \
;         __builtin_amdgcn_global_load_lds((const unsigned*)((const char*)(gbase) + (voff)[_i]), (PG8_LAS unsigned*)(lds + (bufoff) + ldsw + _i * 8192), 16, 0, 0); } while (0)
; #define PG8_LDA(dst, b, h) do { _Pragma("unroll") for (int m = 0; m < 4; ++m) _Pragma("unroll") for (int k = 0; k < 2; ++k) dst[m][k] = *(const PG8_LAS bf16x8*)(lds + PG8_SA(b, h) + aoff + m * 2048 + k * 1024); } while (0)
; #define PG8_MMA(ai, bj, At, Bt) do { __builtin_amdgcn_s_setprio(1); _Pragma("unroll") for (int m = 0; m < 4; ++m) _Pragma("unroll") for (int n = 0; n < 2; ++n) _Pragma("unroll") for (int k = 0; k < 2; ++k) \
;         acc[ai][bj][m][n] = __builtin_amdgcn_mfma_f32_16x16x32_bf16(Bt[n][k], At[m][k], acc[ai][bj][m][n], 0, 0, 0); __builtin_amdgcn_s_setprio(0); } while (0)
; #define PG8_WAIT_V(n) asm volatile("s_waitcnt vmcnt(" #n ")" ::: "memory")
; #define PG8_WAIT_L(n) asm volatile("s_waitcnt lgkmcnt(" #n ")" ::: "memory")
; #define PG8_BAR __builtin_amdgcn_s_barrier()
; #define PG8_SCHED __builtin_amdgcn_sched_barrier(0)
; template <class Epi, class Sched, bool ALIGN_EPI = false, bool SP2 = false>
; __device__ __forceinline__ void gemm_phase(PG8_LAS unsigned char* lds, const Gemm g, const Sched& S, const Epi& E, const int tid) {
;     ...
;             PG8_WAIT_V(8); PG8_WAIT_L(0); PG8_BAR; PG8_MMA(0, 0, At, B0); PG8_MMA(0, 1, At, B1); PG8_BAR; PG8_SCHED;
;             PG8_LDA(At, 1, 1); PG8_STAGE(PG8_SB(1, 0), b3, voffB); PG8_STAGE(PG8_SB(1, 1), b3 + hstep, voffB); PG8_STAGE(PG8_SA(1, 0), a3, voffA);
;             PG8_WAIT_V(8); PG8_WAIT_L(0); PG8_BAR; PG8_MMA(1, 0, At, B0); PG8_MMA(1, 1, At, B1); PG8_BAR; PG8_SCHED;
;     ...
;         if constexpr (ALIGN_EPI) { if (wr == 0) PG8_BAR; }
;         if constexpr (!Epi::AFTER_DRAIN) { E(acc, cur, wr, wc, fr, fq); S.done(cur); }
;         if (!has_next) break;
	s_setprio 1
	s_waitcnt lgkmcnt(0)
	v_mfma_f32_16x16x32_bf16 v[54:57], v[14:17], v[22:25], v[66:69]
	v_mfma_f32_16x16x32_bf16 v[122:125], v[18:21], v[30:33], v[54:57]
	v_mfma_f32_16x16x32_bf16 v[54:57], v[168:171], v[22:25], v[70:73]
	v_mfma_f32_16x16x32_bf16 v[114:117], v[196:199], v[30:33], v[54:57]
	v_mfma_f32_16x16x32_bf16 v[54:57], v[14:17], v[58:61], v[74:77]
	v_mfma_f32_16x16x32_bf16 v[110:113], v[18:21], v[234:237], v[54:57]
	v_mfma_f32_16x16x32_bf16 v[54:57], v[168:171], v[58:61], v[78:81]
	v_mfma_f32_16x16x32_bf16 v[102:105], v[196:199], v[234:237], v[54:57]
	v_mfma_f32_16x16x32_bf16 v[54:57], v[14:17], v[238:241], v[82:85]
	v_mfma_f32_16x16x32_bf16 v[94:97], v[18:21], v[242:245], v[54:57]
	v_mfma_f32_16x16x32_bf16 v[54:57], v[168:171], v[238:241], v[86:89]
	v_mfma_f32_16x16x32_bf16 v[86:89], v[196:199], v[242:245], v[54:57]
	v_mfma_f32_16x16x32_bf16 v[54:57], v[14:17], v[246:249], v[90:93]
	v_mfma_f32_16x16x32_bf16 v[62:65], v[18:21], v[180:183], v[54:57]
	v_mfma_f32_16x16x32_bf16 v[54:57], v[168:171], v[246:249], v[214:217]
	v_mfma_f32_16x16x32_bf16 v[54:57], v[196:199], v[180:183], v[54:57]
	s_setprio 0
	s_setprio 1
	v_mfma_f32_16x16x32_bf16 v[66:69], v[200:203], v[22:25], v[98:101]
	v_mfma_f32_16x16x32_bf16 v[22:25], v[226:229], v[22:25], v[34:37]
	v_mfma_f32_16x16x32_bf16 v[118:121], v[230:233], v[30:33], v[22:25]
	v_mfma_f32_16x16x32_bf16 v[22:25], v[200:203], v[58:61], v[38:41]
	v_mfma_f32_16x16x32_bf16 v[106:109], v[222:225], v[234:237], v[22:25]
	v_mfma_f32_16x16x32_bf16 v[22:25], v[226:229], v[58:61], v[42:45]
	v_mfma_f32_16x16x32_bf16 v[98:101], v[230:233], v[234:237], v[22:25]
	v_mfma_f32_16x16x32_bf16 v[22:25], v[200:203], v[238:241], v[46:49]
	v_mfma_f32_16x16x32_bf16 v[90:93], v[222:225], v[242:245], v[22:25]
	v_mfma_f32_16x16x32_bf16 v[22:25], v[226:229], v[238:241], v[50:53]
	v_mfma_f32_16x16x32_bf16 v[82:85], v[230:233], v[242:245], v[22:25]
	v_mfma_f32_16x16x32_bf16 v[22:25], v[200:203], v[246:249], v[172:175]
	v_mfma_f32_16x16x32_bf16 v[58:61], v[222:225], v[180:183], v[22:25]
	v_mfma_f32_16x16x32_bf16 v[22:25], v[226:229], v[246:249], v[176:179]
	v_mfma_f32_16x16x32_bf16 v[126:129], v[222:225], v[30:33], v[66:69]
	v_mfma_f32_16x16x32_bf16 v[50:53], v[230:233], v[180:183], v[22:25]
	s_setprio 0
	s_barrier
	s_mov_b32 m0, s17
	s_nop 2
	v_lshl_add_u64 v[22:23], v[136:137], 0, s[12:13]
	s_add_u32 s50, s84, 0x10080
	ds_read_b128 v[34:37], v138 offset:49152
	ds_read_b128 v[42:45], v138 offset:50176
	ds_read_b128 v[172:175], v138 offset:51200
	ds_read_b128 v[176:179], v138 offset:52224
	ds_read_b128 v[180:183], v138 offset:53248
	ds_read_b128 v[214:217], v138 offset:54272
	ds_read_b128 v[234:237], v138 offset:55296
	ds_read_b128 v[238:241], v138 offset:56320
	global_load_lds_dwordx4 v[22:23], off
	v_lshl_add_u64 v[22:23], v[208:209], 0, s[12:13]
	s_mov_b32 m0, s20
	s_addc_u32 s51, s85, 0
	global_load_lds_dwordx4 v[22:23], off
	v_lshl_add_u64 v[22:23], s[50:51], 0, v[0:1]
	s_mov_b32 m0, s26
	s_nop 0
	global_load_lds_dwordx4 v[22:23], off
	v_lshl_add_u64 v[22:23], s[50:51], 0, v[130:131]
	s_mov_b32 m0, s27
	s_nop 0
	global_load_lds_dwordx4 v[22:23], off
	v_lshl_add_u64 v[22:23], v[210:211], 0, s[12:13]
	s_mov_b32 m0, s21
	s_nop 0
	global_load_lds_dwordx4 v[22:23], off
	v_lshl_add_u64 v[22:23], v[212:213], 0, s[12:13]
	s_mov_b32 m0, s24
	s_nop 0
	global_load_lds_dwordx4 v[22:23], off
	s_waitcnt vmcnt(8)
	s_waitcnt lgkmcnt(0)
	s_barrier
	s_setprio 1
	s_waitcnt lgkmcnt(0)
	v_mfma_f32_16x16x32_bf16 v[22:25], v[14:17], v[34:37], v[140:143]
	v_mfma_f32_16x16x32_bf16 v[78:81], v[18:21], v[42:45], v[22:25]
	v_mfma_f32_16x16x32_bf16 v[22:25], v[168:171], v[34:37], v[144:147]
	v_mfma_f32_16x16x32_bf16 v[70:73], v[196:199], v[42:45], v[22:25]
	v_mfma_f32_16x16x32_bf16 v[22:25], v[14:17], v[172:175], v[148:151]
	v_mfma_f32_16x16x32_bf16 v[46:49], v[18:21], v[176:179], v[22:25]
	v_mfma_f32_16x16x32_bf16 v[22:25], v[168:171], v[172:175], v[152:155]
	v_mfma_f32_16x16x32_bf16 v[38:41], v[196:199], v[176:179], v[22:25]
	v_mfma_f32_16x16x32_bf16 v[22:25], v[14:17], v[180:183], v[156:159]
	v_mfma_f32_16x16x32_bf16 v[2:5], v[14:17], v[234:237], v[2:5]
	v_mfma_f32_16x16x32_bf16 v[30:33], v[18:21], v[214:217], v[22:25]
	v_mfma_f32_16x16x32_bf16 v[22:25], v[168:171], v[180:183], v[160:163]
	v_mfma_f32_16x16x32_bf16 v[14:17], v[18:21], v[238:241], v[2:5]
	v_mfma_f32_16x16x32_bf16 v[2:5], v[168:171], v[234:237], v[6:9]
	v_mfma_f32_16x16x32_bf16 v[22:25], v[196:199], v[214:217], v[22:25]
	v_mfma_f32_16x16x32_bf16 v[6:9], v[196:199], v[238:241], v[2:5]
	s_setprio 0
	s_setprio 1
	v_mfma_f32_16x16x32_bf16 v[2:5], v[200:203], v[34:37], v[10:13]
	v_mfma_f32_16x16x32_bf16 v[74:77], v[222:225], v[42:45], v[2:5]
	v_mfma_f32_16x16x32_bf16 v[2:5], v[226:229], v[34:37], v[204:207]
	v_mfma_f32_16x16x32_bf16 v[66:69], v[230:233], v[42:45], v[2:5]
	v_mfma_f32_16x16x32_bf16 v[2:5], v[200:203], v[172:175], v[26:29]
	v_mfma_f32_16x16x32_bf16 v[42:45], v[222:225], v[176:179], v[2:5]
	v_mfma_f32_16x16x32_bf16 v[2:5], v[226:229], v[172:175], v[184:187]
	v_mfma_f32_16x16x32_bf16 v[34:37], v[230:233], v[176:179], v[2:5]
	v_mfma_f32_16x16x32_bf16 v[2:5], v[200:203], v[180:183], v[218:221]
	v_mfma_f32_16x16x32_bf16 v[26:29], v[222:225], v[214:217], v[2:5]
	v_mfma_f32_16x16x32_bf16 v[2:5], v[226:229], v[180:183], v[188:191]
	v_mfma_f32_16x16x32_bf16 v[18:21], v[230:233], v[214:217], v[2:5]
	v_mfma_f32_16x16x32_bf16 v[2:5], v[200:203], v[234:237], v[192:195]
	v_mfma_f32_16x16x32_bf16 v[10:13], v[222:225], v[238:241], v[2:5]
	v_mfma_f32_16x16x32_bf16 v[2:5], v[226:229], v[234:237], v[164:167]
	v_mfma_f32_16x16x32_bf16 v[2:5], v[230:233], v[238:241], v[2:5]
	s_setprio 0
	s_barrier
	s_andn2_b64 vcc, exec, s[30:31]
	s_cbranch_vccnz .LBB0_372
	s_barrier

; #define PG8_STAGE(bufoff, gbase, voff) do { _Pragma("unroll") for (int _i = 0; _i < 2; ++_i) \
;         __builtin_amdgcn_global_load_lds((const unsigned*)((const char*)(gbase) + (voff)[_i]), (PG8_LAS unsigned*)(lds + (bufoff) + ldsw + _i * 8192), 16, 0, 0); } while (0)
; #define PG8_LDA(dst, b, h) do { _Pragma("unroll") for (int m = 0; m < 4; ++m) _Pragma("unroll") for (int k = 0; k < 2; ++k) dst[m][k] = *(const PG8_LAS bf16x8*)(lds + PG8_SA(b, h) + aoff + m * 2048 + k * 1024); } while (0)
; #define PG8_LDB(dst, b, h) do { _Pragma("unroll") for (int n = 0; n < 2; ++n) _Pragma("unroll") for (int k = 0; k < 2; ++k) dst[n][k] = *(const PG8_LAS bf16x8*)(lds + PG8_SB(b, h) + boff + n * 2048 + k * 1024); } while (0)
; #define PG8_MMA(ai, bj, At, Bt) do { __builtin_amdgcn_s_setprio(1); _Pragma("unroll") for (int m = 0; m < 4; ++m) _Pragma("unroll") for (int n = 0; n < 2; ++n) _Pragma("unroll") for (int k = 0; k < 2; ++k) \
;         acc[ai][bj][m][n] = __builtin_amdgcn_mfma_f32_16x16x32_bf16(Bt[n][k], At[m][k], acc[ai][bj][m][n], 0, 0, 0); __builtin_amdgcn_s_setprio(0); } while (0)
; #define PG8_WAIT_V(n) asm volatile("s_waitcnt vmcnt(" #n ")" ::: "memory")
; #define PG8_WAIT_L(n) asm volatile("s_waitcnt lgkmcnt(" #n ")" ::: "memory")
; #define PG8_BAR __builtin_amdgcn_s_barrier()
; #define PG8_SCHED __builtin_amdgcn_sched_barrier(0)
; template <class Epi, class Sched, bool ALIGN_EPI = false, bool SP2 = false>
; __device__ __forceinline__ void gemm_phase(PG8_LAS unsigned char* lds, const Gemm g, const Sched& S, const Epi& E, const int tid) {
;     ...
;             PG8_LDB(B0, 0, 0); PG8_LDB(B1, 0, 1); PG8_SCHED; PG8_LDA(At, 0, 0); PG8_STAGE(PG8_SA(1, 1), a1 + hstep, voffA);
;             PG8_WAIT_V(8); PG8_WAIT_L(0); PG8_BAR; PG8_MMA(0, 0, At, B0); PG8_MMA(0, 1, At, B1); PG8_BAR; PG8_SCHED;
;             PG8_LDA(At, 0, 1); PG8_STAGE(PG8_SB(0, 0), b2, voffB); PG8_STAGE(PG8_SB(0, 1), b2 + hstep, voffB); PG8_STAGE(PG8_SA(0, 0), a2, voffA);
;             PG8_WAIT_V(8); PG8_WAIT_L(0); PG8_BAR; PG8_MMA(1, 0, At, B0); PG8_MMA(1, 1, At, B1); PG8_BAR; PG8_SCHED;
.LBB0_388:
	v_or_b32_e32 v0, 0x10000, v179
	v_add_u32_e32 v11, 0x10800, v179
	v_or_b32_e32 v13, 0x14000, v179
	v_add_u32_e32 v15, 0x14800, v179
	v_add_u32_e32 v10, 0x10400, v179
	ds_read_b128 v[18:21], v0
	ds_read_b128 v[22:25], v10
	v_add_u32_e32 v12, 0x10c00, v179
	ds_read_b128 v[26:29], v11
	ds_read_b128 v[30:33], v12
	v_add_u32_e32 v14, 0x14400, v179
	ds_read_b128 v[34:37], v13
	ds_read_b128 v[38:41], v14
	v_add_u32_e32 v16, 0x14c00, v179
	ds_read_b128 v[42:45], v15
	ds_read_b128 v[46:49], v16
	s_add_u32 s20, s30, 0x18080
	s_addc_u32 s21, s31, 0
	s_add_i32 s5, s1, 0xc000
	v_lshl_add_u64 v[74:75], s[20:21], 0, v[168:169]
	s_mov_b32 m0, s5
	s_add_i32 s4, s1, 0xe000
	ds_read_b128 v[2:5], v178
	ds_read_b128 v[6:9], v178 offset:1024
	ds_read_b128 v[50:53], v178 offset:2048
	ds_read_b128 v[54:57], v178 offset:3072
	ds_read_b128 v[58:61], v178 offset:4096
	ds_read_b128 v[62:65], v178 offset:5120
	ds_read_b128 v[66:69], v178 offset:6144
	ds_read_b128 v[70:73], v178 offset:7168
	global_load_lds_dwordx4 v[74:75], off
	v_lshl_add_u64 v[74:75], s[20:21], 0, v[164:165]
	s_mov_b32 m0, s4
	s_nop 0
	global_load_lds_dwordx4 v[74:75], off
	s_waitcnt vmcnt(8)
	s_waitcnt lgkmcnt(0)
	s_barrier
	s_setprio 1
	s_waitcnt lgkmcnt(0)
	v_mfma_f32_16x16x32_bf16 v[74:77], v[18:21], v[2:5], 0
	v_mfma_f32_16x16x32_bf16 v[78:81], v[26:29], v[2:5], 0
	v_mfma_f32_16x16x32_bf16 v[82:85], v[18:21], v[50:53], 0
	v_mfma_f32_16x16x32_bf16 v[86:89], v[26:29], v[50:53], 0
	v_mfma_f32_16x16x32_bf16 v[90:93], v[18:21], v[58:61], 0
	v_mfma_f32_16x16x32_bf16 v[94:97], v[26:29], v[58:61], 0
	v_mfma_f32_16x16x32_bf16 v[98:101], v[18:21], v[66:69], 0
	v_mfma_f32_16x16x32_bf16 v[102:105], v[26:29], v[66:69], 0
	v_mfma_f32_16x16x32_bf16 v[74:77], v[22:25], v[6:9], v[74:77]
	v_mfma_f32_16x16x32_bf16 v[78:81], v[30:33], v[6:9], v[78:81]
	v_mfma_f32_16x16x32_bf16 v[82:85], v[22:25], v[54:57], v[82:85]
	v_mfma_f32_16x16x32_bf16 v[86:89], v[30:33], v[54:57], v[86:89]
	v_mfma_f32_16x16x32_bf16 v[90:93], v[22:25], v[62:65], v[90:93]
	v_mfma_f32_16x16x32_bf16 v[94:97], v[30:33], v[62:65], v[94:97]
	v_mfma_f32_16x16x32_bf16 v[98:101], v[22:25], v[70:73], v[98:101]
	v_mfma_f32_16x16x32_bf16 v[102:105], v[30:33], v[70:73], v[102:105]
	s_setprio 0
	s_setprio 1
	v_mfma_f32_16x16x32_bf16 v[106:109], v[34:37], v[2:5], 0
	v_mfma_f32_16x16x32_bf16 v[2:5], v[42:45], v[2:5], 0
	v_mfma_f32_16x16x32_bf16 v[110:113], v[46:49], v[6:9], v[2:5]
	v_mfma_f32_16x16x32_bf16 v[2:5], v[34:37], v[50:53], 0
	v_mfma_f32_16x16x32_bf16 v[114:117], v[38:41], v[54:57], v[2:5]
	v_mfma_f32_16x16x32_bf16 v[2:5], v[42:45], v[50:53], 0
	v_mfma_f32_16x16x32_bf16 v[50:53], v[46:49], v[54:57], v[2:5]
	v_mfma_f32_16x16x32_bf16 v[2:5], v[34:37], v[58:61], 0
	v_mfma_f32_16x16x32_bf16 v[54:57], v[38:41], v[62:65], v[2:5]
	v_mfma_f32_16x16x32_bf16 v[2:5], v[42:45], v[58:61], 0
	v_mfma_f32_16x16x32_bf16 v[58:61], v[46:49], v[62:65], v[2:5]
	v_mfma_f32_16x16x32_bf16 v[2:5], v[34:37], v[66:69], 0
	v_mfma_f32_16x16x32_bf16 v[62:65], v[38:41], v[70:73], v[2:5]
	v_mfma_f32_16x16x32_bf16 v[2:5], v[42:45], v[66:69], 0
	v_mfma_f32_16x16x32_bf16 v[106:109], v[38:41], v[6:9], v[106:109]
	v_mfma_f32_16x16x32_bf16 v[66:69], v[46:49], v[70:73], v[2:5]
	s_setprio 0
	s_barrier
	s_nop 3
	v_lshl_add_u64 v[2:3], s[46:47], 0, v[166:167]
	s_mov_b64 s[26:27], 0x100
	s_mov_b32 m0, s8
	v_lshl_add_u64 v[4:5], v[2:3], 0, s[26:27]
	ds_read_b128 v[70:73], v178 offset:16384
	ds_read_b128 v[118:121], v178 offset:17408
	ds_read_b128 v[122:125], v178 offset:18432
	ds_read_b128 v[126:129], v178 offset:19456
	ds_read_b128 v[130:133], v178 offset:20480
	ds_read_b128 v[134:137], v178 offset:21504
	ds_read_b128 v[138:141], v178 offset:22528
	ds_read_b128 v[142:145], v178 offset:23552
	global_load_lds_dwordx4 v[4:5], off
	v_lshl_add_u64 v[4:5], s[46:47], 0, v[162:163]
	s_add_u32 s20, s46, 0x18100
	v_lshl_add_u64 v[6:7], v[4:5], 0, s[26:27]
	s_mov_b32 m0, s9
	s_addc_u32 s21, s47, 0
	global_load_lds_dwordx4 v[6:7], off
	v_lshl_add_u64 v[6:7], s[20:21], 0, v[166:167]
	s_mov_b32 m0, s14
	s_nop 0
	global_load_lds_dwordx4 v[6:7], off
	v_lshl_add_u64 v[6:7], s[20:21], 0, v[162:163]
	s_mov_b32 m0, s34
	s_nop 0
	global_load_lds_dwordx4 v[6:7], off
	v_lshl_add_u64 v[6:7], s[30:31], 0, v[168:169]
	v_lshl_add_u64 v[8:9], v[6:7], 0, s[26:27]
	s_mov_b32 m0, s1
	s_nop 0
	global_load_lds_dwordx4 v[8:9], off
	v_lshl_add_u64 v[8:9], s[30:31], 0, v[164:165]
	v_lshl_add_u64 v[146:147], v[8:9], 0, s[26:27]
	s_mov_b32 m0, s35
	s_nop 0
	global_load_lds_dwordx4 v[146:147], off
	s_waitcnt vmcnt(8)
	s_waitcnt lgkmcnt(0)
	s_barrier
	s_setprio 1
	s_waitcnt lgkmcnt(0)
	v_mfma_f32_16x16x32_bf16 v[146:149], v[18:21], v[70:73], 0
	v_mfma_f32_16x16x32_bf16 v[154:157], v[18:21], v[122:125], 0
	v_mfma_f32_16x16x32_bf16 v[170:173], v[18:21], v[130:133], 0
	v_mfma_f32_16x16x32_bf16 v[18:21], v[18:21], v[138:141], 0
	v_mfma_f32_16x16x32_bf16 v[180:183], v[22:25], v[142:145], v[18:21]
	v_mfma_f32_16x16x32_bf16 v[18:21], v[26:29], v[138:141], 0
	v_mfma_f32_16x16x32_bf16 v[150:153], v[26:29], v[70:73], 0
	v_mfma_f32_16x16x32_bf16 v[158:161], v[26:29], v[122:125], 0
	v_mfma_f32_16x16x32_bf16 v[174:177], v[26:29], v[130:133], 0
	v_mfma_f32_16x16x32_bf16 v[26:29], v[30:33], v[142:145], v[18:21]
	v_mfma_f32_16x16x32_bf16 v[146:149], v[22:25], v[118:121], v[146:149]
	v_mfma_f32_16x16x32_bf16 v[150:153], v[30:33], v[118:121], v[150:153]
	v_mfma_f32_16x16x32_bf16 v[154:157], v[22:25], v[126:129], v[154:157]
	v_mfma_f32_16x16x32_bf16 v[158:161], v[30:33], v[126:129], v[158:161]
	v_mfma_f32_16x16x32_bf16 v[170:173], v[22:25], v[134:137], v[170:173]
	v_mfma_f32_16x16x32_bf16 v[174:177], v[30:33], v[134:137], v[174:177]
	s_setprio 0
	s_setprio 1
	v_mfma_f32_16x16x32_bf16 v[18:21], v[34:37], v[70:73], 0
	v_mfma_f32_16x16x32_bf16 v[30:33], v[38:41], v[118:121], v[18:21]
	v_mfma_f32_16x16x32_bf16 v[18:21], v[42:45], v[70:73], 0
	v_mfma_f32_16x16x32_bf16 v[70:73], v[46:49], v[118:121], v[18:21]
	v_mfma_f32_16x16x32_bf16 v[18:21], v[34:37], v[122:125], 0
	v_mfma_f32_16x16x32_bf16 v[118:121], v[38:41], v[126:129], v[18:21]
	v_mfma_f32_16x16x32_bf16 v[18:21], v[42:45], v[122:125], 0
	v_mfma_f32_16x16x32_bf16 v[122:125], v[46:49], v[126:129], v[18:21]
	v_mfma_f32_16x16x32_bf16 v[18:21], v[34:37], v[130:133], 0
	v_mfma_f32_16x16x32_bf16 v[126:129], v[38:41], v[134:137], v[18:21]
	v_mfma_f32_16x16x32_bf16 v[18:21], v[42:45], v[130:133], 0
	v_mfma_f32_16x16x32_bf16 v[130:133], v[46:49], v[134:137], v[18:21]
	v_mfma_f32_16x16x32_bf16 v[18:21], v[34:37], v[138:141], 0
	v_mfma_f32_16x16x32_bf16 v[34:37], v[38:41], v[142:145], v[18:21]
	v_mfma_f32_16x16x32_bf16 v[18:21], v[42:45], v[138:141], 0
	v_mfma_f32_16x16x32_bf16 v[38:41], v[46:49], v[142:145], v[18:21]
	s_setprio 0
	s_barrier
; #define PG8_STAGE(bufoff, gbase, voff) do { _Pragma("unroll") for (int _i = 0; _i < 2; ++_i) \
;         __builtin_amdgcn_global_load_lds((const unsigned*)((const char*)(gbase) + (voff)[_i]), (PG8_LAS unsigned*)(lds + (bufoff) + ldsw + _i * 8192), 16, 0, 0); } while (0)
; #define PG8_LDA(dst, b, h) do { _Pragma("unroll") for (int m = 0; m < 4; ++m) _Pragma("unroll") for (int k = 0; k < 2; ++k) dst[m][k] = *(const PG8_LAS bf16x8*)(lds + PG8_SA(b, h) + aoff + m * 2048 + k * 1024); } while (0)
; #define PG8_LDB(dst, b, h) do { _Pragma("unroll") for (int n = 0; n < 2; ++n) _Pragma("unroll") for (int k = 0; k < 2; ++k) dst[n][k] = *(const PG8_LAS bf16x8*)(lds + PG8_SB(b, h) + boff + n * 2048 + k * 1024); } while (0)
; #define PG8_MMA(ai, bj, At, Bt) do { __builtin_amdgcn_s_setprio(1); _Pragma("unroll") for (int m = 0; m < 4; ++m) _Pragma("unroll") for (int n = 0; n < 2; ++n) _Pragma("unroll") for (int k = 0; k < 2; ++k) \
;         acc[ai][bj][m][n] = __builtin_amdgcn_mfma_f32_16x16x32_bf16(Bt[n][k], At[m][k], acc[ai][bj][m][n], 0, 0, 0); __builtin_amdgcn_s_setprio(0); } while (0)
; #define PG8_WAIT_V(n) asm volatile("s_waitcnt vmcnt(" #n ")" ::: "memory")
; #define PG8_WAIT_L(n) asm volatile("s_waitcnt lgkmcnt(" #n ")" ::: "memory")
; #define PG8_BAR __builtin_amdgcn_s_barrier()
; #define PG8_SCHED __builtin_amdgcn_sched_barrier(0)
; template <class Epi, class Sched, bool ALIGN_EPI = false, bool SP2 = false>
; __device__ __forceinline__ void gemm_phase(PG8_LAS unsigned char* lds, const Gemm g, const Sched& S, const Epi& E, const int tid) {
;     ...
;             PG8_LDB(B0, 1, 0); PG8_LDB(B1, 1, 1); PG8_SCHED; PG8_LDA(At, 1, 0); PG8_STAGE(PG8_SA(0, 1), a2 + hstep, voffA);
;             PG8_WAIT_V(8); PG8_WAIT_L(0); PG8_BAR; PG8_MMA(0, 0, At, B0); PG8_MMA(0, 1, At, B1); PG8_BAR; PG8_SCHED;
;             PG8_LDA(At, 1, 1); PG8_STAGE(PG8_SB(1, 0), b3, voffB); PG8_STAGE(PG8_SB(1, 1), b3 + hstep, voffB); PG8_STAGE(PG8_SA(1, 0), a3, voffA);
	v_or_b32_e32 v17, 0x18000, v179
	s_nop 3
	v_add_u32_e32 v19, 0x18800, v179
	v_or_b32_e32 v21, 0x1c000, v179
	v_add_u32_e32 v23, 0x1c800, v179
	v_add_u32_e32 v18, 0x18400, v179
	ds_read_b128 v[42:45], v17
	ds_read_b128 v[46:49], v18
	v_add_u32_e32 v20, 0x18c00, v179
	ds_read_b128 v[134:137], v19
	ds_read_b128 v[138:141], v20
	v_add_u32_e32 v22, 0x1c400, v179
	ds_read_b128 v[142:145], v21
	ds_read_b128 v[184:187], v22
	v_add_u32_e32 v24, 0x1cc00, v179
	ds_read_b128 v[188:191], v23
	ds_read_b128 v[192:195], v24
	s_add_u32 s20, s30, 0x18100
	s_addc_u32 s21, s31, 0
	s_mov_b32 m0, s84
	v_lshl_add_u64 v[208:209], s[20:21], 0, v[168:169]
	ds_read_b128 v[196:199], v178 offset:32768
	ds_read_b128 v[200:203], v178 offset:33792
	ds_read_b128 v[204:207], v178 offset:34816
	ds_read_b128 v[214:217], v178 offset:35840
	ds_read_b128 v[218:221], v178 offset:36864
	ds_read_b128 v[222:225], v178 offset:37888
	ds_read_b128 v[226:229], v178 offset:38912
	ds_read_b128 v[230:233], v178 offset:39936
	global_load_lds_dwordx4 v[208:209], off
	v_lshl_add_u64 v[208:209], s[20:21], 0, v[164:165]
	s_mov_b32 m0, s85
	s_nop 0
	global_load_lds_dwordx4 v[208:209], off
	s_waitcnt vmcnt(8)
	s_waitcnt lgkmcnt(0)
	s_barrier
	s_setprio 1
	s_waitcnt lgkmcnt(0)
	v_mfma_f32_16x16x32_bf16 v[74:77], v[42:45], v[196:199], v[74:77]
	v_mfma_f32_16x16x32_bf16 v[74:77], v[46:49], v[200:203], v[74:77]
	v_mfma_f32_16x16x32_bf16 v[78:81], v[134:137], v[196:199], v[78:81]
	v_mfma_f32_16x16x32_bf16 v[78:81], v[138:141], v[200:203], v[78:81]
	v_mfma_f32_16x16x32_bf16 v[82:85], v[42:45], v[204:207], v[82:85]
	v_mfma_f32_16x16x32_bf16 v[82:85], v[46:49], v[214:217], v[82:85]
	v_mfma_f32_16x16x32_bf16 v[86:89], v[134:137], v[204:207], v[86:89]
	v_mfma_f32_16x16x32_bf16 v[86:89], v[138:141], v[214:217], v[86:89]
	v_mfma_f32_16x16x32_bf16 v[90:93], v[42:45], v[218:221], v[90:93]
	v_mfma_f32_16x16x32_bf16 v[90:93], v[46:49], v[222:225], v[90:93]
	v_mfma_f32_16x16x32_bf16 v[94:97], v[134:137], v[218:221], v[94:97]
	v_mfma_f32_16x16x32_bf16 v[94:97], v[138:141], v[222:225], v[94:97]
	v_mfma_f32_16x16x32_bf16 v[98:101], v[42:45], v[226:229], v[98:101]
	v_mfma_f32_16x16x32_bf16 v[98:101], v[46:49], v[230:233], v[98:101]
	v_mfma_f32_16x16x32_bf16 v[102:105], v[134:137], v[226:229], v[102:105]
	v_mfma_f32_16x16x32_bf16 v[102:105], v[138:141], v[230:233], v[102:105]
	s_setprio 0
	s_setprio 1
	v_mfma_f32_16x16x32_bf16 v[106:109], v[142:145], v[196:199], v[106:109]
	v_mfma_f32_16x16x32_bf16 v[106:109], v[184:187], v[200:203], v[106:109]
	v_mfma_f32_16x16x32_bf16 v[110:113], v[188:191], v[196:199], v[110:113]
	v_mfma_f32_16x16x32_bf16 v[110:113], v[192:195], v[200:203], v[110:113]
	v_mfma_f32_16x16x32_bf16 v[114:117], v[142:145], v[204:207], v[114:117]
	v_mfma_f32_16x16x32_bf16 v[114:117], v[184:187], v[214:217], v[114:117]
	v_mfma_f32_16x16x32_bf16 v[50:53], v[188:191], v[204:207], v[50:53]
	v_mfma_f32_16x16x32_bf16 v[50:53], v[192:195], v[214:217], v[50:53]
	v_mfma_f32_16x16x32_bf16 v[54:57], v[142:145], v[218:221], v[54:57]
	v_mfma_f32_16x16x32_bf16 v[54:57], v[184:187], v[222:225], v[54:57]
	v_mfma_f32_16x16x32_bf16 v[58:61], v[188:191], v[218:221], v[58:61]
	v_mfma_f32_16x16x32_bf16 v[58:61], v[192:195], v[222:225], v[58:61]
	v_mfma_f32_16x16x32_bf16 v[62:65], v[142:145], v[226:229], v[62:65]
	v_mfma_f32_16x16x32_bf16 v[62:65], v[184:187], v[230:233], v[62:65]
	v_mfma_f32_16x16x32_bf16 v[66:69], v[188:191], v[226:229], v[66:69]
	v_mfma_f32_16x16x32_bf16 v[66:69], v[192:195], v[230:233], v[66:69]
	s_setprio 0
	s_barrier
	s_mov_b64 s[26:27], 0x180
	s_mov_b32 m0, s88
	v_lshl_add_u64 v[208:209], v[2:3], 0, s[26:27]
	s_add_u32 s20, s46, 0x18180
	ds_read_b128 v[196:199], v178 offset:49152
	ds_read_b128 v[200:203], v178 offset:50176
	ds_read_b128 v[204:207], v178 offset:51200
	ds_read_b128 v[214:217], v178 offset:52224
	ds_read_b128 v[218:221], v178 offset:53248
	ds_read_b128 v[222:225], v178 offset:54272
	ds_read_b128 v[226:229], v178 offset:55296
	ds_read_b128 v[230:233], v178 offset:56320
	global_load_lds_dwordx4 v[208:209], off
	v_lshl_add_u64 v[208:209], v[4:5], 0, s[26:27]
	s_mov_b32 m0, s89
	s_addc_u32 s21, s47, 0
	global_load_lds_dwordx4 v[208:209], off
	v_lshl_add_u64 v[208:209], s[20:21], 0, v[166:167]
	s_mov_b32 m0, s28
	s_nop 0
	global_load_lds_dwordx4 v[208:209], off
	v_lshl_add_u64 v[208:209], s[20:21], 0, v[162:163]
	s_mov_b32 m0, s29
	s_nop 0
	global_load_lds_dwordx4 v[208:209], off
	v_lshl_add_u64 v[208:209], v[6:7], 0, s[26:27]
	s_mov_b32 m0, s90
	s_nop 0
	global_load_lds_dwordx4 v[208:209], off
	v_lshl_add_u64 v[208:209], v[8:9], 0, s[26:27]
	s_mov_b32 m0, s91
	s_nop 0
	global_load_lds_dwordx4 v[208:209], off
	s_waitcnt vmcnt(8)
	s_waitcnt lgkmcnt(0)
	s_barrier
; #define PG8_STAGE(bufoff, gbase, voff) do { _Pragma("unroll") for (int _i = 0; _i < 2; ++_i) \
;         __builtin_amdgcn_global_load_lds((const unsigned*)((const char*)(gbase) + (voff)[_i]), (PG8_LAS unsigned*)(lds + (bufoff) + ldsw + _i * 8192), 16, 0, 0); } while (0)
; #define PG8_LDA(dst, b, h) do { _Pragma("unroll") for (int m = 0; m < 4; ++m) _Pragma("unroll") for (int k = 0; k < 2; ++k) dst[m][k] = *(const PG8_LAS bf16x8*)(lds + PG8_SA(b, h) + aoff + m * 2048 + k * 1024); } while (0)
; #define PG8_LDB(dst, b, h) do { _Pragma("unroll") for (int n = 0; n < 2; ++n) _Pragma("unroll") for (int k = 0; k < 2; ++k) dst[n][k] = *(const PG8_LAS bf16x8*)(lds + PG8_SB(b, h) + boff + n * 2048 + k * 1024); } while (0)
; #define PG8_MMA(ai, bj, At, Bt) do { __builtin_amdgcn_s_setprio(1); _Pragma("unroll") for (int m = 0; m < 4; ++m) _Pragma("unroll") for (int n = 0; n < 2; ++n) _Pragma("unroll") for (int k = 0; k < 2; ++k) \
;         acc[ai][bj][m][n] = __builtin_amdgcn_mfma_f32_16x16x32_bf16(Bt[n][k], At[m][k], acc[ai][bj][m][n], 0, 0, 0); __builtin_amdgcn_s_setprio(0); } while (0)
; #define PG8_BAR __builtin_amdgcn_s_barrier()
; template <class Epi, class Sched, bool ALIGN_EPI = false, bool SP2 = false>
; __device__ __forceinline__ void gemm_phase(PG8_LAS unsigned char* lds, const Gemm g, const Sched& S, const Epi& E, const int tid) {
;     ...
;             PG8_LDB(B0, 0, 0); PG8_LDB(B1, 0, 1); PG8_SCHED; PG8_LDA(At, 0, 0); PG8_STAGE(PG8_SA(1, 1), a1 + hstep, voffA);
;             PG8_WAIT_V(8); PG8_WAIT_L(0); PG8_BAR; PG8_MMA(0, 0, At, B0); PG8_MMA(0, 1, At, B1); PG8_BAR; PG8_SCHED;
;             PG8_LDA(At, 0, 1); PG8_STAGE(PG8_SB(0, 0), b2, voffB); PG8_STAGE(PG8_SB(0, 1), b2 + hstep, voffB); PG8_STAGE(PG8_SA(0, 0), a2, voffA);
;             PG8_WAIT_V(8); PG8_WAIT_L(0); PG8_BAR; PG8_MMA(1, 0, At, B0); PG8_MMA(1, 1, At, B1); PG8_BAR; PG8_SCHED;
;             PG8_LDB(B0, 1, 0); PG8_LDB(B1, 1, 1); PG8_SCHED; PG8_LDA(At, 1, 0); PG8_STAGE(PG8_SA(0, 1), a2 + hstep, voffA);
;             PG8_WAIT_V(8); PG8_WAIT_L(0); PG8_BAR; PG8_MMA(0, 0, At, B0); PG8_MMA(0, 1, At, B1); PG8_BAR; PG8_SCHED;
;             PG8_LDA(At, 1, 1); PG8_STAGE(PG8_SB(1, 0), b3, voffB); PG8_STAGE(PG8_SB(1, 1), b3 + hstep, voffB); PG8_STAGE(PG8_SA(1, 0), a3, voffA);
;             PG8_WAIT_V(8); PG8_WAIT_L(0); PG8_BAR; PG8_MMA(1, 0, At, B0); PG8_MMA(1, 1, At, B1); PG8_BAR; PG8_SCHED;
	s_setprio 1
	s_waitcnt lgkmcnt(0)
	v_mfma_f32_16x16x32_bf16 v[146:149], v[42:45], v[196:199], v[146:149]
	v_mfma_f32_16x16x32_bf16 v[154:157], v[42:45], v[204:207], v[154:157]
	v_mfma_f32_16x16x32_bf16 v[170:173], v[42:45], v[218:221], v[170:173]
	v_mfma_f32_16x16x32_bf16 v[42:45], v[42:45], v[226:229], v[180:183]
	v_mfma_f32_16x16x32_bf16 v[26:29], v[134:137], v[226:229], v[26:29]
	v_mfma_f32_16x16x32_bf16 v[150:153], v[134:137], v[196:199], v[150:153]
	v_mfma_f32_16x16x32_bf16 v[158:161], v[134:137], v[204:207], v[158:161]
	v_mfma_f32_16x16x32_bf16 v[174:177], v[134:137], v[218:221], v[174:177]
	v_mfma_f32_16x16x32_bf16 v[42:45], v[46:49], v[230:233], v[42:45]
	v_mfma_f32_16x16x32_bf16 v[26:29], v[138:141], v[230:233], v[26:29]
	v_mfma_f32_16x16x32_bf16 v[146:149], v[46:49], v[200:203], v[146:149]
	v_mfma_f32_16x16x32_bf16 v[150:153], v[138:141], v[200:203], v[150:153]
	v_mfma_f32_16x16x32_bf16 v[154:157], v[46:49], v[214:217], v[154:157]
	v_mfma_f32_16x16x32_bf16 v[158:161], v[138:141], v[214:217], v[158:161]
	v_mfma_f32_16x16x32_bf16 v[170:173], v[46:49], v[222:225], v[170:173]
	v_mfma_f32_16x16x32_bf16 v[174:177], v[138:141], v[222:225], v[174:177]
	s_setprio 0
	s_setprio 1
	v_mfma_f32_16x16x32_bf16 v[30:33], v[142:145], v[196:199], v[30:33]
	v_mfma_f32_16x16x32_bf16 v[46:49], v[188:191], v[196:199], v[70:73]
	v_mfma_f32_16x16x32_bf16 v[70:73], v[142:145], v[204:207], v[118:121]
	v_mfma_f32_16x16x32_bf16 v[118:121], v[188:191], v[204:207], v[122:125]
	v_mfma_f32_16x16x32_bf16 v[122:125], v[142:145], v[218:221], v[126:129]
	v_mfma_f32_16x16x32_bf16 v[126:129], v[188:191], v[218:221], v[130:133]
	v_mfma_f32_16x16x32_bf16 v[34:37], v[142:145], v[226:229], v[34:37]
	v_mfma_f32_16x16x32_bf16 v[38:41], v[188:191], v[226:229], v[38:41]
	v_mfma_f32_16x16x32_bf16 v[30:33], v[184:187], v[200:203], v[30:33]
	v_mfma_f32_16x16x32_bf16 v[46:49], v[192:195], v[200:203], v[46:49]
	v_mfma_f32_16x16x32_bf16 v[70:73], v[184:187], v[214:217], v[70:73]
	v_mfma_f32_16x16x32_bf16 v[118:121], v[192:195], v[214:217], v[118:121]
	v_mfma_f32_16x16x32_bf16 v[122:125], v[184:187], v[222:225], v[122:125]
	v_mfma_f32_16x16x32_bf16 v[126:129], v[192:195], v[222:225], v[126:129]
	v_mfma_f32_16x16x32_bf16 v[34:37], v[184:187], v[230:233], v[34:37]
	v_mfma_f32_16x16x32_bf16 v[38:41], v[192:195], v[230:233], v[38:41]
	s_setprio 0
	s_barrier
	ds_read_b128 v[130:133], v0
	ds_read_b128 v[134:137], v10
	ds_read_b128 v[138:141], v11
	ds_read_b128 v[142:145], v12
	ds_read_b128 v[180:183], v13
	ds_read_b128 v[184:187], v14
	ds_read_b128 v[188:191], v15
	ds_read_b128 v[192:195], v16
	s_add_u32 s20, s30, 0x18180
	s_addc_u32 s21, s31, 0
	s_mov_b32 m0, s5
	v_lshl_add_u64 v[208:209], s[20:21], 0, v[168:169]
	ds_read_b128 v[196:199], v178
	ds_read_b128 v[200:203], v178 offset:1024
	ds_read_b128 v[204:207], v178 offset:2048
	ds_read_b128 v[214:217], v178 offset:3072
	ds_read_b128 v[218:221], v178 offset:4096
	ds_read_b128 v[222:225], v178 offset:5120
	ds_read_b128 v[226:229], v178 offset:6144
	ds_read_b128 v[230:233], v178 offset:7168
	global_load_lds_dwordx4 v[208:209], off
	v_lshl_add_u64 v[208:209], s[20:21], 0, v[164:165]
	s_mov_b32 m0, s4
	s_nop 0
	global_load_lds_dwordx4 v[208:209], off
	s_waitcnt vmcnt(8)
	s_waitcnt lgkmcnt(0)
	s_barrier
	s_setprio 1
	s_waitcnt lgkmcnt(0)
	v_mfma_f32_16x16x32_bf16 v[74:77], v[130:133], v[196:199], v[74:77]
	v_mfma_f32_16x16x32_bf16 v[74:77], v[134:137], v[200:203], v[74:77]
	v_mfma_f32_16x16x32_bf16 v[78:81], v[138:141], v[196:199], v[78:81]
	v_mfma_f32_16x16x32_bf16 v[78:81], v[142:145], v[200:203], v[78:81]
	v_mfma_f32_16x16x32_bf16 v[82:85], v[130:133], v[204:207], v[82:85]
	v_mfma_f32_16x16x32_bf16 v[82:85], v[134:137], v[214:217], v[82:85]
	v_mfma_f32_16x16x32_bf16 v[86:89], v[138:141], v[204:207], v[86:89]
	v_mfma_f32_16x16x32_bf16 v[86:89], v[142:145], v[214:217], v[86:89]
	v_mfma_f32_16x16x32_bf16 v[90:93], v[130:133], v[218:221], v[90:93]
	v_mfma_f32_16x16x32_bf16 v[90:93], v[134:137], v[222:225], v[90:93]
	v_mfma_f32_16x16x32_bf16 v[94:97], v[138:141], v[218:221], v[94:97]
	v_mfma_f32_16x16x32_bf16 v[94:97], v[142:145], v[222:225], v[94:97]
	v_mfma_f32_16x16x32_bf16 v[98:101], v[130:133], v[226:229], v[98:101]
	v_mfma_f32_16x16x32_bf16 v[98:101], v[134:137], v[230:233], v[98:101]
	v_mfma_f32_16x16x32_bf16 v[102:105], v[138:141], v[226:229], v[102:105]
	v_mfma_f32_16x16x32_bf16 v[102:105], v[142:145], v[230:233], v[102:105]
	s_setprio 0
	s_setprio 1
	v_mfma_f32_16x16x32_bf16 v[106:109], v[180:183], v[196:199], v[106:109]
	v_mfma_f32_16x16x32_bf16 v[106:109], v[184:187], v[200:203], v[106:109]
	v_mfma_f32_16x16x32_bf16 v[110:113], v[188:191], v[196:199], v[110:113]
	v_mfma_f32_16x16x32_bf16 v[110:113], v[192:195], v[200:203], v[110:113]
	v_mfma_f32_16x16x32_bf16 v[114:117], v[180:183], v[204:207], v[114:117]
	v_mfma_f32_16x16x32_bf16 v[114:117], v[184:187], v[214:217], v[114:117]
	v_mfma_f32_16x16x32_bf16 v[50:53], v[188:191], v[204:207], v[50:53]
	v_mfma_f32_16x16x32_bf16 v[50:53], v[192:195], v[214:217], v[50:53]
	v_mfma_f32_16x16x32_bf16 v[54:57], v[180:183], v[218:221], v[54:57]
	v_mfma_f32_16x16x32_bf16 v[54:57], v[184:187], v[222:225], v[54:57]
	v_mfma_f32_16x16x32_bf16 v[58:61], v[188:191], v[218:221], v[58:61]
	v_mfma_f32_16x16x32_bf16 v[58:61], v[192:195], v[222:225], v[58:61]
	v_mfma_f32_16x16x32_bf16 v[62:65], v[180:183], v[226:229], v[62:65]
	v_mfma_f32_16x16x32_bf16 v[62:65], v[184:187], v[230:233], v[62:65]
	v_mfma_f32_16x16x32_bf16 v[66:69], v[188:191], v[226:229], v[66:69]
	v_mfma_f32_16x16x32_bf16 v[66:69], v[192:195], v[230:233], v[66:69]
	s_setprio 0
	s_barrier
; #define PG8_STAGE(bufoff, gbase, voff) do { _Pragma("unroll") for (int _i = 0; _i < 2; ++_i) \
;         __builtin_amdgcn_global_load_lds((const unsigned*)((const char*)(gbase) + (voff)[_i]), (PG8_LAS unsigned*)(lds + (bufoff) + ldsw + _i * 8192), 16, 0, 0); } while (0)
; #define PG8_LDA(dst, b, h) do { _Pragma("unroll") for (int m = 0; m < 4; ++m) _Pragma("unroll") for (int k = 0; k < 2; ++k) dst[m][k] = *(const PG8_LAS bf16x8*)(lds + PG8_SA(b, h) + aoff + m * 2048 + k * 1024); } while (0)
; #define PG8_LDB(dst, b, h) do { _Pragma("unroll") for (int n = 0; n < 2; ++n) _Pragma("unroll") for (int k = 0; k < 2; ++k) dst[n][k] = *(const PG8_LAS bf16x8*)(lds + PG8_SB(b, h) + boff + n * 2048 + k * 1024); } while (0)
; #define PG8_MMA(ai, bj, At, Bt) do { __builtin_amdgcn_s_setprio(1); _Pragma("unroll") for (int m = 0; m < 4; ++m) _Pragma("unroll") for (int n = 0; n < 2; ++n) _Pragma("unroll") for (int k = 0; k < 2; ++k) \
;         acc[ai][bj][m][n] = __builtin_amdgcn_mfma_f32_16x16x32_bf16(Bt[n][k], At[m][k], acc[ai][bj][m][n], 0, 0, 0); __builtin_amdgcn_s_setprio(0); } while (0)
; #define PG8_WAIT_V(n) asm volatile("s_waitcnt vmcnt(" #n ")" ::: "memory")
; #define PG8_WAIT_L(n) asm volatile("s_waitcnt lgkmcnt(" #n ")" ::: "memory")
; #define PG8_BAR __builtin_amdgcn_s_barrier()
; #define PG8_SCHED __builtin_amdgcn_sched_barrier(0)
; template <class Epi, class Sched, bool ALIGN_EPI = false, bool SP2 = false>
; __device__ __forceinline__ void gemm_phase(PG8_LAS unsigned char* lds, const Gemm g, const Sched& S, const Epi& E, const int tid) {
;     ...
;             PG8_LDA(At, 0, 1); PG8_STAGE(PG8_SB(0, 0), b2, voffB); PG8_STAGE(PG8_SB(0, 1), b2 + hstep, voffB); PG8_STAGE(PG8_SA(0, 0), a2, voffA);
;             PG8_WAIT_V(8); PG8_WAIT_L(0); PG8_BAR; PG8_MMA(1, 0, At, B0); PG8_MMA(1, 1, At, B1); PG8_BAR; PG8_SCHED;
;             PG8_LDB(B0, 1, 0); PG8_LDB(B1, 1, 1); PG8_SCHED; PG8_LDA(At, 1, 0); PG8_STAGE(PG8_SA(0, 1), a2 + hstep, voffA);
;             PG8_WAIT_V(8); PG8_WAIT_L(0); PG8_BAR; PG8_MMA(0, 0, At, B0); PG8_MMA(0, 1, At, B1); PG8_BAR; PG8_SCHED;
	s_mov_b64 s[26:27], 0x200
	s_mov_b32 m0, s8
	v_lshl_add_u64 v[208:209], v[2:3], 0, s[26:27]
	s_add_u32 s20, s46, 0x18200
	ds_read_b128 v[196:199], v178 offset:16384
	ds_read_b128 v[200:203], v178 offset:17408
	ds_read_b128 v[204:207], v178 offset:18432
	ds_read_b128 v[214:217], v178 offset:19456
	ds_read_b128 v[218:221], v178 offset:20480
	ds_read_b128 v[222:225], v178 offset:21504
	ds_read_b128 v[226:229], v178 offset:22528
	ds_read_b128 v[230:233], v178 offset:23552
	global_load_lds_dwordx4 v[208:209], off
	v_lshl_add_u64 v[208:209], v[4:5], 0, s[26:27]
	s_mov_b32 m0, s9
	s_addc_u32 s21, s47, 0
	global_load_lds_dwordx4 v[208:209], off
	v_lshl_add_u64 v[208:209], s[20:21], 0, v[166:167]
	s_mov_b32 m0, s14
	s_nop 0
	global_load_lds_dwordx4 v[208:209], off
	v_lshl_add_u64 v[208:209], s[20:21], 0, v[162:163]
	s_mov_b32 m0, s34
	s_nop 0
	global_load_lds_dwordx4 v[208:209], off
	v_lshl_add_u64 v[208:209], v[6:7], 0, s[26:27]
	s_mov_b32 m0, s1
	s_nop 0
	global_load_lds_dwordx4 v[208:209], off
	v_lshl_add_u64 v[208:209], v[8:9], 0, s[26:27]
	s_mov_b32 m0, s35
	s_nop 0
	global_load_lds_dwordx4 v[208:209], off
	s_waitcnt vmcnt(8)
	s_waitcnt lgkmcnt(0)
	s_barrier
	s_setprio 1
	s_waitcnt lgkmcnt(0)
	v_mfma_f32_16x16x32_bf16 v[42:45], v[130:133], v[226:229], v[42:45]
	v_mfma_f32_16x16x32_bf16 v[42:45], v[134:137], v[230:233], v[42:45]
	v_mfma_f32_16x16x32_bf16 v[26:29], v[138:141], v[226:229], v[26:29]
	v_mfma_f32_16x16x32_bf16 v[26:29], v[142:145], v[230:233], v[26:29]
	v_mfma_f32_16x16x32_bf16 v[146:149], v[130:133], v[196:199], v[146:149]
	v_mfma_f32_16x16x32_bf16 v[146:149], v[134:137], v[200:203], v[146:149]
	v_mfma_f32_16x16x32_bf16 v[150:153], v[138:141], v[196:199], v[150:153]
	v_mfma_f32_16x16x32_bf16 v[150:153], v[142:145], v[200:203], v[150:153]
	v_mfma_f32_16x16x32_bf16 v[154:157], v[130:133], v[204:207], v[154:157]
	v_mfma_f32_16x16x32_bf16 v[154:157], v[134:137], v[214:217], v[154:157]
	v_mfma_f32_16x16x32_bf16 v[158:161], v[138:141], v[204:207], v[158:161]
	v_mfma_f32_16x16x32_bf16 v[158:161], v[142:145], v[214:217], v[158:161]
	v_mfma_f32_16x16x32_bf16 v[170:173], v[130:133], v[218:221], v[170:173]
	v_mfma_f32_16x16x32_bf16 v[170:173], v[134:137], v[222:225], v[170:173]
	v_mfma_f32_16x16x32_bf16 v[174:177], v[138:141], v[218:221], v[174:177]
	v_mfma_f32_16x16x32_bf16 v[174:177], v[142:145], v[222:225], v[174:177]
	s_setprio 0
	s_setprio 1
	v_mfma_f32_16x16x32_bf16 v[30:33], v[180:183], v[196:199], v[30:33]
	v_mfma_f32_16x16x32_bf16 v[30:33], v[184:187], v[200:203], v[30:33]
	v_mfma_f32_16x16x32_bf16 v[46:49], v[188:191], v[196:199], v[46:49]
	v_mfma_f32_16x16x32_bf16 v[46:49], v[192:195], v[200:203], v[46:49]
	v_mfma_f32_16x16x32_bf16 v[70:73], v[180:183], v[204:207], v[70:73]
	v_mfma_f32_16x16x32_bf16 v[70:73], v[184:187], v[214:217], v[70:73]
	v_mfma_f32_16x16x32_bf16 v[118:121], v[188:191], v[204:207], v[118:121]
	v_mfma_f32_16x16x32_bf16 v[118:121], v[192:195], v[214:217], v[118:121]
	v_mfma_f32_16x16x32_bf16 v[122:125], v[180:183], v[218:221], v[122:125]
	v_mfma_f32_16x16x32_bf16 v[122:125], v[184:187], v[222:225], v[122:125]
	v_mfma_f32_16x16x32_bf16 v[126:129], v[188:191], v[218:221], v[126:129]
	v_mfma_f32_16x16x32_bf16 v[126:129], v[192:195], v[222:225], v[126:129]
	v_mfma_f32_16x16x32_bf16 v[34:37], v[180:183], v[226:229], v[34:37]
	v_mfma_f32_16x16x32_bf16 v[34:37], v[184:187], v[230:233], v[34:37]
	v_mfma_f32_16x16x32_bf16 v[38:41], v[188:191], v[226:229], v[38:41]
	v_mfma_f32_16x16x32_bf16 v[38:41], v[192:195], v[230:233], v[38:41]
	s_setprio 0
	s_barrier
	ds_read_b128 v[130:133], v17
	ds_read_b128 v[134:137], v18
	ds_read_b128 v[138:141], v19
	ds_read_b128 v[142:145], v20
	ds_read_b128 v[180:183], v21
	ds_read_b128 v[184:187], v22
	ds_read_b128 v[188:191], v23
	ds_read_b128 v[192:195], v24
	s_add_u32 s20, s30, 0x18200
	s_addc_u32 s21, s31, 0
	s_mov_b32 m0, s84
	v_lshl_add_u64 v[208:209], s[20:21], 0, v[168:169]
	ds_read_b128 v[196:199], v178 offset:32768
	ds_read_b128 v[200:203], v178 offset:33792
	ds_read_b128 v[204:207], v178 offset:34816
	ds_read_b128 v[214:217], v178 offset:35840
	ds_read_b128 v[218:221], v178 offset:36864
	ds_read_b128 v[222:225], v178 offset:37888
	ds_read_b128 v[226:229], v178 offset:38912
	ds_read_b128 v[230:233], v178 offset:39936
	global_load_lds_dwordx4 v[208:209], off
	v_lshl_add_u64 v[208:209], s[20:21], 0, v[164:165]
	s_mov_b32 m0, s85
	s_nop 0
	global_load_lds_dwordx4 v[208:209], off
	s_waitcnt vmcnt(8)
	s_waitcnt lgkmcnt(0)
	s_barrier
	s_setprio 1
	s_waitcnt lgkmcnt(0)
	v_mfma_f32_16x16x32_bf16 v[74:77], v[130:133], v[196:199], v[74:77]
	v_mfma_f32_16x16x32_bf16 v[74:77], v[134:137], v[200:203], v[74:77]
	v_mfma_f32_16x16x32_bf16 v[78:81], v[138:141], v[196:199], v[78:81]
	v_mfma_f32_16x16x32_bf16 v[78:81], v[142:145], v[200:203], v[78:81]
	v_mfma_f32_16x16x32_bf16 v[82:85], v[130:133], v[204:207], v[82:85]
	v_mfma_f32_16x16x32_bf16 v[82:85], v[134:137], v[214:217], v[82:85]
	v_mfma_f32_16x16x32_bf16 v[86:89], v[138:141], v[204:207], v[86:89]
	v_mfma_f32_16x16x32_bf16 v[86:89], v[142:145], v[214:217], v[86:89]
	v_mfma_f32_16x16x32_bf16 v[90:93], v[130:133], v[218:221], v[90:93]
	v_mfma_f32_16x16x32_bf16 v[90:93], v[134:137], v[222:225], v[90:93]
	v_mfma_f32_16x16x32_bf16 v[94:97], v[138:141], v[218:221], v[94:97]
	v_mfma_f32_16x16x32_bf16 v[94:97], v[142:145], v[222:225], v[94:97]
	v_mfma_f32_16x16x32_bf16 v[98:101], v[130:133], v[226:229], v[98:101]
	v_mfma_f32_16x16x32_bf16 v[98:101], v[134:137], v[230:233], v[98:101]
	v_mfma_f32_16x16x32_bf16 v[102:105], v[138:141], v[226:229], v[102:105]
	v_mfma_f32_16x16x32_bf16 v[102:105], v[142:145], v[230:233], v[102:105]
	s_setprio 0
	s_setprio 1
	v_mfma_f32_16x16x32_bf16 v[106:109], v[180:183], v[196:199], v[106:109]
	v_mfma_f32_16x16x32_bf16 v[106:109], v[184:187], v[200:203], v[106:109]
	v_mfma_f32_16x16x32_bf16 v[110:113], v[188:191], v[196:199], v[110:113]
	v_mfma_f32_16x16x32_bf16 v[110:113], v[192:195], v[200:203], v[110:113]
	v_mfma_f32_16x16x32_bf16 v[114:117], v[180:183], v[204:207], v[114:117]
	v_mfma_f32_16x16x32_bf16 v[114:117], v[184:187], v[214:217], v[114:117]
	v_mfma_f32_16x16x32_bf16 v[50:53], v[188:191], v[204:207], v[50:53]
	v_mfma_f32_16x16x32_bf16 v[50:53], v[192:195], v[214:217], v[50:53]
	v_mfma_f32_16x16x32_bf16 v[54:57], v[180:183], v[218:221], v[54:57]
	v_mfma_f32_16x16x32_bf16 v[54:57], v[184:187], v[222:225], v[54:57]
	v_mfma_f32_16x16x32_bf16 v[58:61], v[188:191], v[218:221], v[58:61]
	v_mfma_f32_16x16x32_bf16 v[58:61], v[192:195], v[222:225], v[58:61]
	v_mfma_f32_16x16x32_bf16 v[62:65], v[180:183], v[226:229], v[62:65]
	v_mfma_f32_16x16x32_bf16 v[62:65], v[184:187], v[230:233], v[62:65]
	v_mfma_f32_16x16x32_bf16 v[66:69], v[188:191], v[226:229], v[66:69]
	v_mfma_f32_16x16x32_bf16 v[66:69], v[192:195], v[230:233], v[66:69]
	s_setprio 0
	s_barrier
; #define PG8_STAGE(bufoff, gbase, voff) do { _Pragma("unroll") for (int _i = 0; _i < 2; ++_i) \
;         __builtin_amdgcn_global_load_lds((const unsigned*)((const char*)(gbase) + (voff)[_i]), (PG8_LAS unsigned*)(lds + (bufoff) + ldsw + _i * 8192), 16, 0, 0); } while (0)
; #define PG8_LDA(dst, b, h) do { _Pragma("unroll") for (int m = 0; m < 4; ++m) _Pragma("unroll") for (int k = 0; k < 2; ++k) dst[m][k] = *(const PG8_LAS bf16x8*)(lds + PG8_SA(b, h) + aoff + m * 2048 + k * 1024); } while (0)
; #define PG8_LDB(dst, b, h) do { _Pragma("unroll") for (int n = 0; n < 2; ++n) _Pragma("unroll") for (int k = 0; k < 2; ++k) dst[n][k] = *(const PG8_LAS bf16x8*)(lds + PG8_SB(b, h) + boff + n * 2048 + k * 1024); } while (0)
; #define PG8_MMA(ai, bj, At, Bt) do { __builtin_amdgcn_s_setprio(1); _Pragma("unroll") for (int m = 0; m < 4; ++m) _Pragma("unroll") for (int n = 0; n < 2; ++n) _Pragma("unroll") for (int k = 0; k < 2; ++k) \
;         acc[ai][bj][m][n] = __builtin_amdgcn_mfma_f32_16x16x32_bf16(Bt[n][k], At[m][k], acc[ai][bj][m][n], 0, 0, 0); __builtin_amdgcn_s_setprio(0); } while (0)
; #define PG8_BAR __builtin_amdgcn_s_barrier()
; template <class Epi, class Sched, bool ALIGN_EPI = false, bool SP2 = false>
; __device__ __forceinline__ void gemm_phase(PG8_LAS unsigned char* lds, const Gemm g, const Sched& S, const Epi& E, const int tid) {
;     ...
;             PG8_LDB(B0, 0, 0); PG8_LDB(B1, 0, 1); PG8_SCHED; PG8_LDA(At, 0, 0); PG8_STAGE(PG8_SA(1, 1), a1 + hstep, voffA);
;             PG8_WAIT_V(8); PG8_WAIT_L(0); PG8_BAR; PG8_MMA(0, 0, At, B0); PG8_MMA(0, 1, At, B1); PG8_BAR; PG8_SCHED;
;             PG8_LDA(At, 0, 1); PG8_STAGE(PG8_SB(0, 0), b2, voffB); PG8_STAGE(PG8_SB(0, 1), b2 + hstep, voffB); PG8_STAGE(PG8_SA(0, 0), a2, voffA);
;             PG8_WAIT_V(8); PG8_WAIT_L(0); PG8_BAR; PG8_MMA(1, 0, At, B0); PG8_MMA(1, 1, At, B1); PG8_BAR; PG8_SCHED;
;             PG8_LDB(B0, 1, 0); PG8_LDB(B1, 1, 1); PG8_SCHED; PG8_LDA(At, 1, 0); PG8_STAGE(PG8_SA(0, 1), a2 + hstep, voffA);
;             PG8_WAIT_V(8); PG8_WAIT_L(0); PG8_BAR; PG8_MMA(0, 0, At, B0); PG8_MMA(0, 1, At, B1); PG8_BAR; PG8_SCHED;
;             PG8_LDA(At, 1, 1); PG8_STAGE(PG8_SB(1, 0), b3, voffB); PG8_STAGE(PG8_SB(1, 1), b3 + hstep, voffB); PG8_STAGE(PG8_SA(1, 0), a3, voffA);
;             PG8_WAIT_V(8); PG8_WAIT_L(0); PG8_BAR; PG8_MMA(1, 0, At, B0); PG8_MMA(1, 1, At, B1); PG8_BAR; PG8_SCHED;
	s_mov_b64 s[26:27], 0x280
	s_mov_b32 m0, s88
	v_lshl_add_u64 v[2:3], v[2:3], 0, s[26:27]
	s_add_u32 s20, s46, 0x18280
	ds_read_b128 v[196:199], v178 offset:49152
	ds_read_b128 v[200:203], v178 offset:50176
	ds_read_b128 v[204:207], v178 offset:51200
	ds_read_b128 v[214:217], v178 offset:52224
	ds_read_b128 v[218:221], v178 offset:53248
	ds_read_b128 v[222:225], v178 offset:54272
	ds_read_b128 v[226:229], v178 offset:55296
	ds_read_b128 v[230:233], v178 offset:56320
	global_load_lds_dwordx4 v[2:3], off
	v_lshl_add_u64 v[2:3], v[4:5], 0, s[26:27]
	s_mov_b32 m0, s89
	s_addc_u32 s21, s47, 0
	global_load_lds_dwordx4 v[2:3], off
	v_lshl_add_u64 v[2:3], s[20:21], 0, v[166:167]
	s_mov_b32 m0, s28
	s_nop 0
	global_load_lds_dwordx4 v[2:3], off
	v_lshl_add_u64 v[2:3], s[20:21], 0, v[162:163]
	s_mov_b32 m0, s29
	s_nop 0
	global_load_lds_dwordx4 v[2:3], off
	v_lshl_add_u64 v[2:3], v[6:7], 0, s[26:27]
	s_mov_b32 m0, s90
	s_nop 0
	global_load_lds_dwordx4 v[2:3], off
	v_lshl_add_u64 v[2:3], v[8:9], 0, s[26:27]
	s_mov_b32 m0, s91
	s_nop 0
	global_load_lds_dwordx4 v[2:3], off
	s_waitcnt vmcnt(8)
	s_waitcnt lgkmcnt(0)
	s_barrier
	s_setprio 1
	s_waitcnt lgkmcnt(0)
	v_mfma_f32_16x16x32_bf16 v[2:5], v[130:133], v[196:199], v[146:149]
	v_mfma_f32_16x16x32_bf16 v[6:9], v[138:141], v[196:199], v[150:153]
	v_mfma_f32_16x16x32_bf16 v[42:45], v[130:133], v[226:229], v[42:45]
	v_mfma_f32_16x16x32_bf16 v[26:29], v[138:141], v[226:229], v[26:29]
	v_mfma_f32_16x16x32_bf16 v[2:5], v[134:137], v[200:203], v[2:5]
	v_mfma_f32_16x16x32_bf16 v[6:9], v[142:145], v[200:203], v[6:9]
	v_mfma_f32_16x16x32_bf16 v[146:149], v[130:133], v[204:207], v[154:157]
	v_mfma_f32_16x16x32_bf16 v[150:153], v[138:141], v[204:207], v[158:161]
	v_mfma_f32_16x16x32_bf16 v[154:157], v[130:133], v[218:221], v[170:173]
	v_mfma_f32_16x16x32_bf16 v[158:161], v[138:141], v[218:221], v[174:177]
	v_mfma_f32_16x16x32_bf16 v[42:45], v[134:137], v[230:233], v[42:45]
	v_mfma_f32_16x16x32_bf16 v[26:29], v[142:145], v[230:233], v[26:29]
	v_mfma_f32_16x16x32_bf16 v[146:149], v[134:137], v[214:217], v[146:149]
	v_mfma_f32_16x16x32_bf16 v[150:153], v[142:145], v[214:217], v[150:153]
	v_mfma_f32_16x16x32_bf16 v[154:157], v[134:137], v[222:225], v[154:157]
	v_mfma_f32_16x16x32_bf16 v[158:161], v[142:145], v[222:225], v[158:161]
	s_setprio 0
	s_setprio 1
	v_mfma_f32_16x16x32_bf16 v[30:33], v[180:183], v[196:199], v[30:33]
	v_mfma_f32_16x16x32_bf16 v[30:33], v[184:187], v[200:203], v[30:33]
	v_mfma_f32_16x16x32_bf16 v[46:49], v[188:191], v[196:199], v[46:49]
	v_mfma_f32_16x16x32_bf16 v[46:49], v[192:195], v[200:203], v[46:49]
	v_mfma_f32_16x16x32_bf16 v[70:73], v[180:183], v[204:207], v[70:73]
	v_mfma_f32_16x16x32_bf16 v[70:73], v[184:187], v[214:217], v[70:73]
	v_mfma_f32_16x16x32_bf16 v[118:121], v[188:191], v[204:207], v[118:121]
	v_mfma_f32_16x16x32_bf16 v[118:121], v[192:195], v[214:217], v[118:121]
	v_mfma_f32_16x16x32_bf16 v[122:125], v[180:183], v[218:221], v[122:125]
	v_mfma_f32_16x16x32_bf16 v[122:125], v[184:187], v[222:225], v[122:125]
	v_mfma_f32_16x16x32_bf16 v[126:129], v[188:191], v[218:221], v[126:129]
	v_mfma_f32_16x16x32_bf16 v[126:129], v[192:195], v[222:225], v[126:129]
	v_mfma_f32_16x16x32_bf16 v[34:37], v[180:183], v[226:229], v[34:37]
	v_mfma_f32_16x16x32_bf16 v[34:37], v[184:187], v[230:233], v[34:37]
	v_mfma_f32_16x16x32_bf16 v[38:41], v[188:191], v[226:229], v[38:41]
	v_mfma_f32_16x16x32_bf16 v[38:41], v[192:195], v[230:233], v[38:41]
	s_setprio 0
	s_barrier
	ds_read_b128 v[130:133], v0
	ds_read_b128 v[134:137], v10
	ds_read_b128 v[138:141], v11
	ds_read_b128 v[142:145], v12
	ds_read_b128 v[10:13], v13
	ds_read_b128 v[170:173], v14
	ds_read_b128 v[174:177], v15
	ds_read_b128 v[180:183], v16
	s_add_u32 s20, s30, 0x18280
	s_addc_u32 s21, s31, 0
	s_mov_b32 m0, s5
	v_lshl_add_u64 v[14:15], s[20:21], 0, v[168:169]
	ds_read_b128 v[184:187], v178
	ds_read_b128 v[188:191], v178 offset:1024
	ds_read_b128 v[192:195], v178 offset:2048
	ds_read_b128 v[196:199], v178 offset:3072
	ds_read_b128 v[200:203], v178 offset:4096
	ds_read_b128 v[204:207], v178 offset:5120
	ds_read_b128 v[214:217], v178 offset:6144
	ds_read_b128 v[218:221], v178 offset:7168
	global_load_lds_dwordx4 v[14:15], off
	v_lshl_add_u64 v[14:15], s[20:21], 0, v[164:165]
	s_mov_b32 m0, s4
	s_nop 0
	global_load_lds_dwordx4 v[14:15], off
	s_waitcnt vmcnt(8)
	s_waitcnt lgkmcnt(0)
	s_barrier
	s_setprio 1
	s_waitcnt lgkmcnt(0)
	v_mfma_f32_16x16x32_bf16 v[94:97], v[138:141], v[200:203], v[94:97]
	v_mfma_f32_16x16x32_bf16 v[222:225], v[142:145], v[204:207], v[94:97]
	v_mfma_f32_16x16x32_bf16 v[94:97], v[130:133], v[214:217], v[98:101]
	v_mfma_f32_16x16x32_bf16 v[74:77], v[130:133], v[184:187], v[74:77]
	v_mfma_f32_16x16x32_bf16 v[78:81], v[138:141], v[184:187], v[78:81]
	v_mfma_f32_16x16x32_bf16 v[82:85], v[130:133], v[192:195], v[82:85]
	v_mfma_f32_16x16x32_bf16 v[86:89], v[138:141], v[192:195], v[86:89]
	v_mfma_f32_16x16x32_bf16 v[90:93], v[130:133], v[200:203], v[90:93]
	v_mfma_f32_16x16x32_bf16 v[98:101], v[134:137], v[218:221], v[94:97]
	v_mfma_f32_16x16x32_bf16 v[94:97], v[138:141], v[214:217], v[102:105]
	v_mfma_f32_16x16x32_bf16 v[74:77], v[134:137], v[188:191], v[74:77]
	v_mfma_f32_16x16x32_bf16 v[78:81], v[142:145], v[188:191], v[78:81]
	v_mfma_f32_16x16x32_bf16 v[82:85], v[134:137], v[196:199], v[82:85]
	v_mfma_f32_16x16x32_bf16 v[86:89], v[142:145], v[196:199], v[86:89]
	v_mfma_f32_16x16x32_bf16 v[90:93], v[134:137], v[204:207], v[90:93]
	v_mfma_f32_16x16x32_bf16 v[102:105], v[142:145], v[218:221], v[94:97]
	s_setprio 0
	s_setprio 1
	v_mfma_f32_16x16x32_bf16 v[94:97], v[10:13], v[184:187], v[106:109]
	v_mfma_f32_16x16x32_bf16 v[226:229], v[170:173], v[188:191], v[94:97]
	v_mfma_f32_16x16x32_bf16 v[94:97], v[174:177], v[184:187], v[110:113]
	v_mfma_f32_16x16x32_bf16 v[50:53], v[174:177], v[192:195], v[50:53]
	v_mfma_f32_16x16x32_bf16 v[54:57], v[10:13], v[200:203], v[54:57]
	v_mfma_f32_16x16x32_bf16 v[58:61], v[174:177], v[200:203], v[58:61]
	v_mfma_f32_16x16x32_bf16 v[62:65], v[10:13], v[214:217], v[62:65]
	v_mfma_f32_16x16x32_bf16 v[184:187], v[180:183], v[188:191], v[94:97]
	v_mfma_f32_16x16x32_bf16 v[94:97], v[10:13], v[192:195], v[114:117]
	v_mfma_f32_16x16x32_bf16 v[50:53], v[180:183], v[196:199], v[50:53]
	v_mfma_f32_16x16x32_bf16 v[54:57], v[170:173], v[204:207], v[54:57]
	v_mfma_f32_16x16x32_bf16 v[58:61], v[180:183], v[204:207], v[58:61]
	v_mfma_f32_16x16x32_bf16 v[62:65], v[170:173], v[218:221], v[62:65]
	v_mfma_f32_16x16x32_bf16 v[66:69], v[174:177], v[214:217], v[66:69]
	v_mfma_f32_16x16x32_bf16 v[188:191], v[170:173], v[196:199], v[94:97]
	v_mfma_f32_16x16x32_bf16 v[192:195], v[180:183], v[218:221], v[66:69]
	s_setprio 0
	s_barrier
; #define PG8_STAGE(bufoff, gbase, voff) do { _Pragma("unroll") for (int _i = 0; _i < 2; ++_i) \
;         __builtin_amdgcn_global_load_lds((const unsigned*)((const char*)(gbase) + (voff)[_i]), (PG8_LAS unsigned*)(lds + (bufoff) + ldsw + _i * 8192), 16, 0, 0); } while (0)
; #define PG8_LDA(dst, b, h) do { _Pragma("unroll") for (int m = 0; m < 4; ++m) _Pragma("unroll") for (int k = 0; k < 2; ++k) dst[m][k] = *(const PG8_LAS bf16x8*)(lds + PG8_SA(b, h) + aoff + m * 2048 + k * 1024); } while (0)
; #define PG8_LDB(dst, b, h) do { _Pragma("unroll") for (int n = 0; n < 2; ++n) _Pragma("unroll") for (int k = 0; k < 2; ++k) dst[n][k] = *(const PG8_LAS bf16x8*)(lds + PG8_SB(b, h) + boff + n * 2048 + k * 1024); } while (0)
; #define PG8_MMA(ai, bj, At, Bt) do { __builtin_amdgcn_s_setprio(1); _Pragma("unroll") for (int m = 0; m < 4; ++m) _Pragma("unroll") for (int n = 0; n < 2; ++n) _Pragma("unroll") for (int k = 0; k < 2; ++k) \
;         acc[ai][bj][m][n] = __builtin_amdgcn_mfma_f32_16x16x32_bf16(Bt[n][k], At[m][k], acc[ai][bj][m][n], 0, 0, 0); __builtin_amdgcn_s_setprio(0); } while (0)
; #define PG8_WAIT_V(n) asm volatile("s_waitcnt vmcnt(" #n ")" ::: "memory")
; #define PG8_WAIT_L(n) asm volatile("s_waitcnt lgkmcnt(" #n ")" ::: "memory")
; #define PG8_BAR __builtin_amdgcn_s_barrier()
; #define PG8_SCHED __builtin_amdgcn_sched_barrier(0)
; template <class Epi, class Sched, bool ALIGN_EPI = false, bool SP2 = false>
; __device__ __forceinline__ void gemm_phase(PG8_LAS unsigned char* lds, const Gemm g, const Sched& S, const Epi& E, const int tid) {
;     ...
;             PG8_LDA(At, 0, 1); PG8_STAGE(PG8_SB(0, 0), b2, voffB); PG8_STAGE(PG8_SB(0, 1), b2 + hstep, voffB); PG8_STAGE(PG8_SA(0, 0), a2, voffA);
;             PG8_WAIT_V(8); PG8_WAIT_L(0); PG8_BAR; PG8_MMA(1, 0, At, B0); PG8_MMA(1, 1, At, B1); PG8_BAR; PG8_SCHED;
;             PG8_LDB(B0, 1, 0); PG8_LDB(B1, 1, 1); PG8_SCHED; PG8_LDA(At, 1, 0); PG8_STAGE(PG8_SA(0, 1), a2 + hstep, voffA);
	s_mov_b32 m0, s8
	v_lshl_add_u64 v[208:209], s[44:45], 0, v[166:167]
	s_add_u32 s4, s44, 0x18000
	s_nop 0
	ds_read_b128 v[66:69], v178 offset:16384
	ds_read_b128 v[94:97], v178 offset:17408
	ds_read_b128 v[106:109], v178 offset:18432
	ds_read_b128 v[110:113], v178 offset:19456
	ds_read_b128 v[114:117], v178 offset:20480
	ds_read_b128 v[196:199], v178 offset:21504
	ds_read_b128 v[200:203], v178 offset:22528
	ds_read_b128 v[204:207], v178 offset:23552
	global_load_lds_dwordx4 v[208:209], off
	v_lshl_add_u64 v[210:211], s[44:45], 0, v[162:163]
	s_mov_b32 m0, s9
	s_addc_u32 s5, s45, 0
	global_load_lds_dwordx4 v[210:211], off
	v_lshl_add_u64 v[14:15], s[4:5], 0, v[166:167]
	s_mov_b32 m0, s14
	v_lshl_add_u64 v[212:213], s[38:39], 0, v[168:169]
	global_load_lds_dwordx4 v[14:15], off
	v_lshl_add_u64 v[14:15], s[4:5], 0, v[162:163]
	s_mov_b32 m0, s34
	v_lshl_add_u64 v[246:247], s[38:39], 0, v[164:165]
	global_load_lds_dwordx4 v[14:15], off
	s_mov_b32 m0, s1
	s_nop 0
	global_load_lds_dwordx4 v[212:213], off
	s_mov_b32 m0, s35
	s_nop 0
	global_load_lds_dwordx4 v[246:247], off
	s_waitcnt vmcnt(8)
	s_waitcnt lgkmcnt(0)
	s_barrier
	s_setprio 1
	s_waitcnt lgkmcnt(0)
	v_mfma_f32_16x16x32_bf16 v[2:5], v[130:133], v[66:69], v[2:5]
	v_mfma_f32_16x16x32_bf16 v[6:9], v[138:141], v[66:69], v[6:9]
	v_mfma_f32_16x16x32_bf16 v[2:5], v[134:137], v[94:97], v[2:5]
	v_mfma_f32_16x16x32_bf16 v[6:9], v[142:145], v[94:97], v[6:9]
	v_mfma_f32_16x16x32_bf16 v[146:149], v[130:133], v[106:109], v[146:149]
	v_mfma_f32_16x16x32_bf16 v[150:153], v[138:141], v[106:109], v[150:153]
	v_mfma_f32_16x16x32_bf16 v[154:157], v[130:133], v[114:117], v[154:157]
	v_mfma_f32_16x16x32_bf16 v[158:161], v[138:141], v[114:117], v[158:161]
	v_mfma_f32_16x16x32_bf16 v[42:45], v[130:133], v[200:203], v[42:45]
	v_mfma_f32_16x16x32_bf16 v[26:29], v[138:141], v[200:203], v[26:29]
	v_mfma_f32_16x16x32_bf16 v[146:149], v[134:137], v[110:113], v[146:149]
	v_mfma_f32_16x16x32_bf16 v[150:153], v[142:145], v[110:113], v[150:153]
	v_mfma_f32_16x16x32_bf16 v[154:157], v[134:137], v[196:199], v[154:157]
	v_mfma_f32_16x16x32_bf16 v[158:161], v[142:145], v[196:199], v[158:161]
	v_mfma_f32_16x16x32_bf16 v[130:133], v[134:137], v[204:207], v[42:45]
	v_mfma_f32_16x16x32_bf16 v[134:137], v[142:145], v[204:207], v[26:29]
	s_setprio 0
	s_setprio 1
	v_mfma_f32_16x16x32_bf16 v[26:29], v[10:13], v[66:69], v[30:33]
	v_mfma_f32_16x16x32_bf16 v[138:141], v[170:173], v[94:97], v[26:29]
	v_mfma_f32_16x16x32_bf16 v[26:29], v[174:177], v[66:69], v[46:49]
	v_mfma_f32_16x16x32_bf16 v[142:145], v[180:183], v[94:97], v[26:29]
	v_mfma_f32_16x16x32_bf16 v[26:29], v[10:13], v[106:109], v[70:73]
	v_mfma_f32_16x16x32_bf16 v[214:217], v[170:173], v[110:113], v[26:29]
	v_mfma_f32_16x16x32_bf16 v[26:29], v[174:177], v[106:109], v[118:121]
	v_mfma_f32_16x16x32_bf16 v[218:221], v[180:183], v[110:113], v[26:29]
	v_mfma_f32_16x16x32_bf16 v[26:29], v[10:13], v[114:117], v[122:125]
	v_mfma_f32_16x16x32_bf16 v[10:13], v[10:13], v[200:203], v[34:37]
	v_mfma_f32_16x16x32_bf16 v[230:233], v[170:173], v[196:199], v[26:29]
	v_mfma_f32_16x16x32_bf16 v[26:29], v[174:177], v[114:117], v[126:129]
	v_mfma_f32_16x16x32_bf16 v[170:173], v[170:173], v[204:207], v[10:13]
	v_mfma_f32_16x16x32_bf16 v[10:13], v[174:177], v[200:203], v[38:41]
	v_mfma_f32_16x16x32_bf16 v[196:199], v[180:183], v[196:199], v[26:29]
	v_mfma_f32_16x16x32_bf16 v[174:177], v[180:183], v[204:207], v[10:13]
	s_setprio 0
	s_barrier
	s_nop 3
	ds_read_b128 v[10:13], v17
	ds_read_b128 v[14:17], v18
	ds_read_b128 v[34:37], v19
	ds_read_b128 v[38:41], v20
	ds_read_b128 v[180:183], v21
	ds_read_b128 v[200:203], v22
	ds_read_b128 v[204:207], v23
	ds_read_b128 v[234:237], v24
	s_add_u32 s4, s38, 0x18000
	s_addc_u32 s5, s39, 0
	s_mov_b32 m0, s84
	v_lshl_add_u64 v[66:67], s[4:5], 0, v[168:169]
	ds_read_b128 v[18:21], v178 offset:32768
	ds_read_b128 v[22:25], v178 offset:33792
	ds_read_b128 v[26:29], v178 offset:34816
	ds_read_b128 v[30:33], v178 offset:35840
	ds_read_b128 v[42:45], v178 offset:36864
	ds_read_b128 v[46:49], v178 offset:37888
	ds_read_b128 v[238:241], v178 offset:38912
	ds_read_b128 v[242:245], v178 offset:39936
	global_load_lds_dwordx4 v[66:67], off
	v_lshl_add_u64 v[66:67], s[4:5], 0, v[164:165]
	s_mov_b32 m0, s85
	s_nop 0
	global_load_lds_dwordx4 v[66:67], off
	s_waitcnt vmcnt(8)
	s_waitcnt lgkmcnt(0)
	s_barrier
; #define PG8_STAGE(bufoff, gbase, voff) do { _Pragma("unroll") for (int _i = 0; _i < 2; ++_i) \
;         __builtin_amdgcn_global_load_lds((const unsigned*)((const char*)(gbase) + (voff)[_i]), (PG8_LAS unsigned*)(lds + (bufoff) + ldsw + _i * 8192), 16, 0, 0); } while (0)
; #define PG8_LDA(dst, b, h) do { _Pragma("unroll") for (int m = 0; m < 4; ++m) _Pragma("unroll") for (int k = 0; k < 2; ++k) dst[m][k] = *(const PG8_LAS bf16x8*)(lds + PG8_SA(b, h) + aoff + m * 2048 + k * 1024); } while (0)
; #define PG8_MMA(ai, bj, At, Bt) do { __builtin_amdgcn_s_setprio(1); _Pragma("unroll") for (int m = 0; m < 4; ++m) _Pragma("unroll") for (int n = 0; n < 2; ++n) _Pragma("unroll") for (int k = 0; k < 2; ++k) \
;         acc[ai][bj][m][n] = __builtin_amdgcn_mfma_f32_16x16x32_bf16(Bt[n][k], At[m][k], acc[ai][bj][m][n], 0, 0, 0); __builtin_amdgcn_s_setprio(0); } while (0)
; #define PG8_WAIT_V(n) asm volatile("s_waitcnt vmcnt(" #n ")" ::: "memory")
; #define PG8_WAIT_L(n) asm volatile("s_waitcnt lgkmcnt(" #n ")" ::: "memory")
; #define PG8_BAR __builtin_amdgcn_s_barrier()
; #define PG8_SCHED __builtin_amdgcn_sched_barrier(0)
; template <class Epi, class Sched, bool ALIGN_EPI = false, bool SP2 = false>
; __device__ __forceinline__ void gemm_phase(PG8_LAS unsigned char* lds, const Gemm g, const Sched& S, const Epi& E, const int tid) {
;     ...
;             PG8_WAIT_V(8); PG8_WAIT_L(0); PG8_BAR; PG8_MMA(0, 0, At, B0); PG8_MMA(0, 1, At, B1); PG8_BAR; PG8_SCHED;
;             PG8_LDA(At, 1, 1); PG8_STAGE(PG8_SB(1, 0), b3, voffB); PG8_STAGE(PG8_SB(1, 1), b3 + hstep, voffB); PG8_STAGE(PG8_SA(1, 0), a3, voffA);
;             PG8_WAIT_V(8); PG8_WAIT_L(0); PG8_BAR; PG8_MMA(1, 0, At, B0); PG8_MMA(1, 1, At, B1); PG8_BAR; PG8_SCHED;
	s_setprio 1
	s_waitcnt lgkmcnt(0)
	v_mfma_f32_16x16x32_bf16 v[66:69], v[10:13], v[18:21], v[74:77]
	v_mfma_f32_16x16x32_bf16 v[126:129], v[14:17], v[22:25], v[66:69]
	v_mfma_f32_16x16x32_bf16 v[66:69], v[34:37], v[18:21], v[78:81]
	v_mfma_f32_16x16x32_bf16 v[122:125], v[38:41], v[22:25], v[66:69]
	v_mfma_f32_16x16x32_bf16 v[66:69], v[10:13], v[26:29], v[82:85]
	v_mfma_f32_16x16x32_bf16 v[110:113], v[14:17], v[30:33], v[66:69]
	v_mfma_f32_16x16x32_bf16 v[66:69], v[34:37], v[26:29], v[86:89]
	v_mfma_f32_16x16x32_bf16 v[106:109], v[38:41], v[30:33], v[66:69]
	v_mfma_f32_16x16x32_bf16 v[66:69], v[10:13], v[42:45], v[90:93]
	v_mfma_f32_16x16x32_bf16 v[94:97], v[14:17], v[46:49], v[66:69]
	v_mfma_f32_16x16x32_bf16 v[66:69], v[34:37], v[42:45], v[222:225]
	v_mfma_f32_16x16x32_bf16 v[90:93], v[38:41], v[46:49], v[66:69]
	v_mfma_f32_16x16x32_bf16 v[66:69], v[10:13], v[238:241], v[98:101]
	v_mfma_f32_16x16x32_bf16 v[70:73], v[14:17], v[242:245], v[66:69]
	v_mfma_f32_16x16x32_bf16 v[66:69], v[34:37], v[238:241], v[102:105]
	v_mfma_f32_16x16x32_bf16 v[66:69], v[38:41], v[242:245], v[66:69]
	s_setprio 0
	s_setprio 1
	v_mfma_f32_16x16x32_bf16 v[74:77], v[180:183], v[18:21], v[226:229]
	v_mfma_f32_16x16x32_bf16 v[18:21], v[204:207], v[18:21], v[184:187]
	v_mfma_f32_16x16x32_bf16 v[114:117], v[234:237], v[22:25], v[18:21]
	v_mfma_f32_16x16x32_bf16 v[18:21], v[180:183], v[26:29], v[188:191]
	v_mfma_f32_16x16x32_bf16 v[102:105], v[200:203], v[30:33], v[18:21]
	v_mfma_f32_16x16x32_bf16 v[18:21], v[204:207], v[26:29], v[50:53]
	v_mfma_f32_16x16x32_bf16 v[98:101], v[234:237], v[30:33], v[18:21]
	v_mfma_f32_16x16x32_bf16 v[18:21], v[180:183], v[42:45], v[54:57]
	v_mfma_f32_16x16x32_bf16 v[86:89], v[200:203], v[46:49], v[18:21]
	v_mfma_f32_16x16x32_bf16 v[18:21], v[204:207], v[42:45], v[58:61]
	v_mfma_f32_16x16x32_bf16 v[82:85], v[234:237], v[46:49], v[18:21]
	v_mfma_f32_16x16x32_bf16 v[18:21], v[180:183], v[238:241], v[62:65]
	v_mfma_f32_16x16x32_bf16 v[54:57], v[200:203], v[242:245], v[18:21]
	v_mfma_f32_16x16x32_bf16 v[18:21], v[204:207], v[238:241], v[192:195]
	v_mfma_f32_16x16x32_bf16 v[118:121], v[200:203], v[22:25], v[74:77]
	v_mfma_f32_16x16x32_bf16 v[50:53], v[234:237], v[242:245], v[18:21]
	s_setprio 0
	s_barrier
	s_mov_b32 m0, s88
	v_lshl_add_u64 v[26:27], v[208:209], 0, s[12:13]
	s_add_u32 s4, s44, 0x18080
	s_nop 0
	ds_read_b128 v[18:21], v178 offset:49152
	ds_read_b128 v[22:25], v178 offset:50176
	ds_read_b128 v[184:187], v178 offset:51200
	ds_read_b128 v[188:191], v178 offset:52224
	ds_read_b128 v[192:195], v178 offset:53248
	ds_read_b128 v[222:225], v178 offset:54272
	ds_read_b128 v[226:229], v178 offset:55296
	ds_read_b128 v[238:241], v178 offset:56320
	global_load_lds_dwordx4 v[26:27], off
	v_lshl_add_u64 v[26:27], v[210:211], 0, s[12:13]
	s_mov_b32 m0, s89
	s_addc_u32 s5, s45, 0
	global_load_lds_dwordx4 v[26:27], off
	v_lshl_add_u64 v[26:27], s[4:5], 0, v[166:167]
	s_mov_b32 m0, s28
	s_nop 0
	global_load_lds_dwordx4 v[26:27], off
	v_lshl_add_u64 v[26:27], s[4:5], 0, v[162:163]
	s_mov_b32 m0, s29
	s_nop 0
	global_load_lds_dwordx4 v[26:27], off
	v_lshl_add_u64 v[26:27], v[212:213], 0, s[12:13]
	s_mov_b32 m0, s90
	s_nop 0
	global_load_lds_dwordx4 v[26:27], off
	v_lshl_add_u64 v[26:27], v[246:247], 0, s[12:13]
	s_mov_b32 m0, s91
	s_nop 0
	global_load_lds_dwordx4 v[26:27], off
	s_waitcnt vmcnt(8)
	s_waitcnt lgkmcnt(0)
	s_barrier
	s_setprio 1
	s_waitcnt lgkmcnt(0)
	v_mfma_f32_16x16x32_bf16 v[2:5], v[10:13], v[18:21], v[2:5]
	v_mfma_f32_16x16x32_bf16 v[78:81], v[14:17], v[22:25], v[2:5]
	v_mfma_f32_16x16x32_bf16 v[2:5], v[34:37], v[18:21], v[6:9]
	v_mfma_f32_16x16x32_bf16 v[74:77], v[38:41], v[22:25], v[2:5]
	v_mfma_f32_16x16x32_bf16 v[2:5], v[10:13], v[184:187], v[146:149]
	v_mfma_f32_16x16x32_bf16 v[46:49], v[14:17], v[188:191], v[2:5]
	v_mfma_f32_16x16x32_bf16 v[2:5], v[34:37], v[184:187], v[150:153]
	v_mfma_f32_16x16x32_bf16 v[42:45], v[38:41], v[188:191], v[2:5]
	v_mfma_f32_16x16x32_bf16 v[2:5], v[10:13], v[192:195], v[154:157]
	v_mfma_f32_16x16x32_bf16 v[30:33], v[14:17], v[222:225], v[2:5]
	v_mfma_f32_16x16x32_bf16 v[2:5], v[34:37], v[192:195], v[158:161]
	v_mfma_f32_16x16x32_bf16 v[26:29], v[38:41], v[222:225], v[2:5]
	v_mfma_f32_16x16x32_bf16 v[2:5], v[10:13], v[226:229], v[130:133]
	v_mfma_f32_16x16x32_bf16 v[14:17], v[14:17], v[238:241], v[2:5]
	v_mfma_f32_16x16x32_bf16 v[2:5], v[34:37], v[226:229], v[134:137]
	v_mfma_f32_16x16x32_bf16 v[10:13], v[38:41], v[238:241], v[2:5]
	s_setprio 0
	s_setprio 1
	v_mfma_f32_16x16x32_bf16 v[2:5], v[180:183], v[18:21], v[138:141]
	v_mfma_f32_16x16x32_bf16 v[62:65], v[200:203], v[22:25], v[2:5]
	v_mfma_f32_16x16x32_bf16 v[2:5], v[204:207], v[18:21], v[142:145]
	v_mfma_f32_16x16x32_bf16 v[58:61], v[234:237], v[22:25], v[2:5]
	v_mfma_f32_16x16x32_bf16 v[2:5], v[180:183], v[184:187], v[214:217]
	v_mfma_f32_16x16x32_bf16 v[38:41], v[200:203], v[188:191], v[2:5]
	v_mfma_f32_16x16x32_bf16 v[2:5], v[204:207], v[184:187], v[218:221]
	v_mfma_f32_16x16x32_bf16 v[34:37], v[234:237], v[188:191], v[2:5]
	v_mfma_f32_16x16x32_bf16 v[2:5], v[180:183], v[192:195], v[230:233]
	v_mfma_f32_16x16x32_bf16 v[22:25], v[200:203], v[222:225], v[2:5]
	v_mfma_f32_16x16x32_bf16 v[2:5], v[204:207], v[192:195], v[196:199]
	v_mfma_f32_16x16x32_bf16 v[18:21], v[234:237], v[222:225], v[2:5]
	v_mfma_f32_16x16x32_bf16 v[2:5], v[180:183], v[226:229], v[170:173]
	v_mfma_f32_16x16x32_bf16 v[6:9], v[200:203], v[238:241], v[2:5]
	v_mfma_f32_16x16x32_bf16 v[2:5], v[204:207], v[226:229], v[174:177]
	v_mfma_f32_16x16x32_bf16 v[2:5], v[234:237], v[238:241], v[2:5]
	s_setprio 0
	s_barrier
	s_andn2_b64 vcc, exec, s[40:41]
	s_cbranch_vccnz .LBB0_390
	s_barrier

; #define PG8_STAGE(bufoff, gbase, voff) do { _Pragma("unroll") for (int _i = 0; _i < 2; ++_i) \
;         __builtin_amdgcn_global_load_lds((const unsigned*)((const char*)(gbase) + (voff)[_i]), (PG8_LAS unsigned*)(lds + (bufoff) + ldsw + _i * 8192), 16, 0, 0); } while (0)
; #define PG8_LDA(dst, b, h) do { _Pragma("unroll") for (int m = 0; m < 4; ++m) _Pragma("unroll") for (int k = 0; k < 2; ++k) dst[m][k] = *(const PG8_LAS bf16x8*)(lds + PG8_SA(b, h) + aoff + m * 2048 + k * 1024); } while (0)
; #define PG8_LDB(dst, b, h) do { _Pragma("unroll") for (int n = 0; n < 2; ++n) _Pragma("unroll") for (int k = 0; k < 2; ++k) dst[n][k] = *(const PG8_LAS bf16x8*)(lds + PG8_SB(b, h) + boff + n * 2048 + k * 1024); } while (0)
; #define PG8_MMA(ai, bj, At, Bt) do { __builtin_amdgcn_s_setprio(1); _Pragma("unroll") for (int m = 0; m < 4; ++m) _Pragma("unroll") for (int n = 0; n < 2; ++n) _Pragma("unroll") for (int k = 0; k < 2; ++k) \
;         acc[ai][bj][m][n] = __builtin_amdgcn_mfma_f32_16x16x32_bf16(Bt[n][k], At[m][k], acc[ai][bj][m][n], 0, 0, 0); __builtin_amdgcn_s_setprio(0); } while (0)
; #define PG8_WAIT_V(n) asm volatile("s_waitcnt vmcnt(" #n ")" ::: "memory")
; #define PG8_WAIT_L(n) asm volatile("s_waitcnt lgkmcnt(" #n ")" ::: "memory")
; #define PG8_BAR __builtin_amdgcn_s_barrier()
; #define PG8_SCHED __builtin_amdgcn_sched_barrier(0)
; template <class Epi, class Sched, bool ALIGN_EPI = false, bool SP2 = false>
; __device__ __forceinline__ void gemm_phase(PG8_LAS unsigned char* lds, const Gemm g, const Sched& S, const Epi& E, const int tid) {
;     ...
;             const bool last = (t == nt - 2);
;             const char* a1 = cA + (size_t)(t + 1) * kstep;
;             const char* a2 = last ? nA : cA + (size_t)(t + 2) * kstep; const char* b2 = last ? nB : cB + (size_t)(t + 2) * kstep;
;             const char* a3 = a2 + kstep; const char* b3 = b2 + kstep;
;             if (last && has_next) S.a_ready(nxt);
;             if constexpr (SP2) {
;             PG8_LDB(B0, 0, 0); PG8_LDB(B1, 0, 1); PG8_SCHED; PG8_LDA(At, 0, 0); PG8_STAGE(PG8_SA(1, 1), a1 + hstep, voffA);
;             PG8_WAIT_V(8); PG8_WAIT_L(0); PG8_BAR; PG8_MMA(0, 0, At, B0); PG8_MMA(0, 1, At, B1); PG8_BAR; PG8_SCHED;
;             PG8_LDA(At, 0, 1); PG8_STAGE(PG8_SB(0, 0), b2, voffB); PG8_STAGE(PG8_SB(0, 1), b2 + hstep, voffB); PG8_STAGE(PG8_SA(0, 0), a2, voffA);
.LBB0_499:
	v_or_b32_e32 v140, 0x10000, v145
	v_add_u32_e32 v146, 0x10400, v145
	v_add_u32_e32 v150, 0x10800, v145
	v_add_u32_e32 v154, 0x10c00, v145
	v_or_b32_e32 v158, 0x14000, v145
	v_add_u32_e32 v162, 0x14400, v145
	v_add_u32_e32 v166, 0x14800, v145
	v_add_u32_e32 v170, 0x14c00, v145
	ds_read_b128 v[140:143], v140
	ds_read_b128 v[146:149], v146
	ds_read_b128 v[150:153], v150
	ds_read_b128 v[154:157], v154
	ds_read_b128 v[158:161], v158
	ds_read_b128 v[162:165], v162
	ds_read_b128 v[166:169], v166
	ds_read_b128 v[170:173], v170
	s_add_u32 s88, s86, 0xfffc0080
	s_addc_u32 s89, s87, -1
	s_cmp_eq_u32 s96, 12
	s_cselect_b32 s91, s39, s89
	s_cselect_b32 s90, s43, s88
	s_cselect_b32 s89, s41, s85
	s_cselect_b32 s88, s50, s51
	v_lshl_add_u64 v[178:179], s[86:87], 0, v[136:137]
	s_add_i32 m0, s0, 0xc000
	ds_read_b128 v[174:177], v144
	ds_read_b128 v[184:187], v144 offset:1024
	ds_read_b128 v[188:191], v144 offset:2048
	ds_read_b128 v[192:195], v144 offset:3072
	ds_read_b128 v[196:199], v144 offset:4096
	ds_read_b128 v[200:203], v144 offset:5120
	ds_read_b128 v[204:207], v144 offset:6144
	ds_read_b128 v[214:217], v144 offset:7168
	global_load_lds_dwordx4 v[178:179], off
	v_lshl_add_u64 v[178:179], s[86:87], 0, v[138:139]
	s_add_i32 m0, s0, 0xe000
	s_nop 0
	global_load_lds_dwordx4 v[178:179], off
	s_waitcnt vmcnt(8)
	s_waitcnt lgkmcnt(0)
	s_barrier
	s_setprio 1
	s_waitcnt lgkmcnt(0)
	v_mfma_f32_16x16x32_bf16 v[126:129], v[140:143], v[174:177], v[126:129]
	v_mfma_f32_16x16x32_bf16 v[126:129], v[146:149], v[184:187], v[126:129]
	v_mfma_f32_16x16x32_bf16 v[122:125], v[150:153], v[174:177], v[122:125]
	v_mfma_f32_16x16x32_bf16 v[122:125], v[154:157], v[184:187], v[122:125]
	v_mfma_f32_16x16x32_bf16 v[114:117], v[140:143], v[188:191], v[114:117]
	v_mfma_f32_16x16x32_bf16 v[114:117], v[146:149], v[192:195], v[114:117]
	v_mfma_f32_16x16x32_bf16 v[106:109], v[150:153], v[188:191], v[106:109]
	v_mfma_f32_16x16x32_bf16 v[106:109], v[154:157], v[192:195], v[106:109]
	v_mfma_f32_16x16x32_bf16 v[98:101], v[140:143], v[196:199], v[98:101]
	v_mfma_f32_16x16x32_bf16 v[98:101], v[146:149], v[200:203], v[98:101]
	v_mfma_f32_16x16x32_bf16 v[90:93], v[150:153], v[196:199], v[90:93]
	v_mfma_f32_16x16x32_bf16 v[90:93], v[154:157], v[200:203], v[90:93]
	v_mfma_f32_16x16x32_bf16 v[82:85], v[140:143], v[204:207], v[82:85]
	v_mfma_f32_16x16x32_bf16 v[82:85], v[146:149], v[214:217], v[82:85]
	v_mfma_f32_16x16x32_bf16 v[74:77], v[150:153], v[204:207], v[74:77]
	v_mfma_f32_16x16x32_bf16 v[74:77], v[154:157], v[214:217], v[74:77]
	s_setprio 0
	s_setprio 1
	v_mfma_f32_16x16x32_bf16 v[118:121], v[158:161], v[174:177], v[118:121]
	v_mfma_f32_16x16x32_bf16 v[118:121], v[162:165], v[184:187], v[118:121]
	v_mfma_f32_16x16x32_bf16 v[110:113], v[166:169], v[174:177], v[110:113]
	v_mfma_f32_16x16x32_bf16 v[110:113], v[170:173], v[184:187], v[110:113]
	v_mfma_f32_16x16x32_bf16 v[102:105], v[158:161], v[188:191], v[102:105]
	v_mfma_f32_16x16x32_bf16 v[102:105], v[162:165], v[192:195], v[102:105]
	v_mfma_f32_16x16x32_bf16 v[94:97], v[166:169], v[188:191], v[94:97]
	v_mfma_f32_16x16x32_bf16 v[94:97], v[170:173], v[192:195], v[94:97]
	v_mfma_f32_16x16x32_bf16 v[86:89], v[158:161], v[196:199], v[86:89]
	v_mfma_f32_16x16x32_bf16 v[86:89], v[162:165], v[200:203], v[86:89]
	v_mfma_f32_16x16x32_bf16 v[78:81], v[166:169], v[196:199], v[78:81]
	v_mfma_f32_16x16x32_bf16 v[78:81], v[170:173], v[200:203], v[78:81]
	v_mfma_f32_16x16x32_bf16 v[70:73], v[158:161], v[204:207], v[70:73]
	v_mfma_f32_16x16x32_bf16 v[70:73], v[162:165], v[214:217], v[70:73]
	v_mfma_f32_16x16x32_bf16 v[66:69], v[166:169], v[204:207], v[66:69]
	v_mfma_f32_16x16x32_bf16 v[66:69], v[170:173], v[214:217], v[66:69]
	s_setprio 0
	s_barrier
	s_mov_b32 m0, s1
	v_lshl_add_u64 v[178:179], s[88:89], 0, v[0:1]
	s_add_u32 s92, s88, 0x40000
	ds_read_b128 v[174:177], v144 offset:16384
	ds_read_b128 v[184:187], v144 offset:17408
	ds_read_b128 v[188:191], v144 offset:18432
	ds_read_b128 v[192:195], v144 offset:19456
	ds_read_b128 v[196:199], v144 offset:20480
	ds_read_b128 v[200:203], v144 offset:21504
	ds_read_b128 v[204:207], v144 offset:22528
	ds_read_b128 v[214:217], v144 offset:23552
	global_load_lds_dwordx4 v[178:179], off
	v_lshl_add_u64 v[180:181], s[88:89], 0, v[134:135]
	s_mov_b32 m0, s2
	s_addc_u32 s93, s89, 0
	global_load_lds_dwordx4 v[180:181], off
	v_lshl_add_u64 v[182:183], s[92:93], 0, v[0:1]
	s_mov_b32 m0, s4
	v_lshl_add_u64 v[218:219], s[90:91], 0, v[132:133]
	global_load_lds_dwordx4 v[182:183], off
	v_lshl_add_u64 v[182:183], s[92:93], 0, v[134:135]
	s_mov_b32 m0, s5
	s_nop 0
	global_load_lds_dwordx4 v[182:183], off
	v_lshl_add_u64 v[182:183], s[90:91], 0, v[130:131]
	s_mov_b32 m0, s0
	s_nop 0
	global_load_lds_dwordx4 v[182:183], off
	s_mov_b32 m0, s6
	s_nop 0
	global_load_lds_dwordx4 v[218:219], off
	s_waitcnt vmcnt(8)
	s_waitcnt lgkmcnt(0)
	s_barrier
; #define PG8_STAGE(bufoff, gbase, voff) do { _Pragma("unroll") for (int _i = 0; _i < 2; ++_i) \
;         __builtin_amdgcn_global_load_lds((const unsigned*)((const char*)(gbase) + (voff)[_i]), (PG8_LAS unsigned*)(lds + (bufoff) + ldsw + _i * 8192), 16, 0, 0); } while (0)
; #define PG8_LDA(dst, b, h) do { _Pragma("unroll") for (int m = 0; m < 4; ++m) _Pragma("unroll") for (int k = 0; k < 2; ++k) dst[m][k] = *(const PG8_LAS bf16x8*)(lds + PG8_SA(b, h) + aoff + m * 2048 + k * 1024); } while (0)
; #define PG8_LDB(dst, b, h) do { _Pragma("unroll") for (int n = 0; n < 2; ++n) _Pragma("unroll") for (int k = 0; k < 2; ++k) dst[n][k] = *(const PG8_LAS bf16x8*)(lds + PG8_SB(b, h) + boff + n * 2048 + k * 1024); } while (0)
; #define PG8_MMA(ai, bj, At, Bt) do { __builtin_amdgcn_s_setprio(1); _Pragma("unroll") for (int m = 0; m < 4; ++m) _Pragma("unroll") for (int n = 0; n < 2; ++n) _Pragma("unroll") for (int k = 0; k < 2; ++k) \
;         acc[ai][bj][m][n] = __builtin_amdgcn_mfma_f32_16x16x32_bf16(Bt[n][k], At[m][k], acc[ai][bj][m][n], 0, 0, 0); __builtin_amdgcn_s_setprio(0); } while (0)
; #define PG8_WAIT_V(n) asm volatile("s_waitcnt vmcnt(" #n ")" ::: "memory")
; #define PG8_WAIT_L(n) asm volatile("s_waitcnt lgkmcnt(" #n ")" ::: "memory")
; #define PG8_BAR __builtin_amdgcn_s_barrier()
; #define PG8_SCHED __builtin_amdgcn_sched_barrier(0)
; template <class Epi, class Sched, bool ALIGN_EPI = false, bool SP2 = false>
; __device__ __forceinline__ void gemm_phase(PG8_LAS unsigned char* lds, const Gemm g, const Sched& S, const Epi& E, const int tid) {
;     ...
;             PG8_WAIT_V(8); PG8_WAIT_L(0); PG8_BAR; PG8_MMA(1, 0, At, B0); PG8_MMA(1, 1, At, B1); PG8_BAR; PG8_SCHED;
;             PG8_LDB(B0, 1, 0); PG8_LDB(B1, 1, 1); PG8_SCHED; PG8_LDA(At, 1, 0); PG8_STAGE(PG8_SA(0, 1), a2 + hstep, voffA);
;             PG8_WAIT_V(8); PG8_WAIT_L(0); PG8_BAR; PG8_MMA(0, 0, At, B0); PG8_MMA(0, 1, At, B1); PG8_BAR; PG8_SCHED;
	s_setprio 1
	s_waitcnt lgkmcnt(0)
	v_mfma_f32_16x16x32_bf16 v[62:65], v[140:143], v[174:177], v[62:65]
	v_mfma_f32_16x16x32_bf16 v[62:65], v[146:149], v[184:187], v[62:65]
	v_mfma_f32_16x16x32_bf16 v[58:61], v[150:153], v[174:177], v[58:61]
	v_mfma_f32_16x16x32_bf16 v[58:61], v[154:157], v[184:187], v[58:61]
	v_mfma_f32_16x16x32_bf16 v[50:53], v[140:143], v[188:191], v[50:53]
	v_mfma_f32_16x16x32_bf16 v[50:53], v[146:149], v[192:195], v[50:53]
	v_mfma_f32_16x16x32_bf16 v[42:45], v[150:153], v[188:191], v[42:45]
	v_mfma_f32_16x16x32_bf16 v[42:45], v[154:157], v[192:195], v[42:45]
	v_mfma_f32_16x16x32_bf16 v[34:37], v[140:143], v[196:199], v[34:37]
	v_mfma_f32_16x16x32_bf16 v[34:37], v[146:149], v[200:203], v[34:37]
	v_mfma_f32_16x16x32_bf16 v[26:29], v[150:153], v[196:199], v[26:29]
	v_mfma_f32_16x16x32_bf16 v[26:29], v[154:157], v[200:203], v[26:29]
	v_mfma_f32_16x16x32_bf16 v[18:21], v[140:143], v[204:207], v[18:21]
	v_mfma_f32_16x16x32_bf16 v[18:21], v[146:149], v[214:217], v[18:21]
	v_mfma_f32_16x16x32_bf16 v[10:13], v[150:153], v[204:207], v[10:13]
	v_mfma_f32_16x16x32_bf16 v[10:13], v[154:157], v[214:217], v[10:13]
	s_setprio 0
	s_setprio 1
	v_mfma_f32_16x16x32_bf16 v[54:57], v[158:161], v[174:177], v[54:57]
	v_mfma_f32_16x16x32_bf16 v[54:57], v[162:165], v[184:187], v[54:57]
	v_mfma_f32_16x16x32_bf16 v[46:49], v[166:169], v[174:177], v[46:49]
	v_mfma_f32_16x16x32_bf16 v[46:49], v[170:173], v[184:187], v[46:49]
	v_mfma_f32_16x16x32_bf16 v[38:41], v[158:161], v[188:191], v[38:41]
	v_mfma_f32_16x16x32_bf16 v[38:41], v[162:165], v[192:195], v[38:41]
	v_mfma_f32_16x16x32_bf16 v[30:33], v[166:169], v[188:191], v[30:33]
	v_mfma_f32_16x16x32_bf16 v[30:33], v[170:173], v[192:195], v[30:33]
	v_mfma_f32_16x16x32_bf16 v[22:25], v[158:161], v[196:199], v[22:25]
	v_mfma_f32_16x16x32_bf16 v[22:25], v[162:165], v[200:203], v[22:25]
	v_mfma_f32_16x16x32_bf16 v[14:17], v[166:169], v[196:199], v[14:17]
	v_mfma_f32_16x16x32_bf16 v[14:17], v[170:173], v[200:203], v[14:17]
	v_mfma_f32_16x16x32_bf16 v[6:9], v[158:161], v[204:207], v[6:9]
	v_mfma_f32_16x16x32_bf16 v[6:9], v[162:165], v[214:217], v[6:9]
	v_mfma_f32_16x16x32_bf16 v[2:5], v[166:169], v[204:207], v[2:5]
	v_mfma_f32_16x16x32_bf16 v[2:5], v[170:173], v[214:217], v[2:5]
	s_setprio 0
	s_barrier
	v_or_b32_e32 v140, 0x18000, v145
	v_add_u32_e32 v146, 0x18400, v145
	v_add_u32_e32 v150, 0x18800, v145
	v_add_u32_e32 v154, 0x18c00, v145
	v_or_b32_e32 v158, 0x1c000, v145
	v_add_u32_e32 v162, 0x1c400, v145
	v_add_u32_e32 v166, 0x1c800, v145
	v_add_u32_e32 v170, 0x1cc00, v145
	ds_read_b128 v[140:143], v140
	ds_read_b128 v[146:149], v146
	ds_read_b128 v[150:153], v150
	ds_read_b128 v[154:157], v154
	ds_read_b128 v[158:161], v158
	ds_read_b128 v[162:165], v162
	ds_read_b128 v[166:169], v166
	ds_read_b128 v[170:173], v170
	s_add_u32 s90, s90, 0x40000
	s_addc_u32 s91, s91, 0
	s_mov_b32 m0, s8
	v_lshl_add_u64 v[220:221], s[90:91], 0, v[130:131]
	ds_read_b128 v[174:177], v144 offset:32768
	ds_read_b128 v[184:187], v144 offset:33792
	ds_read_b128 v[188:191], v144 offset:34816
	ds_read_b128 v[192:195], v144 offset:35840
	ds_read_b128 v[196:199], v144 offset:36864
	ds_read_b128 v[200:203], v144 offset:37888
	ds_read_b128 v[204:207], v144 offset:38912
	ds_read_b128 v[214:217], v144 offset:39936
	global_load_lds_dwordx4 v[220:221], off
	v_lshl_add_u64 v[220:221], s[90:91], 0, v[132:133]
	s_mov_b32 m0, s9
	s_nop 0
	global_load_lds_dwordx4 v[220:221], off
	s_waitcnt vmcnt(8)
	s_waitcnt lgkmcnt(0)
	s_barrier
	s_setprio 1
	s_waitcnt lgkmcnt(0)
	v_mfma_f32_16x16x32_bf16 v[126:129], v[140:143], v[174:177], v[126:129]
	v_mfma_f32_16x16x32_bf16 v[126:129], v[146:149], v[184:187], v[126:129]
	v_mfma_f32_16x16x32_bf16 v[122:125], v[150:153], v[174:177], v[122:125]
	v_mfma_f32_16x16x32_bf16 v[122:125], v[154:157], v[184:187], v[122:125]
	v_mfma_f32_16x16x32_bf16 v[114:117], v[140:143], v[188:191], v[114:117]
	v_mfma_f32_16x16x32_bf16 v[114:117], v[146:149], v[192:195], v[114:117]
	v_mfma_f32_16x16x32_bf16 v[106:109], v[150:153], v[188:191], v[106:109]
	v_mfma_f32_16x16x32_bf16 v[106:109], v[154:157], v[192:195], v[106:109]
	v_mfma_f32_16x16x32_bf16 v[98:101], v[140:143], v[196:199], v[98:101]
	v_mfma_f32_16x16x32_bf16 v[98:101], v[146:149], v[200:203], v[98:101]
	v_mfma_f32_16x16x32_bf16 v[90:93], v[150:153], v[196:199], v[90:93]
	v_mfma_f32_16x16x32_bf16 v[90:93], v[154:157], v[200:203], v[90:93]
	v_mfma_f32_16x16x32_bf16 v[82:85], v[140:143], v[204:207], v[82:85]
	v_mfma_f32_16x16x32_bf16 v[82:85], v[146:149], v[214:217], v[82:85]
	v_mfma_f32_16x16x32_bf16 v[74:77], v[150:153], v[204:207], v[74:77]
	v_mfma_f32_16x16x32_bf16 v[74:77], v[154:157], v[214:217], v[74:77]
	s_setprio 0
	s_setprio 1
	v_mfma_f32_16x16x32_bf16 v[118:121], v[158:161], v[174:177], v[118:121]
	v_mfma_f32_16x16x32_bf16 v[118:121], v[162:165], v[184:187], v[118:121]
	v_mfma_f32_16x16x32_bf16 v[110:113], v[166:169], v[174:177], v[110:113]
	v_mfma_f32_16x16x32_bf16 v[110:113], v[170:173], v[184:187], v[110:113]
	v_mfma_f32_16x16x32_bf16 v[102:105], v[158:161], v[188:191], v[102:105]
	v_mfma_f32_16x16x32_bf16 v[102:105], v[162:165], v[192:195], v[102:105]
	v_mfma_f32_16x16x32_bf16 v[94:97], v[166:169], v[188:191], v[94:97]
	v_mfma_f32_16x16x32_bf16 v[94:97], v[170:173], v[192:195], v[94:97]
	v_mfma_f32_16x16x32_bf16 v[86:89], v[158:161], v[196:199], v[86:89]
	v_mfma_f32_16x16x32_bf16 v[86:89], v[162:165], v[200:203], v[86:89]
	v_mfma_f32_16x16x32_bf16 v[78:81], v[166:169], v[196:199], v[78:81]
	v_mfma_f32_16x16x32_bf16 v[78:81], v[170:173], v[200:203], v[78:81]
	v_mfma_f32_16x16x32_bf16 v[70:73], v[158:161], v[204:207], v[70:73]
	v_mfma_f32_16x16x32_bf16 v[70:73], v[162:165], v[214:217], v[70:73]
	v_mfma_f32_16x16x32_bf16 v[66:69], v[166:169], v[204:207], v[66:69]
	v_mfma_f32_16x16x32_bf16 v[66:69], v[170:173], v[214:217], v[66:69]
	s_setprio 0
	s_barrier
; #define PG8_STAGE(bufoff, gbase, voff) do { _Pragma("unroll") for (int _i = 0; _i < 2; ++_i) \
;         __builtin_amdgcn_global_load_lds((const unsigned*)((const char*)(gbase) + (voff)[_i]), (PG8_LAS unsigned*)(lds + (bufoff) + ldsw + _i * 8192), 16, 0, 0); } while (0)
; #define PG8_LDA(dst, b, h) do { _Pragma("unroll") for (int m = 0; m < 4; ++m) _Pragma("unroll") for (int k = 0; k < 2; ++k) dst[m][k] = *(const PG8_LAS bf16x8*)(lds + PG8_SA(b, h) + aoff + m * 2048 + k * 1024); } while (0)
; #define PG8_MMA(ai, bj, At, Bt) do { __builtin_amdgcn_s_setprio(1); _Pragma("unroll") for (int m = 0; m < 4; ++m) _Pragma("unroll") for (int n = 0; n < 2; ++n) _Pragma("unroll") for (int k = 0; k < 2; ++k) \
;         acc[ai][bj][m][n] = __builtin_amdgcn_mfma_f32_16x16x32_bf16(Bt[n][k], At[m][k], acc[ai][bj][m][n], 0, 0, 0); __builtin_amdgcn_s_setprio(0); } while (0)
; #define PG8_WAIT_V(n) asm volatile("s_waitcnt vmcnt(" #n ")" ::: "memory")
; #define PG8_WAIT_L(n) asm volatile("s_waitcnt lgkmcnt(" #n ")" ::: "memory")
; #define PG8_BAR __builtin_amdgcn_s_barrier()
; #define PG8_SCHED __builtin_amdgcn_sched_barrier(0)
; template <class Epi, class Sched, bool ALIGN_EPI = false, bool SP2 = false>
; __device__ __forceinline__ void gemm_phase(PG8_LAS unsigned char* lds, const Gemm g, const Sched& S, const Epi& E, const int tid) {
;     ...
;         for (int t = 0; t < nt; t += 2) {
;     ...
;             PG8_LDA(At, 1, 1); PG8_STAGE(PG8_SB(1, 0), b3, voffB); PG8_STAGE(PG8_SB(1, 1), b3 + hstep, voffB); PG8_STAGE(PG8_SA(1, 0), a3, voffA);
;             PG8_WAIT_V(8); PG8_WAIT_L(0); PG8_BAR; PG8_MMA(1, 0, At, B0); PG8_MMA(1, 1, At, B1); PG8_BAR; PG8_SCHED;
	s_mov_b32 m0, s17
	v_lshl_add_u64 v[178:179], v[178:179], 0, s[12:13]
	s_add_u32 s88, s88, 0x40080
	ds_read_b128 v[174:177], v144 offset:49152
	ds_read_b128 v[184:187], v144 offset:50176
	ds_read_b128 v[188:191], v144 offset:51200
	ds_read_b128 v[192:195], v144 offset:52224
	ds_read_b128 v[196:199], v144 offset:53248
	ds_read_b128 v[200:203], v144 offset:54272
	ds_read_b128 v[204:207], v144 offset:55296
	ds_read_b128 v[214:217], v144 offset:56320
	global_load_lds_dwordx4 v[178:179], off
	v_lshl_add_u64 v[178:179], v[180:181], 0, s[12:13]
	s_mov_b32 m0, s20
	s_addc_u32 s89, s89, 0
	global_load_lds_dwordx4 v[178:179], off
	v_lshl_add_u64 v[178:179], s[88:89], 0, v[0:1]
	s_mov_b32 m0, s26
	s_nop 0
	global_load_lds_dwordx4 v[178:179], off
	v_lshl_add_u64 v[178:179], s[88:89], 0, v[134:135]
	s_mov_b32 m0, s27
	s_nop 0
	global_load_lds_dwordx4 v[178:179], off
	v_lshl_add_u64 v[178:179], v[182:183], 0, s[12:13]
	s_mov_b32 m0, s21
	s_nop 0
	global_load_lds_dwordx4 v[178:179], off
	v_lshl_add_u64 v[178:179], v[218:219], 0, s[12:13]
	s_mov_b32 m0, s24
	s_nop 0
	global_load_lds_dwordx4 v[178:179], off
	s_waitcnt vmcnt(8)
	s_waitcnt lgkmcnt(0)
	s_barrier
	s_setprio 1
	s_waitcnt lgkmcnt(0)
	v_mfma_f32_16x16x32_bf16 v[62:65], v[140:143], v[174:177], v[62:65]
	v_mfma_f32_16x16x32_bf16 v[62:65], v[146:149], v[184:187], v[62:65]
	v_mfma_f32_16x16x32_bf16 v[58:61], v[150:153], v[174:177], v[58:61]
	v_mfma_f32_16x16x32_bf16 v[58:61], v[154:157], v[184:187], v[58:61]
	v_mfma_f32_16x16x32_bf16 v[50:53], v[140:143], v[188:191], v[50:53]
	v_mfma_f32_16x16x32_bf16 v[50:53], v[146:149], v[192:195], v[50:53]
	v_mfma_f32_16x16x32_bf16 v[42:45], v[150:153], v[188:191], v[42:45]
	v_mfma_f32_16x16x32_bf16 v[42:45], v[154:157], v[192:195], v[42:45]
	v_mfma_f32_16x16x32_bf16 v[34:37], v[140:143], v[196:199], v[34:37]
	v_mfma_f32_16x16x32_bf16 v[34:37], v[146:149], v[200:203], v[34:37]
	v_mfma_f32_16x16x32_bf16 v[26:29], v[150:153], v[196:199], v[26:29]
	v_mfma_f32_16x16x32_bf16 v[26:29], v[154:157], v[200:203], v[26:29]
	v_mfma_f32_16x16x32_bf16 v[18:21], v[140:143], v[204:207], v[18:21]
	v_mfma_f32_16x16x32_bf16 v[18:21], v[146:149], v[214:217], v[18:21]
	v_mfma_f32_16x16x32_bf16 v[10:13], v[150:153], v[204:207], v[10:13]
	v_mfma_f32_16x16x32_bf16 v[10:13], v[154:157], v[214:217], v[10:13]
	s_setprio 0
	s_setprio 1
	v_mfma_f32_16x16x32_bf16 v[54:57], v[158:161], v[174:177], v[54:57]
	v_mfma_f32_16x16x32_bf16 v[54:57], v[162:165], v[184:187], v[54:57]
	v_mfma_f32_16x16x32_bf16 v[46:49], v[166:169], v[174:177], v[46:49]
	v_mfma_f32_16x16x32_bf16 v[46:49], v[170:173], v[184:187], v[46:49]
	v_mfma_f32_16x16x32_bf16 v[38:41], v[158:161], v[188:191], v[38:41]
	v_mfma_f32_16x16x32_bf16 v[38:41], v[162:165], v[192:195], v[38:41]
	v_mfma_f32_16x16x32_bf16 v[30:33], v[166:169], v[188:191], v[30:33]
	v_mfma_f32_16x16x32_bf16 v[30:33], v[170:173], v[192:195], v[30:33]
	v_mfma_f32_16x16x32_bf16 v[22:25], v[158:161], v[196:199], v[22:25]
	v_mfma_f32_16x16x32_bf16 v[22:25], v[162:165], v[200:203], v[22:25]
	v_mfma_f32_16x16x32_bf16 v[14:17], v[166:169], v[196:199], v[14:17]
	v_mfma_f32_16x16x32_bf16 v[14:17], v[170:173], v[200:203], v[14:17]
	v_mfma_f32_16x16x32_bf16 v[6:9], v[158:161], v[204:207], v[6:9]
	v_mfma_f32_16x16x32_bf16 v[6:9], v[162:165], v[214:217], v[6:9]
	v_mfma_f32_16x16x32_bf16 v[2:5], v[166:169], v[204:207], v[2:5]
	v_mfma_f32_16x16x32_bf16 v[2:5], v[170:173], v[214:217], v[2:5]
	s_setprio 0
	s_barrier
	s_add_i32 s96, s96, 2
	s_add_u32 s86, s86, 0x100
	s_addc_u32 s87, s87, 0
	s_add_u32 s51, s51, 0x100
	s_addc_u32 s85, s85, 0
	s_cmp_gt_u32 s96, 13
	s_cbranch_scc0 .LBB0_499
	s_and_b64 vcc, exec, s[14:15]
	s_cbranch_vccz .LBB0_502
	s_barrier

; #define PG8_STAGE(bufoff, gbase, voff) do { _Pragma("unroll") for (int _i = 0; _i < 2; ++_i) \
;         __builtin_amdgcn_global_load_lds((const unsigned*)((const char*)(gbase) + (voff)[_i]), (PG8_LAS unsigned*)(lds + (bufoff) + ldsw + _i * 8192), 16, 0, 0); } while (0)
; #define PG8_LDA(dst, b, h) do { _Pragma("unroll") for (int m = 0; m < 4; ++m) _Pragma("unroll") for (int k = 0; k < 2; ++k) dst[m][k] = *(const PG8_LAS bf16x8*)(lds + PG8_SA(b, h) + aoff + m * 2048 + k * 1024); } while (0)
; #define PG8_LDB(dst, b, h) do { _Pragma("unroll") for (int n = 0; n < 2; ++n) _Pragma("unroll") for (int k = 0; k < 2; ++k) dst[n][k] = *(const PG8_LAS bf16x8*)(lds + PG8_SB(b, h) + boff + n * 2048 + k * 1024); } while (0)
; #define PG8_MMA(ai, bj, At, Bt) do { __builtin_amdgcn_s_setprio(1); _Pragma("unroll") for (int m = 0; m < 4; ++m) _Pragma("unroll") for (int n = 0; n < 2; ++n) _Pragma("unroll") for (int k = 0; k < 2; ++k) \
;         acc[ai][bj][m][n] = __builtin_amdgcn_mfma_f32_16x16x32_bf16(Bt[n][k], At[m][k], acc[ai][bj][m][n], 0, 0, 0); __builtin_amdgcn_s_setprio(0); } while (0)
; #define PG8_WAIT_V(n) asm volatile("s_waitcnt vmcnt(" #n ")" ::: "memory")
; #define PG8_WAIT_L(n) asm volatile("s_waitcnt lgkmcnt(" #n ")" ::: "memory")
; #define PG8_BAR __builtin_amdgcn_s_barrier()
; #define PG8_SCHED __builtin_amdgcn_sched_barrier(0)
; template <class Epi, class Sched, bool ALIGN_EPI = false, bool SP2 = false>
; __device__ __forceinline__ void gemm_phase(PG8_LAS unsigned char* lds, const Gemm g, const Sched& S, const Epi& E, const int tid) {
;     ...
;             const bool last = (t == nt - 2);
;             const char* a1 = cA + (size_t)(t + 1) * kstep;
;             const char* a2 = last ? nA : cA + (size_t)(t + 2) * kstep; const char* b2 = last ? nB : cB + (size_t)(t + 2) * kstep;
;             const char* a3 = a2 + kstep; const char* b3 = b2 + kstep;
;             if (last && has_next) S.a_ready(nxt);
;             if constexpr (SP2) {
;             PG8_LDB(B0, 0, 0); PG8_LDB(B1, 0, 1); PG8_SCHED; PG8_LDA(At, 0, 0); PG8_STAGE(PG8_SA(1, 1), a1 + hstep, voffA);
;             PG8_WAIT_V(8); PG8_WAIT_L(0); PG8_BAR; PG8_MMA(0, 0, At, B0); PG8_MMA(0, 1, At, B1); PG8_BAR; PG8_SCHED;
;             PG8_LDA(At, 0, 1); PG8_STAGE(PG8_SB(0, 0), b2, voffB); PG8_STAGE(PG8_SB(0, 1), b2 + hstep, voffB); PG8_STAGE(PG8_SA(0, 0), a2, voffA);
.LBB0_684:
	v_or_b32_e32 v130, 0x10000, v177
	v_add_u32_e32 v134, 0x10400, v177
	v_add_u32_e32 v138, 0x10800, v177
	v_add_u32_e32 v142, 0x10c00, v177
	v_or_b32_e32 v146, 0x14000, v177
	v_add_u32_e32 v157, 0x14400, v177
	ds_read_b128 v[130:133], v130
	ds_read_b128 v[134:137], v134
	ds_read_b128 v[138:141], v138
	ds_read_b128 v[142:145], v142
	ds_read_b128 v[146:149], v146
	ds_read_b128 v[164:167], v157
	v_add_u32_e32 v157, 0x14800, v177
	v_add_u32_e32 v172, 0x14c00, v177
	s_add_i32 s92, s88, 2
	ds_read_b128 v[168:171], v157
	ds_read_b128 v[172:175], v172
	s_add_u32 s93, s86, 0x80
	s_addc_u32 s89, s87, 0
	s_cmp_eq_u32 s20, s88
	s_cselect_b32 s88, s38, s93
	s_cselect_b32 s89, s39, s89
	s_cselect_b32 s95, s85, vcc_hi
	s_cselect_b32 s94, s84, vcc_lo
	v_lshl_add_u64 v[178:179], s[86:87], 0, v[160:161]
	s_add_i32 m0, s17, 0xc000
	ds_read_b128 v[184:187], v176
	ds_read_b128 v[188:191], v176 offset:1024
	ds_read_b128 v[192:195], v176 offset:2048
	ds_read_b128 v[196:199], v176 offset:3072
	ds_read_b128 v[200:203], v176 offset:4096
	ds_read_b128 v[204:207], v176 offset:5120
	ds_read_b128 v[214:217], v176 offset:6144
	ds_read_b128 v[218:221], v176 offset:7168
	global_load_lds_dwordx4 v[178:179], off
	v_lshl_add_u64 v[178:179], s[86:87], 0, v[162:163]
	s_add_i32 m0, s17, 0xe000
	s_nop 0
	global_load_lds_dwordx4 v[178:179], off
	s_waitcnt vmcnt(8)
	s_waitcnt lgkmcnt(0)
	s_barrier
	s_setprio 1
	s_waitcnt lgkmcnt(0)
	v_mfma_f32_16x16x32_bf16 v[126:129], v[130:133], v[184:187], v[126:129]
	v_mfma_f32_16x16x32_bf16 v[126:129], v[134:137], v[188:191], v[126:129]
	v_mfma_f32_16x16x32_bf16 v[122:125], v[138:141], v[184:187], v[122:125]
	v_mfma_f32_16x16x32_bf16 v[122:125], v[142:145], v[188:191], v[122:125]
	v_mfma_f32_16x16x32_bf16 v[110:113], v[130:133], v[192:195], v[110:113]
	v_mfma_f32_16x16x32_bf16 v[110:113], v[134:137], v[196:199], v[110:113]
	v_mfma_f32_16x16x32_bf16 v[106:109], v[138:141], v[192:195], v[106:109]
	v_mfma_f32_16x16x32_bf16 v[106:109], v[142:145], v[196:199], v[106:109]
	v_mfma_f32_16x16x32_bf16 v[94:97], v[130:133], v[200:203], v[94:97]
	v_mfma_f32_16x16x32_bf16 v[94:97], v[134:137], v[204:207], v[94:97]
	v_mfma_f32_16x16x32_bf16 v[90:93], v[138:141], v[200:203], v[90:93]
	v_mfma_f32_16x16x32_bf16 v[90:93], v[142:145], v[204:207], v[90:93]
	v_mfma_f32_16x16x32_bf16 v[78:81], v[130:133], v[214:217], v[78:81]
	v_mfma_f32_16x16x32_bf16 v[78:81], v[134:137], v[218:221], v[78:81]
	v_mfma_f32_16x16x32_bf16 v[74:77], v[138:141], v[214:217], v[74:77]
	v_mfma_f32_16x16x32_bf16 v[74:77], v[142:145], v[218:221], v[74:77]
	s_setprio 0
	s_setprio 1
	v_mfma_f32_16x16x32_bf16 v[118:121], v[146:149], v[184:187], v[118:121]
	v_mfma_f32_16x16x32_bf16 v[118:121], v[164:167], v[188:191], v[118:121]
	v_mfma_f32_16x16x32_bf16 v[114:117], v[168:171], v[184:187], v[114:117]
	v_mfma_f32_16x16x32_bf16 v[114:117], v[172:175], v[188:191], v[114:117]
	v_mfma_f32_16x16x32_bf16 v[102:105], v[146:149], v[192:195], v[102:105]
	v_mfma_f32_16x16x32_bf16 v[102:105], v[164:167], v[196:199], v[102:105]
	v_mfma_f32_16x16x32_bf16 v[98:101], v[168:171], v[192:195], v[98:101]
	v_mfma_f32_16x16x32_bf16 v[98:101], v[172:175], v[196:199], v[98:101]
	v_mfma_f32_16x16x32_bf16 v[86:89], v[146:149], v[200:203], v[86:89]
	v_mfma_f32_16x16x32_bf16 v[86:89], v[164:167], v[204:207], v[86:89]
	v_mfma_f32_16x16x32_bf16 v[82:85], v[168:171], v[200:203], v[82:85]
	v_mfma_f32_16x16x32_bf16 v[82:85], v[172:175], v[204:207], v[82:85]
	v_mfma_f32_16x16x32_bf16 v[70:73], v[146:149], v[214:217], v[70:73]
	v_mfma_f32_16x16x32_bf16 v[70:73], v[164:167], v[218:221], v[70:73]
	v_mfma_f32_16x16x32_bf16 v[66:69], v[168:171], v[214:217], v[66:69]
	v_mfma_f32_16x16x32_bf16 v[66:69], v[172:175], v[218:221], v[66:69]
	s_setprio 0
	s_barrier
	s_mov_b32 m0, s26
	v_lshl_add_u64 v[178:179], s[94:95], 0, v[0:1]
	v_lshl_add_u64 v[180:181], s[94:95], 0, v[150:151]
	s_add_u32 s94, s94, s40
	ds_read_b128 v[184:187], v176 offset:16384
	ds_read_b128 v[188:191], v176 offset:17408
	ds_read_b128 v[192:195], v176 offset:18432
	ds_read_b128 v[196:199], v176 offset:19456
	ds_read_b128 v[200:203], v176 offset:20480
	ds_read_b128 v[204:207], v176 offset:21504
	ds_read_b128 v[214:217], v176 offset:22528
	ds_read_b128 v[218:221], v176 offset:23552
	global_load_lds_dwordx4 v[178:179], off
	s_mov_b32 m0, s27
	s_addc_u32 s95, s95, 0
	global_load_lds_dwordx4 v[180:181], off
	v_lshl_add_u64 v[182:183], s[94:95], 0, v[0:1]
	s_mov_b32 m0, s34
	v_lshl_add_u64 v[222:223], s[94:95], 0, v[150:151]
	global_load_lds_dwordx4 v[182:183], off
	s_mov_b32 m0, s35
	v_lshl_add_u64 v[224:225], s[88:89], 0, v[154:155]
	global_load_lds_dwordx4 v[222:223], off
	s_mov_b32 m0, s17
	v_lshl_add_u64 v[226:227], s[88:89], 0, v[152:153]
	global_load_lds_dwordx4 v[224:225], off
	s_mov_b32 m0, s50
	s_nop 0
	global_load_lds_dwordx4 v[226:227], off
	s_waitcnt vmcnt(8)
	s_waitcnt lgkmcnt(0)
	s_barrier
; #define PG8_STAGE(bufoff, gbase, voff) do { _Pragma("unroll") for (int _i = 0; _i < 2; ++_i) \
;         __builtin_amdgcn_global_load_lds((const unsigned*)((const char*)(gbase) + (voff)[_i]), (PG8_LAS unsigned*)(lds + (bufoff) + ldsw + _i * 8192), 16, 0, 0); } while (0)
; #define PG8_LDA(dst, b, h) do { _Pragma("unroll") for (int m = 0; m < 4; ++m) _Pragma("unroll") for (int k = 0; k < 2; ++k) dst[m][k] = *(const PG8_LAS bf16x8*)(lds + PG8_SA(b, h) + aoff + m * 2048 + k * 1024); } while (0)
; #define PG8_LDB(dst, b, h) do { _Pragma("unroll") for (int n = 0; n < 2; ++n) _Pragma("unroll") for (int k = 0; k < 2; ++k) dst[n][k] = *(const PG8_LAS bf16x8*)(lds + PG8_SB(b, h) + boff + n * 2048 + k * 1024); } while (0)
; #define PG8_MMA(ai, bj, At, Bt) do { __builtin_amdgcn_s_setprio(1); _Pragma("unroll") for (int m = 0; m < 4; ++m) _Pragma("unroll") for (int n = 0; n < 2; ++n) _Pragma("unroll") for (int k = 0; k < 2; ++k) \
;         acc[ai][bj][m][n] = __builtin_amdgcn_mfma_f32_16x16x32_bf16(Bt[n][k], At[m][k], acc[ai][bj][m][n], 0, 0, 0); __builtin_amdgcn_s_setprio(0); } while (0)
; #define PG8_WAIT_V(n) asm volatile("s_waitcnt vmcnt(" #n ")" ::: "memory")
; #define PG8_WAIT_L(n) asm volatile("s_waitcnt lgkmcnt(" #n ")" ::: "memory")
; #define PG8_BAR __builtin_amdgcn_s_barrier()
; #define PG8_SCHED __builtin_amdgcn_sched_barrier(0)
; template <class Epi, class Sched, bool ALIGN_EPI = false, bool SP2 = false>
; __device__ __forceinline__ void gemm_phase(PG8_LAS unsigned char* lds, const Gemm g, const Sched& S, const Epi& E, const int tid) {
;     ...
;             PG8_WAIT_V(8); PG8_WAIT_L(0); PG8_BAR; PG8_MMA(1, 0, At, B0); PG8_MMA(1, 1, At, B1); PG8_BAR; PG8_SCHED;
;             PG8_LDB(B0, 1, 0); PG8_LDB(B1, 1, 1); PG8_SCHED; PG8_LDA(At, 1, 0); PG8_STAGE(PG8_SA(0, 1), a2 + hstep, voffA);
;             PG8_WAIT_V(8); PG8_WAIT_L(0); PG8_BAR; PG8_MMA(0, 0, At, B0); PG8_MMA(0, 1, At, B1); PG8_BAR; PG8_SCHED;
	s_setprio 1
	s_waitcnt lgkmcnt(0)
	v_mfma_f32_16x16x32_bf16 v[62:65], v[130:133], v[184:187], v[62:65]
	v_mfma_f32_16x16x32_bf16 v[62:65], v[134:137], v[188:191], v[62:65]
	v_mfma_f32_16x16x32_bf16 v[58:61], v[138:141], v[184:187], v[58:61]
	v_mfma_f32_16x16x32_bf16 v[58:61], v[142:145], v[188:191], v[58:61]
	v_mfma_f32_16x16x32_bf16 v[46:49], v[130:133], v[192:195], v[46:49]
	v_mfma_f32_16x16x32_bf16 v[46:49], v[134:137], v[196:199], v[46:49]
	v_mfma_f32_16x16x32_bf16 v[42:45], v[138:141], v[192:195], v[42:45]
	v_mfma_f32_16x16x32_bf16 v[42:45], v[142:145], v[196:199], v[42:45]
	v_mfma_f32_16x16x32_bf16 v[30:33], v[130:133], v[200:203], v[30:33]
	v_mfma_f32_16x16x32_bf16 v[30:33], v[134:137], v[204:207], v[30:33]
	v_mfma_f32_16x16x32_bf16 v[26:29], v[138:141], v[200:203], v[26:29]
	v_mfma_f32_16x16x32_bf16 v[26:29], v[142:145], v[204:207], v[26:29]
	v_mfma_f32_16x16x32_bf16 v[14:17], v[130:133], v[214:217], v[14:17]
	v_mfma_f32_16x16x32_bf16 v[14:17], v[134:137], v[218:221], v[14:17]
	v_mfma_f32_16x16x32_bf16 v[10:13], v[138:141], v[214:217], v[10:13]
	v_mfma_f32_16x16x32_bf16 v[10:13], v[142:145], v[218:221], v[10:13]
	s_setprio 0
	s_setprio 1
	v_mfma_f32_16x16x32_bf16 v[54:57], v[146:149], v[184:187], v[54:57]
	v_mfma_f32_16x16x32_bf16 v[54:57], v[164:167], v[188:191], v[54:57]
	v_mfma_f32_16x16x32_bf16 v[50:53], v[168:171], v[184:187], v[50:53]
	v_mfma_f32_16x16x32_bf16 v[50:53], v[172:175], v[188:191], v[50:53]
	v_mfma_f32_16x16x32_bf16 v[38:41], v[146:149], v[192:195], v[38:41]
	v_mfma_f32_16x16x32_bf16 v[38:41], v[164:167], v[196:199], v[38:41]
	v_mfma_f32_16x16x32_bf16 v[34:37], v[168:171], v[192:195], v[34:37]
	v_mfma_f32_16x16x32_bf16 v[34:37], v[172:175], v[196:199], v[34:37]
	v_mfma_f32_16x16x32_bf16 v[22:25], v[146:149], v[200:203], v[22:25]
	v_mfma_f32_16x16x32_bf16 v[22:25], v[164:167], v[204:207], v[22:25]
	v_mfma_f32_16x16x32_bf16 v[18:21], v[168:171], v[200:203], v[18:21]
	v_mfma_f32_16x16x32_bf16 v[18:21], v[172:175], v[204:207], v[18:21]
	v_mfma_f32_16x16x32_bf16 v[6:9], v[146:149], v[214:217], v[6:9]
	v_mfma_f32_16x16x32_bf16 v[6:9], v[164:167], v[218:221], v[6:9]
	v_mfma_f32_16x16x32_bf16 v[2:5], v[168:171], v[214:217], v[2:5]
	v_mfma_f32_16x16x32_bf16 v[2:5], v[172:175], v[218:221], v[2:5]
	s_setprio 0
	s_barrier
	v_or_b32_e32 v130, 0x18000, v177
	v_add_u32_e32 v134, 0x18400, v177
	v_add_u32_e32 v138, 0x18800, v177
	v_add_u32_e32 v142, 0x18c00, v177
	v_or_b32_e32 v146, 0x1c000, v177
	v_add_u32_e32 v157, 0x1c400, v177
	ds_read_b128 v[130:133], v130
	ds_read_b128 v[134:137], v134
	ds_read_b128 v[138:141], v138
	ds_read_b128 v[142:145], v142
	ds_read_b128 v[146:149], v146
	ds_read_b128 v[164:167], v157
	v_add_u32_e32 v157, 0x1c800, v177
	v_add_u32_e32 v172, 0x1cc00, v177
	ds_read_b128 v[168:171], v157
	ds_read_b128 v[172:175], v172
	s_add_u32 s88, s88, s40
	s_addc_u32 s89, s89, 0
	s_mov_b32 m0, s51
	v_lshl_add_u64 v[228:229], s[88:89], 0, v[154:155]
	ds_read_b128 v[184:187], v176 offset:32768
	ds_read_b128 v[188:191], v176 offset:33792
	ds_read_b128 v[192:195], v176 offset:34816
	ds_read_b128 v[196:199], v176 offset:35840
	ds_read_b128 v[200:203], v176 offset:36864
	ds_read_b128 v[204:207], v176 offset:37888
	ds_read_b128 v[214:217], v176 offset:38912
	ds_read_b128 v[218:221], v176 offset:39936
	global_load_lds_dwordx4 v[228:229], off
	v_lshl_add_u64 v[228:229], s[88:89], 0, v[152:153]
	s_mov_b32 m0, s90
	s_nop 0
	global_load_lds_dwordx4 v[228:229], off
	s_waitcnt vmcnt(8)
	s_waitcnt lgkmcnt(0)
	s_barrier
	s_setprio 1
	s_waitcnt lgkmcnt(0)
	v_mfma_f32_16x16x32_bf16 v[126:129], v[130:133], v[184:187], v[126:129]
	v_mfma_f32_16x16x32_bf16 v[126:129], v[134:137], v[188:191], v[126:129]
	v_mfma_f32_16x16x32_bf16 v[122:125], v[138:141], v[184:187], v[122:125]
	v_mfma_f32_16x16x32_bf16 v[122:125], v[142:145], v[188:191], v[122:125]
	v_mfma_f32_16x16x32_bf16 v[110:113], v[130:133], v[192:195], v[110:113]
	v_mfma_f32_16x16x32_bf16 v[110:113], v[134:137], v[196:199], v[110:113]
	v_mfma_f32_16x16x32_bf16 v[106:109], v[138:141], v[192:195], v[106:109]
	v_mfma_f32_16x16x32_bf16 v[106:109], v[142:145], v[196:199], v[106:109]
	v_mfma_f32_16x16x32_bf16 v[94:97], v[130:133], v[200:203], v[94:97]
	v_mfma_f32_16x16x32_bf16 v[94:97], v[134:137], v[204:207], v[94:97]
	v_mfma_f32_16x16x32_bf16 v[90:93], v[138:141], v[200:203], v[90:93]
	v_mfma_f32_16x16x32_bf16 v[90:93], v[142:145], v[204:207], v[90:93]
	v_mfma_f32_16x16x32_bf16 v[78:81], v[130:133], v[214:217], v[78:81]
	v_mfma_f32_16x16x32_bf16 v[78:81], v[134:137], v[218:221], v[78:81]
	v_mfma_f32_16x16x32_bf16 v[74:77], v[138:141], v[214:217], v[74:77]
	v_mfma_f32_16x16x32_bf16 v[74:77], v[142:145], v[218:221], v[74:77]
	s_setprio 0
	s_setprio 1
	v_mfma_f32_16x16x32_bf16 v[118:121], v[146:149], v[184:187], v[118:121]
	v_mfma_f32_16x16x32_bf16 v[118:121], v[164:167], v[188:191], v[118:121]
	v_mfma_f32_16x16x32_bf16 v[114:117], v[168:171], v[184:187], v[114:117]
	v_mfma_f32_16x16x32_bf16 v[114:117], v[172:175], v[188:191], v[114:117]
	v_mfma_f32_16x16x32_bf16 v[102:105], v[146:149], v[192:195], v[102:105]
	v_mfma_f32_16x16x32_bf16 v[102:105], v[164:167], v[196:199], v[102:105]
	v_mfma_f32_16x16x32_bf16 v[98:101], v[168:171], v[192:195], v[98:101]
	v_mfma_f32_16x16x32_bf16 v[98:101], v[172:175], v[196:199], v[98:101]
	v_mfma_f32_16x16x32_bf16 v[86:89], v[146:149], v[200:203], v[86:89]
	v_mfma_f32_16x16x32_bf16 v[86:89], v[164:167], v[204:207], v[86:89]
	v_mfma_f32_16x16x32_bf16 v[82:85], v[168:171], v[200:203], v[82:85]
	v_mfma_f32_16x16x32_bf16 v[82:85], v[172:175], v[204:207], v[82:85]
	v_mfma_f32_16x16x32_bf16 v[70:73], v[146:149], v[214:217], v[70:73]
	v_mfma_f32_16x16x32_bf16 v[70:73], v[164:167], v[218:221], v[70:73]
	v_mfma_f32_16x16x32_bf16 v[66:69], v[168:171], v[214:217], v[66:69]
	v_mfma_f32_16x16x32_bf16 v[66:69], v[172:175], v[218:221], v[66:69]
	s_setprio 0
	s_barrier
; #define PG8_STAGE(bufoff, gbase, voff) do { _Pragma("unroll") for (int _i = 0; _i < 2; ++_i) \
;         __builtin_amdgcn_global_load_lds((const unsigned*)((const char*)(gbase) + (voff)[_i]), (PG8_LAS unsigned*)(lds + (bufoff) + ldsw + _i * 8192), 16, 0, 0); } while (0)
; #define PG8_LDA(dst, b, h) do { _Pragma("unroll") for (int m = 0; m < 4; ++m) _Pragma("unroll") for (int k = 0; k < 2; ++k) dst[m][k] = *(const PG8_LAS bf16x8*)(lds + PG8_SA(b, h) + aoff + m * 2048 + k * 1024); } while (0)
; #define PG8_MMA(ai, bj, At, Bt) do { __builtin_amdgcn_s_setprio(1); _Pragma("unroll") for (int m = 0; m < 4; ++m) _Pragma("unroll") for (int n = 0; n < 2; ++n) _Pragma("unroll") for (int k = 0; k < 2; ++k) \
;         acc[ai][bj][m][n] = __builtin_amdgcn_mfma_f32_16x16x32_bf16(Bt[n][k], At[m][k], acc[ai][bj][m][n], 0, 0, 0); __builtin_amdgcn_s_setprio(0); } while (0)
; #define PG8_WAIT_V(n) asm volatile("s_waitcnt vmcnt(" #n ")" ::: "memory")
; #define PG8_WAIT_L(n) asm volatile("s_waitcnt lgkmcnt(" #n ")" ::: "memory")
; #define PG8_BAR __builtin_amdgcn_s_barrier()
; #define PG8_SCHED __builtin_amdgcn_sched_barrier(0)
; template <class Epi, class Sched, bool ALIGN_EPI = false, bool SP2 = false>
; __device__ __forceinline__ void gemm_phase(PG8_LAS unsigned char* lds, const Gemm g, const Sched& S, const Epi& E, const int tid) {
;     ...
;         for (int t = 0; t < nt; t += 2) {
;     ...
;             PG8_LDA(At, 1, 1); PG8_STAGE(PG8_SB(1, 0), b3, voffB); PG8_STAGE(PG8_SB(1, 1), b3 + hstep, voffB); PG8_STAGE(PG8_SA(1, 0), a3, voffA);
;             PG8_WAIT_V(8); PG8_WAIT_L(0); PG8_BAR; PG8_MMA(1, 0, At, B0); PG8_MMA(1, 1, At, B1); PG8_BAR; PG8_SCHED;
	s_mov_b32 m0, s91
	v_lshl_add_u64 v[178:179], v[178:179], 0, s[12:13]
	ds_read_b128 v[184:187], v176 offset:49152
	ds_read_b128 v[188:191], v176 offset:50176
	ds_read_b128 v[192:195], v176 offset:51200
	ds_read_b128 v[196:199], v176 offset:52224
	ds_read_b128 v[200:203], v176 offset:53248
	ds_read_b128 v[204:207], v176 offset:54272
	ds_read_b128 v[214:217], v176 offset:55296
	ds_read_b128 v[218:221], v176 offset:56320
	global_load_lds_dwordx4 v[178:179], off
	v_lshl_add_u64 v[178:179], v[180:181], 0, s[12:13]
	s_mov_b32 m0, s28
	s_nop 0
	global_load_lds_dwordx4 v[178:179], off
	v_lshl_add_u64 v[178:179], v[182:183], 0, s[12:13]
	s_mov_b32 m0, s97
	s_nop 0
	global_load_lds_dwordx4 v[178:179], off
	v_lshl_add_u64 v[178:179], v[222:223], 0, s[12:13]
	s_mov_b32 m0, s15
	s_nop 0
	global_load_lds_dwordx4 v[178:179], off
	v_lshl_add_u64 v[178:179], v[224:225], 0, s[12:13]
	s_mov_b32 m0, s29
	s_nop 0
	global_load_lds_dwordx4 v[178:179], off
	v_lshl_add_u64 v[178:179], v[226:227], 0, s[12:13]
	s_mov_b32 m0, s96
	s_nop 0
	global_load_lds_dwordx4 v[178:179], off
	s_waitcnt vmcnt(8)
	s_waitcnt lgkmcnt(0)
	s_barrier
	s_setprio 1
	s_waitcnt lgkmcnt(0)
	v_mfma_f32_16x16x32_bf16 v[62:65], v[130:133], v[184:187], v[62:65]
	v_mfma_f32_16x16x32_bf16 v[62:65], v[134:137], v[188:191], v[62:65]
	v_mfma_f32_16x16x32_bf16 v[58:61], v[138:141], v[184:187], v[58:61]
	v_mfma_f32_16x16x32_bf16 v[58:61], v[142:145], v[188:191], v[58:61]
	v_mfma_f32_16x16x32_bf16 v[46:49], v[130:133], v[192:195], v[46:49]
	v_mfma_f32_16x16x32_bf16 v[46:49], v[134:137], v[196:199], v[46:49]
	v_mfma_f32_16x16x32_bf16 v[42:45], v[138:141], v[192:195], v[42:45]
	v_mfma_f32_16x16x32_bf16 v[42:45], v[142:145], v[196:199], v[42:45]
	v_mfma_f32_16x16x32_bf16 v[30:33], v[130:133], v[200:203], v[30:33]
	v_mfma_f32_16x16x32_bf16 v[30:33], v[134:137], v[204:207], v[30:33]
	v_mfma_f32_16x16x32_bf16 v[26:29], v[138:141], v[200:203], v[26:29]
	v_mfma_f32_16x16x32_bf16 v[26:29], v[142:145], v[204:207], v[26:29]
	v_mfma_f32_16x16x32_bf16 v[14:17], v[130:133], v[214:217], v[14:17]
	v_mfma_f32_16x16x32_bf16 v[14:17], v[134:137], v[218:221], v[14:17]
	v_mfma_f32_16x16x32_bf16 v[10:13], v[138:141], v[214:217], v[10:13]
	v_mfma_f32_16x16x32_bf16 v[10:13], v[142:145], v[218:221], v[10:13]
	s_setprio 0
	s_setprio 1
	v_mfma_f32_16x16x32_bf16 v[54:57], v[146:149], v[184:187], v[54:57]
	v_mfma_f32_16x16x32_bf16 v[54:57], v[164:167], v[188:191], v[54:57]
	v_mfma_f32_16x16x32_bf16 v[50:53], v[168:171], v[184:187], v[50:53]
	v_mfma_f32_16x16x32_bf16 v[50:53], v[172:175], v[188:191], v[50:53]
	v_mfma_f32_16x16x32_bf16 v[38:41], v[146:149], v[192:195], v[38:41]
	v_mfma_f32_16x16x32_bf16 v[38:41], v[164:167], v[196:199], v[38:41]
	v_mfma_f32_16x16x32_bf16 v[34:37], v[168:171], v[192:195], v[34:37]
	v_mfma_f32_16x16x32_bf16 v[34:37], v[172:175], v[196:199], v[34:37]
	v_mfma_f32_16x16x32_bf16 v[22:25], v[146:149], v[200:203], v[22:25]
	v_mfma_f32_16x16x32_bf16 v[22:25], v[164:167], v[204:207], v[22:25]
	v_mfma_f32_16x16x32_bf16 v[18:21], v[168:171], v[200:203], v[18:21]
	v_mfma_f32_16x16x32_bf16 v[18:21], v[172:175], v[204:207], v[18:21]
	v_mfma_f32_16x16x32_bf16 v[6:9], v[146:149], v[214:217], v[6:9]
	v_mfma_f32_16x16x32_bf16 v[6:9], v[164:167], v[218:221], v[6:9]
	v_mfma_f32_16x16x32_bf16 v[2:5], v[168:171], v[214:217], v[2:5]
	v_mfma_f32_16x16x32_bf16 v[2:5], v[172:175], v[218:221], v[2:5]
	s_setprio 0
	s_barrier
	s_add_u32 s86, s86, 0x100
	s_addc_u32 s87, s87, 0
	s_add_u32 vcc_lo, vcc_lo, 0x100
	s_addc_u32 vcc_hi, vcc_hi, 0
	s_cmp_ge_u32 s92, s2
	s_mov_b32 s88, s92
	s_cbranch_scc0 .LBB0_684
	s_and_b64 vcc, exec, s[30:31]
	s_cbranch_vccz .LBB0_687
	s_barrier

; #define PG8_STAGE(bufoff, gbase, voff) do { _Pragma("unroll") for (int _i = 0; _i < 2; ++_i) \
;         __builtin_amdgcn_global_load_lds((const unsigned*)((const char*)(gbase) + (voff)[_i]), (PG8_LAS unsigned*)(lds + (bufoff) + ldsw + _i * 8192), 16, 0, 0); } while (0)
; #define PG8_LDA(dst, b, h) do { _Pragma("unroll") for (int m = 0; m < 4; ++m) _Pragma("unroll") for (int k = 0; k < 2; ++k) dst[m][k] = *(const PG8_LAS bf16x8*)(lds + PG8_SA(b, h) + aoff + m * 2048 + k * 1024); } while (0)
; #define PG8_LDB(dst, b, h) do { _Pragma("unroll") for (int n = 0; n < 2; ++n) _Pragma("unroll") for (int k = 0; k < 2; ++k) dst[n][k] = *(const PG8_LAS bf16x8*)(lds + PG8_SB(b, h) + boff + n * 2048 + k * 1024); } while (0)
; #define PG8_MMA(ai, bj, At, Bt) do { __builtin_amdgcn_s_setprio(1); _Pragma("unroll") for (int m = 0; m < 4; ++m) _Pragma("unroll") for (int n = 0; n < 2; ++n) _Pragma("unroll") for (int k = 0; k < 2; ++k) \
;         acc[ai][bj][m][n] = __builtin_amdgcn_mfma_f32_16x16x32_bf16(Bt[n][k], At[m][k], acc[ai][bj][m][n], 0, 0, 0); __builtin_amdgcn_s_setprio(0); } while (0)
; #define PG8_WAIT_V(n) asm volatile("s_waitcnt vmcnt(" #n ")" ::: "memory")
; #define PG8_WAIT_L(n) asm volatile("s_waitcnt lgkmcnt(" #n ")" ::: "memory")
; #define PG8_BAR __builtin_amdgcn_s_barrier()
; #define PG8_SCHED __builtin_amdgcn_sched_barrier(0)
; template <class Epi, class Sched, bool ALIGN_EPI = false, bool SP2 = false>
; __device__ __forceinline__ void gemm_phase(PG8_LAS unsigned char* lds, const Gemm g, const Sched& S, const Epi& E, const int tid) {
;     ...
;             const bool last = (t == nt - 2);
;             const char* a1 = cA + (size_t)(t + 1) * kstep;
;             const char* a2 = last ? nA : cA + (size_t)(t + 2) * kstep; const char* b2 = last ? nB : cB + (size_t)(t + 2) * kstep;
;             const char* a3 = a2 + kstep; const char* b3 = b2 + kstep;
;             if (last && has_next) S.a_ready(nxt);
;             if constexpr (SP2) {
;             PG8_LDB(B0, 0, 0); PG8_LDB(B1, 0, 1); PG8_SCHED; PG8_LDA(At, 0, 0); PG8_STAGE(PG8_SA(1, 1), a1 + hstep, voffA);
;             PG8_WAIT_V(8); PG8_WAIT_L(0); PG8_BAR; PG8_MMA(0, 0, At, B0); PG8_MMA(0, 1, At, B1); PG8_BAR; PG8_SCHED;
;             PG8_LDA(At, 0, 1); PG8_STAGE(PG8_SB(0, 0), b2, voffB); PG8_STAGE(PG8_SB(0, 1), b2 + hstep, voffB); PG8_STAGE(PG8_SA(0, 0), a2, voffA);
.LBB0_695:
	s_add_i32 s42, s41, 2
	s_mov_b32 s43, s7
	s_or_b32 s6, s41, 1
	s_lshl_b64 s[44:45], s[42:43], 7
	v_or_b32_e32 v138, 0x10000, v137
	v_add_u32_e32 v142, 0x10400, v137
	v_add_u32_e32 v146, 0x10800, v137
	v_add_u32_e32 v150, 0x10c00, v137
	v_or_b32_e32 v154, 0x14000, v137
	v_add_u32_e32 v158, 0x14400, v137
	v_add_u32_e32 v162, 0x14800, v137
	v_add_u32_e32 v166, 0x14c00, v137
	s_cmp_lg_u32 s41, s35
	ds_read_b128 v[138:141], v138
	ds_read_b128 v[142:145], v142
	ds_read_b128 v[146:149], v146
	ds_read_b128 v[150:153], v150
	ds_read_b128 v[154:157], v154
	ds_read_b128 v[158:161], v158
	ds_read_b128 v[162:165], v162
	ds_read_b128 v[166:169], v166
	s_cselect_b32 s43, s44, 0
	s_cselect_b32 s41, s45, 0
	s_add_u32 s44, s36, s43
	s_addc_u32 s45, s37, s41
	s_add_u32 s46, s30, s43
	s_addc_u32 s47, s31, s41
	s_lshl_b64 s[50:51], s[6:7], 7
	s_add_u32 s50, s38, s50
	s_addc_u32 s51, s39, s51
	v_lshl_add_u64 v[178:179], s[50:51], 0, v[134:135]
	s_add_i32 m0, s4, 0xc000
	ds_read_b128 v[170:173], v136
	ds_read_b128 v[174:177], v136 offset:1024
	ds_read_b128 v[184:187], v136 offset:2048
	ds_read_b128 v[188:191], v136 offset:3072
	ds_read_b128 v[192:195], v136 offset:4096
	ds_read_b128 v[196:199], v136 offset:5120
	ds_read_b128 v[200:203], v136 offset:6144
	ds_read_b128 v[204:207], v136 offset:7168
	global_load_lds_dwordx4 v[178:179], off
	v_lshl_add_u64 v[178:179], s[50:51], 0, v[132:133]
	s_add_i32 m0, s4, 0xe000
	s_nop 0
	global_load_lds_dwordx4 v[178:179], off
	s_waitcnt vmcnt(8)
	s_waitcnt lgkmcnt(0)
	s_barrier
	s_setprio 1
	s_waitcnt lgkmcnt(0)
	v_mfma_f32_16x16x32_bf16 v[126:129], v[138:141], v[170:173], v[126:129]
	v_mfma_f32_16x16x32_bf16 v[126:129], v[142:145], v[174:177], v[126:129]
	v_mfma_f32_16x16x32_bf16 v[122:125], v[146:149], v[170:173], v[122:125]
	v_mfma_f32_16x16x32_bf16 v[122:125], v[150:153], v[174:177], v[122:125]
	v_mfma_f32_16x16x32_bf16 v[118:121], v[138:141], v[184:187], v[118:121]
	v_mfma_f32_16x16x32_bf16 v[118:121], v[142:145], v[188:191], v[118:121]
	v_mfma_f32_16x16x32_bf16 v[114:117], v[146:149], v[184:187], v[114:117]
	v_mfma_f32_16x16x32_bf16 v[114:117], v[150:153], v[188:191], v[114:117]
	v_mfma_f32_16x16x32_bf16 v[106:109], v[138:141], v[192:195], v[106:109]
	v_mfma_f32_16x16x32_bf16 v[106:109], v[142:145], v[196:199], v[106:109]
	v_mfma_f32_16x16x32_bf16 v[98:101], v[146:149], v[192:195], v[98:101]
	v_mfma_f32_16x16x32_bf16 v[98:101], v[150:153], v[196:199], v[98:101]
	v_mfma_f32_16x16x32_bf16 v[90:93], v[138:141], v[200:203], v[90:93]
	v_mfma_f32_16x16x32_bf16 v[90:93], v[142:145], v[204:207], v[90:93]
	v_mfma_f32_16x16x32_bf16 v[82:85], v[146:149], v[200:203], v[82:85]
	v_mfma_f32_16x16x32_bf16 v[82:85], v[150:153], v[204:207], v[82:85]
	s_setprio 0
	s_setprio 1
	v_mfma_f32_16x16x32_bf16 v[110:113], v[154:157], v[170:173], v[110:113]
	v_mfma_f32_16x16x32_bf16 v[110:113], v[158:161], v[174:177], v[110:113]
	v_mfma_f32_16x16x32_bf16 v[102:105], v[162:165], v[170:173], v[102:105]
	v_mfma_f32_16x16x32_bf16 v[102:105], v[166:169], v[174:177], v[102:105]
	v_mfma_f32_16x16x32_bf16 v[94:97], v[154:157], v[184:187], v[94:97]
	v_mfma_f32_16x16x32_bf16 v[94:97], v[158:161], v[188:191], v[94:97]
	v_mfma_f32_16x16x32_bf16 v[86:89], v[162:165], v[184:187], v[86:89]
	v_mfma_f32_16x16x32_bf16 v[86:89], v[166:169], v[188:191], v[86:89]
	v_mfma_f32_16x16x32_bf16 v[78:81], v[154:157], v[192:195], v[78:81]
	v_mfma_f32_16x16x32_bf16 v[78:81], v[158:161], v[196:199], v[78:81]
	v_mfma_f32_16x16x32_bf16 v[74:77], v[162:165], v[192:195], v[74:77]
	v_mfma_f32_16x16x32_bf16 v[74:77], v[166:169], v[196:199], v[74:77]
	v_mfma_f32_16x16x32_bf16 v[70:73], v[154:157], v[200:203], v[70:73]
	v_mfma_f32_16x16x32_bf16 v[70:73], v[158:161], v[204:207], v[70:73]
	v_mfma_f32_16x16x32_bf16 v[66:69], v[162:165], v[200:203], v[66:69]
	v_mfma_f32_16x16x32_bf16 v[66:69], v[166:169], v[204:207], v[66:69]
	s_setprio 0
	s_barrier
	s_mov_b32 m0, s0
	v_lshl_add_u64 v[178:179], s[46:47], 0, v[0:1]
	v_lshl_add_u64 v[180:181], s[46:47], 0, v[130:131]
	s_add_u32 s46, s46, s40
	ds_read_b128 v[170:173], v136 offset:16384
	ds_read_b128 v[174:177], v136 offset:17408
	ds_read_b128 v[184:187], v136 offset:18432
	ds_read_b128 v[188:191], v136 offset:19456
	ds_read_b128 v[192:195], v136 offset:20480
	ds_read_b128 v[196:199], v136 offset:21504
	ds_read_b128 v[200:203], v136 offset:22528
	ds_read_b128 v[204:207], v136 offset:23552
	global_load_lds_dwordx4 v[178:179], off
	s_mov_b32 m0, s1
	s_addc_u32 s47, s47, 0
	global_load_lds_dwordx4 v[180:181], off
	v_lshl_add_u64 v[182:183], s[46:47], 0, v[0:1]
	s_mov_b32 m0, s5
	v_lshl_add_u64 v[214:215], s[46:47], 0, v[130:131]
	global_load_lds_dwordx4 v[182:183], off
	s_mov_b32 m0, s8
	v_lshl_add_u64 v[216:217], s[44:45], 0, v[134:135]
	global_load_lds_dwordx4 v[214:215], off
	s_mov_b32 m0, s4
	v_lshl_add_u64 v[218:219], s[44:45], 0, v[132:133]
	global_load_lds_dwordx4 v[216:217], off
	s_mov_b32 m0, s9
	s_nop 0
	global_load_lds_dwordx4 v[218:219], off
	s_waitcnt vmcnt(8)
	s_waitcnt lgkmcnt(0)
	s_barrier
; #define PG8_STAGE(bufoff, gbase, voff) do { _Pragma("unroll") for (int _i = 0; _i < 2; ++_i) \
;         __builtin_amdgcn_global_load_lds((const unsigned*)((const char*)(gbase) + (voff)[_i]), (PG8_LAS unsigned*)(lds + (bufoff) + ldsw + _i * 8192), 16, 0, 0); } while (0)
; #define PG8_LDA(dst, b, h) do { _Pragma("unroll") for (int m = 0; m < 4; ++m) _Pragma("unroll") for (int k = 0; k < 2; ++k) dst[m][k] = *(const PG8_LAS bf16x8*)(lds + PG8_SA(b, h) + aoff + m * 2048 + k * 1024); } while (0)
; #define PG8_LDB(dst, b, h) do { _Pragma("unroll") for (int n = 0; n < 2; ++n) _Pragma("unroll") for (int k = 0; k < 2; ++k) dst[n][k] = *(const PG8_LAS bf16x8*)(lds + PG8_SB(b, h) + boff + n * 2048 + k * 1024); } while (0)
; #define PG8_MMA(ai, bj, At, Bt) do { __builtin_amdgcn_s_setprio(1); _Pragma("unroll") for (int m = 0; m < 4; ++m) _Pragma("unroll") for (int n = 0; n < 2; ++n) _Pragma("unroll") for (int k = 0; k < 2; ++k) \
;         acc[ai][bj][m][n] = __builtin_amdgcn_mfma_f32_16x16x32_bf16(Bt[n][k], At[m][k], acc[ai][bj][m][n], 0, 0, 0); __builtin_amdgcn_s_setprio(0); } while (0)
; #define PG8_WAIT_V(n) asm volatile("s_waitcnt vmcnt(" #n ")" ::: "memory")
; #define PG8_WAIT_L(n) asm volatile("s_waitcnt lgkmcnt(" #n ")" ::: "memory")
; #define PG8_BAR __builtin_amdgcn_s_barrier()
; #define PG8_SCHED __builtin_amdgcn_sched_barrier(0)
; template <class Epi, class Sched, bool ALIGN_EPI = false, bool SP2 = false>
; __device__ __forceinline__ void gemm_phase(PG8_LAS unsigned char* lds, const Gemm g, const Sched& S, const Epi& E, const int tid) {
;     ...
;             PG8_WAIT_V(8); PG8_WAIT_L(0); PG8_BAR; PG8_MMA(1, 0, At, B0); PG8_MMA(1, 1, At, B1); PG8_BAR; PG8_SCHED;
;             PG8_LDB(B0, 1, 0); PG8_LDB(B1, 1, 1); PG8_SCHED; PG8_LDA(At, 1, 0); PG8_STAGE(PG8_SA(0, 1), a2 + hstep, voffA);
;             PG8_WAIT_V(8); PG8_WAIT_L(0); PG8_BAR; PG8_MMA(0, 0, At, B0); PG8_MMA(0, 1, At, B1); PG8_BAR; PG8_SCHED;
	s_setprio 1
	s_waitcnt lgkmcnt(0)
	v_mfma_f32_16x16x32_bf16 v[62:65], v[138:141], v[170:173], v[62:65]
	v_mfma_f32_16x16x32_bf16 v[62:65], v[142:145], v[174:177], v[62:65]
	v_mfma_f32_16x16x32_bf16 v[58:61], v[146:149], v[170:173], v[58:61]
	v_mfma_f32_16x16x32_bf16 v[58:61], v[150:153], v[174:177], v[58:61]
	v_mfma_f32_16x16x32_bf16 v[54:57], v[138:141], v[184:187], v[54:57]
	v_mfma_f32_16x16x32_bf16 v[54:57], v[142:145], v[188:191], v[54:57]
	v_mfma_f32_16x16x32_bf16 v[50:53], v[146:149], v[184:187], v[50:53]
	v_mfma_f32_16x16x32_bf16 v[50:53], v[150:153], v[188:191], v[50:53]
	v_mfma_f32_16x16x32_bf16 v[38:41], v[138:141], v[192:195], v[38:41]
	v_mfma_f32_16x16x32_bf16 v[38:41], v[142:145], v[196:199], v[38:41]
	v_mfma_f32_16x16x32_bf16 v[34:37], v[146:149], v[192:195], v[34:37]
	v_mfma_f32_16x16x32_bf16 v[34:37], v[150:153], v[196:199], v[34:37]
	v_mfma_f32_16x16x32_bf16 v[22:25], v[138:141], v[200:203], v[22:25]
	v_mfma_f32_16x16x32_bf16 v[22:25], v[142:145], v[204:207], v[22:25]
	v_mfma_f32_16x16x32_bf16 v[18:21], v[146:149], v[200:203], v[18:21]
	v_mfma_f32_16x16x32_bf16 v[18:21], v[150:153], v[204:207], v[18:21]
	s_setprio 0
	s_setprio 1
	v_mfma_f32_16x16x32_bf16 v[46:49], v[154:157], v[170:173], v[46:49]
	v_mfma_f32_16x16x32_bf16 v[46:49], v[158:161], v[174:177], v[46:49]
	v_mfma_f32_16x16x32_bf16 v[42:45], v[162:165], v[170:173], v[42:45]
	v_mfma_f32_16x16x32_bf16 v[42:45], v[166:169], v[174:177], v[42:45]
	v_mfma_f32_16x16x32_bf16 v[30:33], v[154:157], v[184:187], v[30:33]
	v_mfma_f32_16x16x32_bf16 v[30:33], v[158:161], v[188:191], v[30:33]
	v_mfma_f32_16x16x32_bf16 v[26:29], v[162:165], v[184:187], v[26:29]
	v_mfma_f32_16x16x32_bf16 v[26:29], v[166:169], v[188:191], v[26:29]
	v_mfma_f32_16x16x32_bf16 v[14:17], v[154:157], v[192:195], v[14:17]
	v_mfma_f32_16x16x32_bf16 v[14:17], v[158:161], v[196:199], v[14:17]
	v_mfma_f32_16x16x32_bf16 v[10:13], v[162:165], v[192:195], v[10:13]
	v_mfma_f32_16x16x32_bf16 v[10:13], v[166:169], v[196:199], v[10:13]
	v_mfma_f32_16x16x32_bf16 v[6:9], v[154:157], v[200:203], v[6:9]
	v_mfma_f32_16x16x32_bf16 v[6:9], v[158:161], v[204:207], v[6:9]
	v_mfma_f32_16x16x32_bf16 v[2:5], v[162:165], v[200:203], v[2:5]
	v_mfma_f32_16x16x32_bf16 v[2:5], v[166:169], v[204:207], v[2:5]
	s_setprio 0
	s_barrier
	v_or_b32_e32 v138, 0x18000, v137
	v_add_u32_e32 v142, 0x18400, v137
	v_add_u32_e32 v146, 0x18800, v137
	v_add_u32_e32 v150, 0x18c00, v137
	v_or_b32_e32 v154, 0x1c000, v137
	v_add_u32_e32 v158, 0x1c400, v137
	v_add_u32_e32 v162, 0x1c800, v137
	v_add_u32_e32 v166, 0x1cc00, v137
	ds_read_b128 v[138:141], v138
	ds_read_b128 v[142:145], v142
	ds_read_b128 v[146:149], v146
	ds_read_b128 v[150:153], v150
	ds_read_b128 v[154:157], v154
	ds_read_b128 v[158:161], v158
	ds_read_b128 v[162:165], v162
	ds_read_b128 v[166:169], v166
	s_add_u32 s44, s44, s40
	s_addc_u32 s45, s45, 0
	s_mov_b32 m0, s14
	v_lshl_add_u64 v[220:221], s[44:45], 0, v[134:135]
	ds_read_b128 v[170:173], v136 offset:32768
	ds_read_b128 v[174:177], v136 offset:33792
	ds_read_b128 v[184:187], v136 offset:34816
	ds_read_b128 v[188:191], v136 offset:35840
	ds_read_b128 v[192:195], v136 offset:36864
	ds_read_b128 v[196:199], v136 offset:37888
	ds_read_b128 v[200:203], v136 offset:38912
	ds_read_b128 v[204:207], v136 offset:39936
	global_load_lds_dwordx4 v[220:221], off
	v_lshl_add_u64 v[220:221], s[44:45], 0, v[132:133]
	s_mov_b32 m0, s15
	s_nop 0
	global_load_lds_dwordx4 v[220:221], off
	s_waitcnt vmcnt(8)
	s_waitcnt lgkmcnt(0)
	s_barrier
	s_setprio 1
	s_waitcnt lgkmcnt(0)
	v_mfma_f32_16x16x32_bf16 v[126:129], v[138:141], v[170:173], v[126:129]
	v_mfma_f32_16x16x32_bf16 v[126:129], v[142:145], v[174:177], v[126:129]
	v_mfma_f32_16x16x32_bf16 v[122:125], v[146:149], v[170:173], v[122:125]
	v_mfma_f32_16x16x32_bf16 v[122:125], v[150:153], v[174:177], v[122:125]
	v_mfma_f32_16x16x32_bf16 v[118:121], v[138:141], v[184:187], v[118:121]
	v_mfma_f32_16x16x32_bf16 v[118:121], v[142:145], v[188:191], v[118:121]
	v_mfma_f32_16x16x32_bf16 v[114:117], v[146:149], v[184:187], v[114:117]
	v_mfma_f32_16x16x32_bf16 v[114:117], v[150:153], v[188:191], v[114:117]
	v_mfma_f32_16x16x32_bf16 v[106:109], v[138:141], v[192:195], v[106:109]
	v_mfma_f32_16x16x32_bf16 v[106:109], v[142:145], v[196:199], v[106:109]
	v_mfma_f32_16x16x32_bf16 v[98:101], v[146:149], v[192:195], v[98:101]
	v_mfma_f32_16x16x32_bf16 v[98:101], v[150:153], v[196:199], v[98:101]
	v_mfma_f32_16x16x32_bf16 v[90:93], v[138:141], v[200:203], v[90:93]
	v_mfma_f32_16x16x32_bf16 v[90:93], v[142:145], v[204:207], v[90:93]
	v_mfma_f32_16x16x32_bf16 v[82:85], v[146:149], v[200:203], v[82:85]
	v_mfma_f32_16x16x32_bf16 v[82:85], v[150:153], v[204:207], v[82:85]
	s_setprio 0
	s_setprio 1
	v_mfma_f32_16x16x32_bf16 v[110:113], v[154:157], v[170:173], v[110:113]
	v_mfma_f32_16x16x32_bf16 v[110:113], v[158:161], v[174:177], v[110:113]
	v_mfma_f32_16x16x32_bf16 v[102:105], v[162:165], v[170:173], v[102:105]
	v_mfma_f32_16x16x32_bf16 v[102:105], v[166:169], v[174:177], v[102:105]
	v_mfma_f32_16x16x32_bf16 v[94:97], v[154:157], v[184:187], v[94:97]
	v_mfma_f32_16x16x32_bf16 v[94:97], v[158:161], v[188:191], v[94:97]
	v_mfma_f32_16x16x32_bf16 v[86:89], v[162:165], v[184:187], v[86:89]
	v_mfma_f32_16x16x32_bf16 v[86:89], v[166:169], v[188:191], v[86:89]
	v_mfma_f32_16x16x32_bf16 v[78:81], v[154:157], v[192:195], v[78:81]
	v_mfma_f32_16x16x32_bf16 v[78:81], v[158:161], v[196:199], v[78:81]
	v_mfma_f32_16x16x32_bf16 v[74:77], v[162:165], v[192:195], v[74:77]
	v_mfma_f32_16x16x32_bf16 v[74:77], v[166:169], v[196:199], v[74:77]
	v_mfma_f32_16x16x32_bf16 v[70:73], v[154:157], v[200:203], v[70:73]
	v_mfma_f32_16x16x32_bf16 v[70:73], v[158:161], v[204:207], v[70:73]
	v_mfma_f32_16x16x32_bf16 v[66:69], v[162:165], v[200:203], v[66:69]
	v_mfma_f32_16x16x32_bf16 v[66:69], v[166:169], v[204:207], v[66:69]
	s_setprio 0
	s_barrier
; #define PG8_STAGE(bufoff, gbase, voff) do { _Pragma("unroll") for (int _i = 0; _i < 2; ++_i) \
;         __builtin_amdgcn_global_load_lds((const unsigned*)((const char*)(gbase) + (voff)[_i]), (PG8_LAS unsigned*)(lds + (bufoff) + ldsw + _i * 8192), 16, 0, 0); } while (0)
; #define PG8_LDA(dst, b, h) do { _Pragma("unroll") for (int m = 0; m < 4; ++m) _Pragma("unroll") for (int k = 0; k < 2; ++k) dst[m][k] = *(const PG8_LAS bf16x8*)(lds + PG8_SA(b, h) + aoff + m * 2048 + k * 1024); } while (0)
; #define PG8_MMA(ai, bj, At, Bt) do { __builtin_amdgcn_s_setprio(1); _Pragma("unroll") for (int m = 0; m < 4; ++m) _Pragma("unroll") for (int n = 0; n < 2; ++n) _Pragma("unroll") for (int k = 0; k < 2; ++k) \
;         acc[ai][bj][m][n] = __builtin_amdgcn_mfma_f32_16x16x32_bf16(Bt[n][k], At[m][k], acc[ai][bj][m][n], 0, 0, 0); __builtin_amdgcn_s_setprio(0); } while (0)
; #define PG8_WAIT_V(n) asm volatile("s_waitcnt vmcnt(" #n ")" ::: "memory")
; #define PG8_WAIT_L(n) asm volatile("s_waitcnt lgkmcnt(" #n ")" ::: "memory")
; #define PG8_BAR __builtin_amdgcn_s_barrier()
; #define PG8_SCHED __builtin_amdgcn_sched_barrier(0)
; template <class Epi, class Sched, bool ALIGN_EPI = false, bool SP2 = false>
; __device__ __forceinline__ void gemm_phase(PG8_LAS unsigned char* lds, const Gemm g, const Sched& S, const Epi& E, const int tid) {
;     ...
;         for (int t = 0; t < nt; t += 2) {
;     ...
;             PG8_LDA(At, 1, 1); PG8_STAGE(PG8_SB(1, 0), b3, voffB); PG8_STAGE(PG8_SB(1, 1), b3 + hstep, voffB); PG8_STAGE(PG8_SA(1, 0), a3, voffA);
;             PG8_WAIT_V(8); PG8_WAIT_L(0); PG8_BAR; PG8_MMA(1, 0, At, B0); PG8_MMA(1, 1, At, B1); PG8_BAR; PG8_SCHED;
	s_mov_b32 m0, s24
	v_lshl_add_u64 v[178:179], v[178:179], 0, s[12:13]
	ds_read_b128 v[170:173], v136 offset:49152
	ds_read_b128 v[174:177], v136 offset:50176
	ds_read_b128 v[184:187], v136 offset:51200
	ds_read_b128 v[188:191], v136 offset:52224
	ds_read_b128 v[192:195], v136 offset:53248
	ds_read_b128 v[196:199], v136 offset:54272
	ds_read_b128 v[200:203], v136 offset:55296
	ds_read_b128 v[204:207], v136 offset:56320
	global_load_lds_dwordx4 v[178:179], off
	v_lshl_add_u64 v[178:179], v[180:181], 0, s[12:13]
	s_mov_b32 m0, s26
	s_nop 0
	global_load_lds_dwordx4 v[178:179], off
	v_lshl_add_u64 v[178:179], v[182:183], 0, s[12:13]
	s_mov_b32 m0, s29
	s_nop 0
	global_load_lds_dwordx4 v[178:179], off
	v_lshl_add_u64 v[178:179], v[214:215], 0, s[12:13]
	s_mov_b32 m0, s34
	s_nop 0
	global_load_lds_dwordx4 v[178:179], off
	v_lshl_add_u64 v[178:179], v[216:217], 0, s[12:13]
	s_mov_b32 m0, s27
	s_nop 0
	global_load_lds_dwordx4 v[178:179], off
	v_lshl_add_u64 v[178:179], v[218:219], 0, s[12:13]
	s_mov_b32 m0, s28
	s_nop 0
	global_load_lds_dwordx4 v[178:179], off
	s_waitcnt vmcnt(8)
	s_waitcnt lgkmcnt(0)
	s_barrier
	s_setprio 1
	s_waitcnt lgkmcnt(0)
	v_mfma_f32_16x16x32_bf16 v[62:65], v[138:141], v[170:173], v[62:65]
	v_mfma_f32_16x16x32_bf16 v[62:65], v[142:145], v[174:177], v[62:65]
	v_mfma_f32_16x16x32_bf16 v[58:61], v[146:149], v[170:173], v[58:61]
	v_mfma_f32_16x16x32_bf16 v[58:61], v[150:153], v[174:177], v[58:61]
	v_mfma_f32_16x16x32_bf16 v[54:57], v[138:141], v[184:187], v[54:57]
	v_mfma_f32_16x16x32_bf16 v[54:57], v[142:145], v[188:191], v[54:57]
	v_mfma_f32_16x16x32_bf16 v[50:53], v[146:149], v[184:187], v[50:53]
	v_mfma_f32_16x16x32_bf16 v[50:53], v[150:153], v[188:191], v[50:53]
	v_mfma_f32_16x16x32_bf16 v[38:41], v[138:141], v[192:195], v[38:41]
	v_mfma_f32_16x16x32_bf16 v[38:41], v[142:145], v[196:199], v[38:41]
	v_mfma_f32_16x16x32_bf16 v[34:37], v[146:149], v[192:195], v[34:37]
	v_mfma_f32_16x16x32_bf16 v[34:37], v[150:153], v[196:199], v[34:37]
	v_mfma_f32_16x16x32_bf16 v[22:25], v[138:141], v[200:203], v[22:25]
	v_mfma_f32_16x16x32_bf16 v[22:25], v[142:145], v[204:207], v[22:25]
	v_mfma_f32_16x16x32_bf16 v[18:21], v[146:149], v[200:203], v[18:21]
	v_mfma_f32_16x16x32_bf16 v[18:21], v[150:153], v[204:207], v[18:21]
	s_setprio 0
	s_setprio 1
	v_mfma_f32_16x16x32_bf16 v[46:49], v[154:157], v[170:173], v[46:49]
	v_mfma_f32_16x16x32_bf16 v[46:49], v[158:161], v[174:177], v[46:49]
	v_mfma_f32_16x16x32_bf16 v[42:45], v[162:165], v[170:173], v[42:45]
	v_mfma_f32_16x16x32_bf16 v[42:45], v[166:169], v[174:177], v[42:45]
	v_mfma_f32_16x16x32_bf16 v[30:33], v[154:157], v[184:187], v[30:33]
	v_mfma_f32_16x16x32_bf16 v[30:33], v[158:161], v[188:191], v[30:33]
	v_mfma_f32_16x16x32_bf16 v[26:29], v[162:165], v[184:187], v[26:29]
	v_mfma_f32_16x16x32_bf16 v[26:29], v[166:169], v[188:191], v[26:29]
	v_mfma_f32_16x16x32_bf16 v[14:17], v[154:157], v[192:195], v[14:17]
	v_mfma_f32_16x16x32_bf16 v[14:17], v[158:161], v[196:199], v[14:17]
	v_mfma_f32_16x16x32_bf16 v[10:13], v[162:165], v[192:195], v[10:13]
	v_mfma_f32_16x16x32_bf16 v[10:13], v[166:169], v[196:199], v[10:13]
	v_mfma_f32_16x16x32_bf16 v[6:9], v[154:157], v[200:203], v[6:9]
	v_mfma_f32_16x16x32_bf16 v[6:9], v[158:161], v[204:207], v[6:9]
	v_mfma_f32_16x16x32_bf16 v[2:5], v[162:165], v[200:203], v[2:5]
	v_mfma_f32_16x16x32_bf16 v[2:5], v[166:169], v[204:207], v[2:5]
	s_setprio 0
	s_barrier
	s_cmp_ge_u32 s42, s21
	s_mov_b32 s41, s42
	s_cbranch_scc0 .LBB0_695
	v_readlane_b32 s26, v254, 47
	v_readlane_b32 s28, v254, 49
	s_cmpk_lt_u32 s2, 0x100
	v_readlane_b32 s27, v254, 48
	v_readlane_b32 s29, v254, 50
	s_cbranch_scc0 .LBB0_698
	s_barrier

; #define PG8_STAGE(bufoff, gbase, voff) do { _Pragma("unroll") for (int _i = 0; _i < 2; ++_i) \
;         __builtin_amdgcn_global_load_lds((const unsigned*)((const char*)(gbase) + (voff)[_i]), (PG8_LAS unsigned*)(lds + (bufoff) + ldsw + _i * 8192), 16, 0, 0); } while (0)
; #define PG8_LDA(dst, b, h) do { _Pragma("unroll") for (int m = 0; m < 4; ++m) _Pragma("unroll") for (int k = 0; k < 2; ++k) dst[m][k] = *(const PG8_LAS bf16x8*)(lds + PG8_SA(b, h) + aoff + m * 2048 + k * 1024); } while (0)
; #define PG8_LDB(dst, b, h) do { _Pragma("unroll") for (int n = 0; n < 2; ++n) _Pragma("unroll") for (int k = 0; k < 2; ++k) dst[n][k] = *(const PG8_LAS bf16x8*)(lds + PG8_SB(b, h) + boff + n * 2048 + k * 1024); } while (0)
; #define PG8_MMA(ai, bj, At, Bt) do { __builtin_amdgcn_s_setprio(1); _Pragma("unroll") for (int m = 0; m < 4; ++m) _Pragma("unroll") for (int n = 0; n < 2; ++n) _Pragma("unroll") for (int k = 0; k < 2; ++k) \
;         acc[ai][bj][m][n] = __builtin_amdgcn_mfma_f32_16x16x32_bf16(Bt[n][k], At[m][k], acc[ai][bj][m][n], 0, 0, 0); __builtin_amdgcn_s_setprio(0); } while (0)
; #define PG8_WAIT_V(n) asm volatile("s_waitcnt vmcnt(" #n ")" ::: "memory")
; #define PG8_WAIT_L(n) asm volatile("s_waitcnt lgkmcnt(" #n ")" ::: "memory")
; #define PG8_BAR __builtin_amdgcn_s_barrier()
; #define PG8_SCHED __builtin_amdgcn_sched_barrier(0)
; template <class Epi, class Sched, bool ALIGN_EPI = false, bool SP2 = false>
; __device__ __forceinline__ void gemm_phase(PG8_LAS unsigned char* lds, const Gemm g, const Sched& S, const Epi& E, const int tid) {
;     ...
;             const bool last = (t == nt - 2);
;             const char* a1 = cA + (size_t)(t + 1) * kstep;
;             const char* a2 = last ? nA : cA + (size_t)(t + 2) * kstep; const char* b2 = last ? nB : cB + (size_t)(t + 2) * kstep;
;             const char* a3 = a2 + kstep; const char* b3 = b2 + kstep;
;             if (last && has_next) S.a_ready(nxt);
;             if constexpr (SP2) {
;             PG8_LDB(B0, 0, 0); PG8_LDB(B1, 0, 1); PG8_SCHED; PG8_LDA(At, 0, 0); PG8_STAGE(PG8_SA(1, 1), a1 + hstep, voffA);
;             PG8_WAIT_V(8); PG8_WAIT_L(0); PG8_BAR; PG8_MMA(0, 0, At, B0); PG8_MMA(0, 1, At, B1); PG8_BAR; PG8_SCHED;
;             PG8_LDA(At, 0, 1); PG8_STAGE(PG8_SB(0, 0), b2, voffB); PG8_STAGE(PG8_SB(0, 1), b2 + hstep, voffB); PG8_STAGE(PG8_SA(0, 0), a2, voffA);
.LBB0_713:
	v_or_b32_e32 v142, 0x10000, v141
	v_add_u32_e32 v146, 0x10400, v141
	v_add_u32_e32 v150, 0x10800, v141
	v_add_u32_e32 v154, 0x10c00, v141
	v_or_b32_e32 v158, 0x14000, v141
	v_add_u32_e32 v162, 0x14400, v141
	v_add_u32_e32 v166, 0x14800, v141
	v_add_u32_e32 v170, 0x14c00, v141
	ds_read_b128 v[142:145], v142
	ds_read_b128 v[146:149], v146
	ds_read_b128 v[150:153], v150
	ds_read_b128 v[154:157], v154
	ds_read_b128 v[158:161], v158
	ds_read_b128 v[162:165], v162
	ds_read_b128 v[166:169], v166
	ds_read_b128 v[170:173], v170
	s_add_u32 s84, s30, 0xfffc0080
	s_addc_u32 s85, s31, -1
	s_cmp_eq_u32 s43, 12
	s_cselect_b32 s87, s5, s85
	s_cselect_b32 s86, s15, s84
	s_cselect_b32 s85, s20, s41
	s_cselect_b32 s84, s21, s24
	v_lshl_add_u64 v[178:179], s[30:31], 0, v[136:137]
	s_add_i32 m0, s1, 0xc000
	ds_read_b128 v[174:177], v140
	ds_read_b128 v[184:187], v140 offset:1024
	ds_read_b128 v[188:191], v140 offset:2048
	ds_read_b128 v[192:195], v140 offset:3072
	ds_read_b128 v[196:199], v140 offset:4096
	ds_read_b128 v[200:203], v140 offset:5120
	ds_read_b128 v[204:207], v140 offset:6144
	ds_read_b128 v[214:217], v140 offset:7168
	global_load_lds_dwordx4 v[178:179], off
	v_lshl_add_u64 v[178:179], s[30:31], 0, v[138:139]
	s_add_i32 m0, s1, 0xe000
	s_nop 0
	global_load_lds_dwordx4 v[178:179], off
	s_waitcnt vmcnt(8)
	s_waitcnt lgkmcnt(0)
	s_barrier
	s_setprio 1
	s_waitcnt lgkmcnt(0)
	v_mfma_f32_16x16x32_bf16 v[126:129], v[142:145], v[174:177], v[126:129]
	v_mfma_f32_16x16x32_bf16 v[126:129], v[146:149], v[184:187], v[126:129]
	v_mfma_f32_16x16x32_bf16 v[118:121], v[150:153], v[174:177], v[118:121]
	v_mfma_f32_16x16x32_bf16 v[118:121], v[154:157], v[184:187], v[118:121]
	v_mfma_f32_16x16x32_bf16 v[110:113], v[142:145], v[188:191], v[110:113]
	v_mfma_f32_16x16x32_bf16 v[110:113], v[146:149], v[192:195], v[110:113]
	v_mfma_f32_16x16x32_bf16 v[102:105], v[150:153], v[188:191], v[102:105]
	v_mfma_f32_16x16x32_bf16 v[102:105], v[154:157], v[192:195], v[102:105]
	v_mfma_f32_16x16x32_bf16 v[94:97], v[142:145], v[196:199], v[94:97]
	v_mfma_f32_16x16x32_bf16 v[94:97], v[146:149], v[200:203], v[94:97]
	v_mfma_f32_16x16x32_bf16 v[86:89], v[150:153], v[196:199], v[86:89]
	v_mfma_f32_16x16x32_bf16 v[86:89], v[154:157], v[200:203], v[86:89]
	v_mfma_f32_16x16x32_bf16 v[78:81], v[142:145], v[204:207], v[78:81]
	v_mfma_f32_16x16x32_bf16 v[78:81], v[146:149], v[214:217], v[78:81]
	v_mfma_f32_16x16x32_bf16 v[70:73], v[150:153], v[204:207], v[70:73]
	v_mfma_f32_16x16x32_bf16 v[70:73], v[154:157], v[214:217], v[70:73]
	s_setprio 0
	s_setprio 1
	v_mfma_f32_16x16x32_bf16 v[122:125], v[158:161], v[174:177], v[122:125]
	v_mfma_f32_16x16x32_bf16 v[122:125], v[162:165], v[184:187], v[122:125]
	v_mfma_f32_16x16x32_bf16 v[114:117], v[166:169], v[174:177], v[114:117]
	v_mfma_f32_16x16x32_bf16 v[114:117], v[170:173], v[184:187], v[114:117]
	v_mfma_f32_16x16x32_bf16 v[106:109], v[158:161], v[188:191], v[106:109]
	v_mfma_f32_16x16x32_bf16 v[106:109], v[162:165], v[192:195], v[106:109]
	v_mfma_f32_16x16x32_bf16 v[98:101], v[166:169], v[188:191], v[98:101]
	v_mfma_f32_16x16x32_bf16 v[98:101], v[170:173], v[192:195], v[98:101]
	v_mfma_f32_16x16x32_bf16 v[90:93], v[158:161], v[196:199], v[90:93]
	v_mfma_f32_16x16x32_bf16 v[90:93], v[162:165], v[200:203], v[90:93]
	v_mfma_f32_16x16x32_bf16 v[82:85], v[166:169], v[196:199], v[82:85]
	v_mfma_f32_16x16x32_bf16 v[82:85], v[170:173], v[200:203], v[82:85]
	v_mfma_f32_16x16x32_bf16 v[74:77], v[158:161], v[204:207], v[74:77]
	v_mfma_f32_16x16x32_bf16 v[74:77], v[162:165], v[214:217], v[74:77]
	v_mfma_f32_16x16x32_bf16 v[66:69], v[166:169], v[204:207], v[66:69]
	v_mfma_f32_16x16x32_bf16 v[66:69], v[170:173], v[214:217], v[66:69]
	s_setprio 0
	s_barrier
	s_mov_b32 m0, s6
	v_lshl_add_u64 v[178:179], s[84:85], 0, v[0:1]
	s_add_u32 s92, s84, 0x40000
	ds_read_b128 v[174:177], v140 offset:16384
	ds_read_b128 v[184:187], v140 offset:17408
	ds_read_b128 v[188:191], v140 offset:18432
	ds_read_b128 v[192:195], v140 offset:19456
	ds_read_b128 v[196:199], v140 offset:20480
	ds_read_b128 v[200:203], v140 offset:21504
	ds_read_b128 v[204:207], v140 offset:22528
	ds_read_b128 v[214:217], v140 offset:23552
	global_load_lds_dwordx4 v[178:179], off
	v_lshl_add_u64 v[180:181], s[84:85], 0, v[130:131]
	s_mov_b32 m0, s8
	s_addc_u32 s93, s85, 0
	global_load_lds_dwordx4 v[180:181], off
	v_lshl_add_u64 v[182:183], s[92:93], 0, v[0:1]
	s_mov_b32 m0, s9
	v_lshl_add_u64 v[218:219], s[86:87], 0, v[132:133]
	global_load_lds_dwordx4 v[182:183], off
	v_lshl_add_u64 v[182:183], s[92:93], 0, v[130:131]
	s_mov_b32 m0, s14
	s_nop 0
	global_load_lds_dwordx4 v[182:183], off
	v_lshl_add_u64 v[182:183], s[86:87], 0, v[134:135]
	s_mov_b32 m0, s1
	s_nop 0
	global_load_lds_dwordx4 v[182:183], off
	s_mov_b32 m0, s34
	s_nop 0
	global_load_lds_dwordx4 v[218:219], off
	s_waitcnt vmcnt(8)
	s_waitcnt lgkmcnt(0)
	s_barrier
; #define PG8_STAGE(bufoff, gbase, voff) do { _Pragma("unroll") for (int _i = 0; _i < 2; ++_i) \
;         __builtin_amdgcn_global_load_lds((const unsigned*)((const char*)(gbase) + (voff)[_i]), (PG8_LAS unsigned*)(lds + (bufoff) + ldsw + _i * 8192), 16, 0, 0); } while (0)
; #define PG8_LDA(dst, b, h) do { _Pragma("unroll") for (int m = 0; m < 4; ++m) _Pragma("unroll") for (int k = 0; k < 2; ++k) dst[m][k] = *(const PG8_LAS bf16x8*)(lds + PG8_SA(b, h) + aoff + m * 2048 + k * 1024); } while (0)
; #define PG8_LDB(dst, b, h) do { _Pragma("unroll") for (int n = 0; n < 2; ++n) _Pragma("unroll") for (int k = 0; k < 2; ++k) dst[n][k] = *(const PG8_LAS bf16x8*)(lds + PG8_SB(b, h) + boff + n * 2048 + k * 1024); } while (0)
; #define PG8_MMA(ai, bj, At, Bt) do { __builtin_amdgcn_s_setprio(1); _Pragma("unroll") for (int m = 0; m < 4; ++m) _Pragma("unroll") for (int n = 0; n < 2; ++n) _Pragma("unroll") for (int k = 0; k < 2; ++k) \
;         acc[ai][bj][m][n] = __builtin_amdgcn_mfma_f32_16x16x32_bf16(Bt[n][k], At[m][k], acc[ai][bj][m][n], 0, 0, 0); __builtin_amdgcn_s_setprio(0); } while (0)
; #define PG8_WAIT_V(n) asm volatile("s_waitcnt vmcnt(" #n ")" ::: "memory")
; #define PG8_WAIT_L(n) asm volatile("s_waitcnt lgkmcnt(" #n ")" ::: "memory")
; #define PG8_BAR __builtin_amdgcn_s_barrier()
; #define PG8_SCHED __builtin_amdgcn_sched_barrier(0)
; template <class Epi, class Sched, bool ALIGN_EPI = false, bool SP2 = false>
; __device__ __forceinline__ void gemm_phase(PG8_LAS unsigned char* lds, const Gemm g, const Sched& S, const Epi& E, const int tid) {
;     ...
;             PG8_WAIT_V(8); PG8_WAIT_L(0); PG8_BAR; PG8_MMA(1, 0, At, B0); PG8_MMA(1, 1, At, B1); PG8_BAR; PG8_SCHED;
;             PG8_LDB(B0, 1, 0); PG8_LDB(B1, 1, 1); PG8_SCHED; PG8_LDA(At, 1, 0); PG8_STAGE(PG8_SA(0, 1), a2 + hstep, voffA);
;             PG8_WAIT_V(8); PG8_WAIT_L(0); PG8_BAR; PG8_MMA(0, 0, At, B0); PG8_MMA(0, 1, At, B1); PG8_BAR; PG8_SCHED;
	s_setprio 1
	s_waitcnt lgkmcnt(0)
	v_mfma_f32_16x16x32_bf16 v[62:65], v[142:145], v[174:177], v[62:65]
	v_mfma_f32_16x16x32_bf16 v[62:65], v[146:149], v[184:187], v[62:65]
	v_mfma_f32_16x16x32_bf16 v[54:57], v[150:153], v[174:177], v[54:57]
	v_mfma_f32_16x16x32_bf16 v[54:57], v[154:157], v[184:187], v[54:57]
	v_mfma_f32_16x16x32_bf16 v[46:49], v[142:145], v[188:191], v[46:49]
	v_mfma_f32_16x16x32_bf16 v[46:49], v[146:149], v[192:195], v[46:49]
	v_mfma_f32_16x16x32_bf16 v[38:41], v[150:153], v[188:191], v[38:41]
	v_mfma_f32_16x16x32_bf16 v[38:41], v[154:157], v[192:195], v[38:41]
	v_mfma_f32_16x16x32_bf16 v[30:33], v[142:145], v[196:199], v[30:33]
	v_mfma_f32_16x16x32_bf16 v[30:33], v[146:149], v[200:203], v[30:33]
	v_mfma_f32_16x16x32_bf16 v[22:25], v[150:153], v[196:199], v[22:25]
	v_mfma_f32_16x16x32_bf16 v[22:25], v[154:157], v[200:203], v[22:25]
	v_mfma_f32_16x16x32_bf16 v[14:17], v[142:145], v[204:207], v[14:17]
	v_mfma_f32_16x16x32_bf16 v[14:17], v[146:149], v[214:217], v[14:17]
	v_mfma_f32_16x16x32_bf16 v[6:9], v[150:153], v[204:207], v[6:9]
	v_mfma_f32_16x16x32_bf16 v[6:9], v[154:157], v[214:217], v[6:9]
	s_setprio 0
	s_setprio 1
	v_mfma_f32_16x16x32_bf16 v[58:61], v[158:161], v[174:177], v[58:61]
	v_mfma_f32_16x16x32_bf16 v[58:61], v[162:165], v[184:187], v[58:61]
	v_mfma_f32_16x16x32_bf16 v[50:53], v[166:169], v[174:177], v[50:53]
	v_mfma_f32_16x16x32_bf16 v[50:53], v[170:173], v[184:187], v[50:53]
	v_mfma_f32_16x16x32_bf16 v[42:45], v[158:161], v[188:191], v[42:45]
	v_mfma_f32_16x16x32_bf16 v[42:45], v[162:165], v[192:195], v[42:45]
	v_mfma_f32_16x16x32_bf16 v[34:37], v[166:169], v[188:191], v[34:37]
	v_mfma_f32_16x16x32_bf16 v[34:37], v[170:173], v[192:195], v[34:37]
	v_mfma_f32_16x16x32_bf16 v[26:29], v[158:161], v[196:199], v[26:29]
	v_mfma_f32_16x16x32_bf16 v[26:29], v[162:165], v[200:203], v[26:29]
	v_mfma_f32_16x16x32_bf16 v[18:21], v[166:169], v[196:199], v[18:21]
	v_mfma_f32_16x16x32_bf16 v[18:21], v[170:173], v[200:203], v[18:21]
	v_mfma_f32_16x16x32_bf16 v[10:13], v[158:161], v[204:207], v[10:13]
	v_mfma_f32_16x16x32_bf16 v[10:13], v[162:165], v[214:217], v[10:13]
	v_mfma_f32_16x16x32_bf16 v[2:5], v[166:169], v[204:207], v[2:5]
	v_mfma_f32_16x16x32_bf16 v[2:5], v[170:173], v[214:217], v[2:5]
	s_setprio 0
	s_barrier
	v_or_b32_e32 v142, 0x18000, v141
	v_add_u32_e32 v146, 0x18400, v141
	v_add_u32_e32 v150, 0x18800, v141
	v_add_u32_e32 v154, 0x18c00, v141
	v_or_b32_e32 v158, 0x1c000, v141
	v_add_u32_e32 v162, 0x1c400, v141
	v_add_u32_e32 v166, 0x1c800, v141
	v_add_u32_e32 v170, 0x1cc00, v141
	ds_read_b128 v[142:145], v142
	ds_read_b128 v[146:149], v146
	ds_read_b128 v[150:153], v150
	ds_read_b128 v[154:157], v154
	ds_read_b128 v[158:161], v158
	ds_read_b128 v[162:165], v162
	ds_read_b128 v[166:169], v166
	ds_read_b128 v[170:173], v170
	s_add_u32 s86, s86, 0x40000
	s_addc_u32 s87, s87, 0
	s_mov_b32 m0, s35
	v_lshl_add_u64 v[220:221], s[86:87], 0, v[134:135]
	ds_read_b128 v[174:177], v140 offset:32768
	ds_read_b128 v[184:187], v140 offset:33792
	ds_read_b128 v[188:191], v140 offset:34816
	ds_read_b128 v[192:195], v140 offset:35840
	ds_read_b128 v[196:199], v140 offset:36864
	ds_read_b128 v[200:203], v140 offset:37888
	ds_read_b128 v[204:207], v140 offset:38912
	ds_read_b128 v[214:217], v140 offset:39936
	global_load_lds_dwordx4 v[220:221], off
	v_lshl_add_u64 v[220:221], s[86:87], 0, v[132:133]
	s_mov_b32 m0, s88
	s_nop 0
	global_load_lds_dwordx4 v[220:221], off
	s_waitcnt vmcnt(8)
	s_waitcnt lgkmcnt(0)
	s_barrier
	s_setprio 1
	s_waitcnt lgkmcnt(0)
	v_mfma_f32_16x16x32_bf16 v[126:129], v[142:145], v[174:177], v[126:129]
	v_mfma_f32_16x16x32_bf16 v[126:129], v[146:149], v[184:187], v[126:129]
	v_mfma_f32_16x16x32_bf16 v[118:121], v[150:153], v[174:177], v[118:121]
	v_mfma_f32_16x16x32_bf16 v[118:121], v[154:157], v[184:187], v[118:121]
	v_mfma_f32_16x16x32_bf16 v[110:113], v[142:145], v[188:191], v[110:113]
	v_mfma_f32_16x16x32_bf16 v[110:113], v[146:149], v[192:195], v[110:113]
	v_mfma_f32_16x16x32_bf16 v[102:105], v[150:153], v[188:191], v[102:105]
	v_mfma_f32_16x16x32_bf16 v[102:105], v[154:157], v[192:195], v[102:105]
	v_mfma_f32_16x16x32_bf16 v[94:97], v[142:145], v[196:199], v[94:97]
	v_mfma_f32_16x16x32_bf16 v[94:97], v[146:149], v[200:203], v[94:97]
	v_mfma_f32_16x16x32_bf16 v[86:89], v[150:153], v[196:199], v[86:89]
	v_mfma_f32_16x16x32_bf16 v[86:89], v[154:157], v[200:203], v[86:89]
	v_mfma_f32_16x16x32_bf16 v[78:81], v[142:145], v[204:207], v[78:81]
	v_mfma_f32_16x16x32_bf16 v[78:81], v[146:149], v[214:217], v[78:81]
	v_mfma_f32_16x16x32_bf16 v[70:73], v[150:153], v[204:207], v[70:73]
	v_mfma_f32_16x16x32_bf16 v[70:73], v[154:157], v[214:217], v[70:73]
	s_setprio 0
	s_setprio 1
	v_mfma_f32_16x16x32_bf16 v[122:125], v[158:161], v[174:177], v[122:125]
	v_mfma_f32_16x16x32_bf16 v[122:125], v[162:165], v[184:187], v[122:125]
	v_mfma_f32_16x16x32_bf16 v[114:117], v[166:169], v[174:177], v[114:117]
	v_mfma_f32_16x16x32_bf16 v[114:117], v[170:173], v[184:187], v[114:117]
	v_mfma_f32_16x16x32_bf16 v[106:109], v[158:161], v[188:191], v[106:109]
	v_mfma_f32_16x16x32_bf16 v[106:109], v[162:165], v[192:195], v[106:109]
	v_mfma_f32_16x16x32_bf16 v[98:101], v[166:169], v[188:191], v[98:101]
	v_mfma_f32_16x16x32_bf16 v[98:101], v[170:173], v[192:195], v[98:101]
	v_mfma_f32_16x16x32_bf16 v[90:93], v[158:161], v[196:199], v[90:93]
	v_mfma_f32_16x16x32_bf16 v[90:93], v[162:165], v[200:203], v[90:93]
	v_mfma_f32_16x16x32_bf16 v[82:85], v[166:169], v[196:199], v[82:85]
	v_mfma_f32_16x16x32_bf16 v[82:85], v[170:173], v[200:203], v[82:85]
	v_mfma_f32_16x16x32_bf16 v[74:77], v[158:161], v[204:207], v[74:77]
	v_mfma_f32_16x16x32_bf16 v[74:77], v[162:165], v[214:217], v[74:77]
	v_mfma_f32_16x16x32_bf16 v[66:69], v[166:169], v[204:207], v[66:69]
	v_mfma_f32_16x16x32_bf16 v[66:69], v[170:173], v[214:217], v[66:69]
	s_setprio 0
	s_barrier
; #define PG8_STAGE(bufoff, gbase, voff) do { _Pragma("unroll") for (int _i = 0; _i < 2; ++_i) \
;         __builtin_amdgcn_global_load_lds((const unsigned*)((const char*)(gbase) + (voff)[_i]), (PG8_LAS unsigned*)(lds + (bufoff) + ldsw + _i * 8192), 16, 0, 0); } while (0)
; #define PG8_LDA(dst, b, h) do { _Pragma("unroll") for (int m = 0; m < 4; ++m) _Pragma("unroll") for (int k = 0; k < 2; ++k) dst[m][k] = *(const PG8_LAS bf16x8*)(lds + PG8_SA(b, h) + aoff + m * 2048 + k * 1024); } while (0)
; #define PG8_MMA(ai, bj, At, Bt) do { __builtin_amdgcn_s_setprio(1); _Pragma("unroll") for (int m = 0; m < 4; ++m) _Pragma("unroll") for (int n = 0; n < 2; ++n) _Pragma("unroll") for (int k = 0; k < 2; ++k) \
;         acc[ai][bj][m][n] = __builtin_amdgcn_mfma_f32_16x16x32_bf16(Bt[n][k], At[m][k], acc[ai][bj][m][n], 0, 0, 0); __builtin_amdgcn_s_setprio(0); } while (0)
; #define PG8_WAIT_V(n) asm volatile("s_waitcnt vmcnt(" #n ")" ::: "memory")
; #define PG8_WAIT_L(n) asm volatile("s_waitcnt lgkmcnt(" #n ")" ::: "memory")
; #define PG8_BAR __builtin_amdgcn_s_barrier()
; #define PG8_SCHED __builtin_amdgcn_sched_barrier(0)
; template <class Epi, class Sched, bool ALIGN_EPI = false, bool SP2 = false>
; __device__ __forceinline__ void gemm_phase(PG8_LAS unsigned char* lds, const Gemm g, const Sched& S, const Epi& E, const int tid) {
;     ...
;         for (int t = 0; t < nt; t += 2) {
;     ...
;             PG8_LDA(At, 1, 1); PG8_STAGE(PG8_SB(1, 0), b3, voffB); PG8_STAGE(PG8_SB(1, 1), b3 + hstep, voffB); PG8_STAGE(PG8_SA(1, 0), a3, voffA);
;             PG8_WAIT_V(8); PG8_WAIT_L(0); PG8_BAR; PG8_MMA(1, 0, At, B0); PG8_MMA(1, 1, At, B1); PG8_BAR; PG8_SCHED;
	s_mov_b32 m0, s0
	v_lshl_add_u64 v[178:179], v[178:179], 0, s[12:13]
	s_add_u32 s84, s84, 0x40080
	ds_read_b128 v[174:177], v140 offset:49152
	ds_read_b128 v[184:187], v140 offset:50176
	ds_read_b128 v[188:191], v140 offset:51200
	ds_read_b128 v[192:195], v140 offset:52224
	ds_read_b128 v[196:199], v140 offset:53248
	ds_read_b128 v[200:203], v140 offset:54272
	ds_read_b128 v[204:207], v140 offset:55296
	ds_read_b128 v[214:217], v140 offset:56320
	global_load_lds_dwordx4 v[178:179], off
	v_lshl_add_u64 v[178:179], v[180:181], 0, s[12:13]
	s_mov_b32 m0, s17
	s_addc_u32 s85, s85, 0
	global_load_lds_dwordx4 v[178:179], off
	v_lshl_add_u64 v[178:179], s[84:85], 0, v[0:1]
	s_mov_b32 m0, s51
	s_nop 0
	global_load_lds_dwordx4 v[178:179], off
	v_lshl_add_u64 v[178:179], s[84:85], 0, v[130:131]
	s_mov_b32 m0, s26
	s_nop 0
	global_load_lds_dwordx4 v[178:179], off
	v_lshl_add_u64 v[178:179], v[182:183], 0, s[12:13]
	s_mov_b32 m0, s91
	s_nop 0
	global_load_lds_dwordx4 v[178:179], off
	v_lshl_add_u64 v[178:179], v[218:219], 0, s[12:13]
	s_mov_b32 m0, s50
	s_nop 0
	global_load_lds_dwordx4 v[178:179], off
	s_waitcnt vmcnt(8)
	s_waitcnt lgkmcnt(0)
	s_barrier
	s_setprio 1
	s_waitcnt lgkmcnt(0)
	v_mfma_f32_16x16x32_bf16 v[62:65], v[142:145], v[174:177], v[62:65]
	v_mfma_f32_16x16x32_bf16 v[62:65], v[146:149], v[184:187], v[62:65]
	v_mfma_f32_16x16x32_bf16 v[54:57], v[150:153], v[174:177], v[54:57]
	v_mfma_f32_16x16x32_bf16 v[54:57], v[154:157], v[184:187], v[54:57]
	v_mfma_f32_16x16x32_bf16 v[46:49], v[142:145], v[188:191], v[46:49]
	v_mfma_f32_16x16x32_bf16 v[46:49], v[146:149], v[192:195], v[46:49]
	v_mfma_f32_16x16x32_bf16 v[38:41], v[150:153], v[188:191], v[38:41]
	v_mfma_f32_16x16x32_bf16 v[38:41], v[154:157], v[192:195], v[38:41]
	v_mfma_f32_16x16x32_bf16 v[30:33], v[142:145], v[196:199], v[30:33]
	v_mfma_f32_16x16x32_bf16 v[30:33], v[146:149], v[200:203], v[30:33]
	v_mfma_f32_16x16x32_bf16 v[22:25], v[150:153], v[196:199], v[22:25]
	v_mfma_f32_16x16x32_bf16 v[22:25], v[154:157], v[200:203], v[22:25]
	v_mfma_f32_16x16x32_bf16 v[14:17], v[142:145], v[204:207], v[14:17]
	v_mfma_f32_16x16x32_bf16 v[14:17], v[146:149], v[214:217], v[14:17]
	v_mfma_f32_16x16x32_bf16 v[6:9], v[150:153], v[204:207], v[6:9]
	v_mfma_f32_16x16x32_bf16 v[6:9], v[154:157], v[214:217], v[6:9]
	s_setprio 0
	s_setprio 1
	v_mfma_f32_16x16x32_bf16 v[58:61], v[158:161], v[174:177], v[58:61]
	v_mfma_f32_16x16x32_bf16 v[58:61], v[162:165], v[184:187], v[58:61]
	v_mfma_f32_16x16x32_bf16 v[50:53], v[166:169], v[174:177], v[50:53]
	v_mfma_f32_16x16x32_bf16 v[50:53], v[170:173], v[184:187], v[50:53]
	v_mfma_f32_16x16x32_bf16 v[42:45], v[158:161], v[188:191], v[42:45]
	v_mfma_f32_16x16x32_bf16 v[42:45], v[162:165], v[192:195], v[42:45]
	v_mfma_f32_16x16x32_bf16 v[34:37], v[166:169], v[188:191], v[34:37]
	v_mfma_f32_16x16x32_bf16 v[34:37], v[170:173], v[192:195], v[34:37]
	v_mfma_f32_16x16x32_bf16 v[26:29], v[158:161], v[196:199], v[26:29]
	v_mfma_f32_16x16x32_bf16 v[26:29], v[162:165], v[200:203], v[26:29]
	v_mfma_f32_16x16x32_bf16 v[18:21], v[166:169], v[196:199], v[18:21]
	v_mfma_f32_16x16x32_bf16 v[18:21], v[170:173], v[200:203], v[18:21]
	v_mfma_f32_16x16x32_bf16 v[10:13], v[158:161], v[204:207], v[10:13]
	v_mfma_f32_16x16x32_bf16 v[10:13], v[162:165], v[214:217], v[10:13]
	v_mfma_f32_16x16x32_bf16 v[2:5], v[166:169], v[204:207], v[2:5]
	v_mfma_f32_16x16x32_bf16 v[2:5], v[170:173], v[214:217], v[2:5]
	s_setprio 0
	s_barrier
	s_add_i32 s43, s43, 2
	s_add_u32 s30, s30, 0x100
	s_addc_u32 s31, s31, 0
	s_add_u32 s24, s24, 0x100
	s_addc_u32 s41, s41, 0
	s_cmp_gt_u32 s43, 13
	s_cbranch_scc0 .LBB0_713
	s_and_b64 vcc, exec, s[38:39]
	s_cbranch_vccz .LBB0_716
	s_barrier
